# non-temporal hint also on the mixer in-projection and pre-phase scratch stores (streaming writes consumed by later phases)
# speedup vs baseline: 1.0044x; 1.0010x over previous
.LBB0_735:
	s_mov_b32 s19, s4
	v_mov_b32_e32 v156, v151
	s_mov_b32 s17, s41
	v_mov_b32_e32 v144, v150
	s_lshl_b64 s[24:25], s[8:9], 1
	v_lshl_add_u32 v144, s19, 6, v144
	s_add_u32 s24, s60, s24
	v_ashrrev_i32_e32 v145, 31, v144
	s_addc_u32 s25, s61, s25
	v_lshlrev_b64 v[146:147], 9, v[144:145]
	v_lshl_add_u64 v[146:147], s[24:25], 0, v[146:147]
	s_lshl_b32 s24, s17, 5
	s_ashr_i32 s25, s24, 31
	v_lshl_add_u64 v[148:149], s[24:25], 1, v[146:147]
	v_lshlrev_b32_e32 v146, 3, v156
	v_ashrrev_i32_e32 v147, 31, v146
	v_lshl_add_u64 v[148:149], v[146:147], 1, v[148:149]
	v_cvt_pk_bf16_f32 v156, v76, v77
	v_cvt_pk_bf16_f32 v157, v78, v79
	v_cvt_pk_bf16_f32 v158, v72, v73
	v_cvt_pk_bf16_f32 v159, v74, v75
	global_store_dwordx4 v[148:149], v[156:159], off nt
	v_cvt_pk_bf16_f32 v124, v124, v125
	s_movk_i32 s8, 0x2000
	v_cvt_pk_bf16_f32 v125, v126, v127
	v_cvt_pk_bf16_f32 v126, v120, v121
	v_cvt_pk_bf16_f32 v127, v122, v123
	global_store_dwordx4 v[148:149], v[124:127], off offset:256 nt
	v_cvt_pk_bf16_f32 v120, v68, v69
	v_cvt_pk_bf16_f32 v121, v70, v71
	v_cvt_pk_bf16_f32 v122, v64, v65
	v_cvt_pk_bf16_f32 v123, v66, v67
	s_nop 1
	v_add_co_u32_e32 v124, vcc, s8, v148
	s_mov_b32 s8, 0x10000
	s_nop 0
	v_addc_co_u32_e32 v125, vcc, 0, v149, vcc
	global_store_dwordx4 v[124:125], v[120:123], off nt
	v_cvt_pk_bf16_f32 v116, v116, v117
	v_cvt_pk_bf16_f32 v117, v118, v119
	v_cvt_pk_bf16_f32 v118, v112, v113
	v_cvt_pk_bf16_f32 v119, v114, v115
	global_store_dwordx4 v[124:125], v[116:119], off offset:256 nt
	v_cvt_pk_bf16_f32 v112, v56, v57
	v_cvt_pk_bf16_f32 v113, v58, v59
	v_cvt_pk_bf16_f32 v114, v52, v53
	v_cvt_pk_bf16_f32 v115, v54, v55
	s_nop 1
	v_add_co_u32_e32 v116, vcc, s39, v148
	s_nop 1
	v_addc_co_u32_e32 v117, vcc, 0, v149, vcc
	global_store_dwordx4 v[116:117], v[112:115], off nt
	v_cvt_pk_bf16_f32 v108, v108, v109
	v_cvt_pk_bf16_f32 v109, v110, v111
	v_cvt_pk_bf16_f32 v110, v104, v105
	v_cvt_pk_bf16_f32 v111, v106, v107
	global_store_dwordx4 v[116:117], v[108:111], off offset:256 nt
	v_cvt_pk_bf16_f32 v104, v44, v45
	v_cvt_pk_bf16_f32 v105, v46, v47
	v_cvt_pk_bf16_f32 v106, v40, v41
	v_cvt_pk_bf16_f32 v107, v42, v43
	s_nop 1
	v_add_co_u32_e32 v108, vcc, s40, v148
	s_nop 1
	v_addc_co_u32_e32 v109, vcc, 0, v149, vcc
	global_store_dwordx4 v[108:109], v[104:107], off nt
	v_cvt_pk_bf16_f32 v100, v100, v101
	v_cvt_pk_bf16_f32 v101, v102, v103
	v_cvt_pk_bf16_f32 v102, v96, v97
	v_cvt_pk_bf16_f32 v103, v98, v99
	global_store_dwordx4 v[108:109], v[100:103], off offset:256 nt
	v_cvt_pk_bf16_f32 v96, v28, v29
	v_cvt_pk_bf16_f32 v97, v30, v31
	v_cvt_pk_bf16_f32 v98, v24, v25
	v_cvt_pk_bf16_f32 v99, v26, v27
	s_nop 1
	v_add_co_u32_e32 v100, vcc, s8, v148
	s_mov_b32 s8, 0x12000
	s_nop 0
	v_addc_co_u32_e32 v101, vcc, 0, v149, vcc
	global_store_dwordx4 v[100:101], v[96:99], off nt
	v_cvt_pk_bf16_f32 v92, v92, v93
	v_cvt_pk_bf16_f32 v93, v94, v95
	v_cvt_pk_bf16_f32 v94, v88, v89
	v_cvt_pk_bf16_f32 v95, v90, v91
	global_store_dwordx4 v[100:101], v[92:95], off offset:256 nt
	v_cvt_pk_bf16_f32 v88, v20, v21
	v_cvt_pk_bf16_f32 v89, v22, v23
	v_cvt_pk_bf16_f32 v90, v16, v17
	v_cvt_pk_bf16_f32 v91, v18, v19
	s_nop 1
	v_add_co_u32_e32 v92, vcc, s8, v148
	s_nop 1
	v_addc_co_u32_e32 v93, vcc, 0, v149, vcc
	global_store_dwordx4 v[92:93], v[88:91], off nt
	v_cvt_pk_bf16_f32 v84, v84, v85
	v_cvt_pk_bf16_f32 v85, v86, v87
	v_cvt_pk_bf16_f32 v86, v80, v81
	v_cvt_pk_bf16_f32 v87, v82, v83
	global_store_dwordx4 v[92:93], v[84:87], off offset:256 nt
	v_cvt_pk_bf16_f32 v80, v12, v13
	v_cvt_pk_bf16_f32 v81, v14, v15
	v_cvt_pk_bf16_f32 v82, v8, v9
	v_cvt_pk_bf16_f32 v83, v10, v11
	s_nop 1
	v_add_co_u32_e32 v84, vcc, s37, v148
	s_nop 1
	v_addc_co_u32_e32 v85, vcc, 0, v149, vcc
	global_store_dwordx4 v[84:85], v[80:83], off nt
	v_cvt_pk_bf16_f32 v60, v60, v61
	v_cvt_pk_bf16_f32 v61, v62, v63
	v_cvt_pk_bf16_f32 v62, v48, v49
	v_cvt_pk_bf16_f32 v63, v50, v51
	global_store_dwordx4 v[84:85], v[60:63], off offset:256 nt
	v_cvt_pk_bf16_f32 v48, v4, v5
	v_cvt_pk_bf16_f32 v49, v6, v7
	v_cvt_pk_bf16_f32 v50, v0, v1
	v_cvt_pk_bf16_f32 v51, v2, v3
	s_nop 1
	v_add_co_u32_e32 v60, vcc, s38, v148
	s_nop 1
	v_addc_co_u32_e32 v61, vcc, 0, v149, vcc
	s_andn2_b64 vcc, exec, s[14:15]
	global_store_dwordx4 v[60:61], v[48:51], off nt
	v_cvt_pk_bf16_f32 v36, v36, v37
	v_cvt_pk_bf16_f32 v37, v38, v39
	v_cvt_pk_bf16_f32 v38, v32, v33
	v_cvt_pk_bf16_f32 v39, v34, v35
	global_store_dwordx4 v[60:61], v[36:39], off offset:256 nt
	s_cbranch_vccnz .LBB0_738
	s_cmp_lg_u32 s43, 26
	s_cselect_b64 s[24:25], -1, 0
	s_cmp_lg_u32 s17, 0
	s_cselect_b64 s[26:27], -1, 0
	s_or_b64 s[24:25], s[26:27], s[24:25]
	s_and_b64 vcc, exec, s[24:25]
	s_cbranch_vccnz .LBB0_738
	v_lshl_add_u32 v32, s42, 8, v144
	v_ashrrev_i32_e32 v33, 31, v32
	v_lshlrev_b64 v[34:35], 7, v[32:33]
	v_lshl_add_u64 v[34:35], s[66:67], 0, v[34:35]
	v_lshlrev_b64 v[36:37], 2, v[146:147]
	v_lshl_add_u64 v[34:35], v[34:35], 0, v[36:37]
	global_store_dwordx4 v[34:35], v[76:79], off nt
	global_store_dwordx4 v[34:35], v[72:75], off offset:16 nt
	v_add_u32_e32 v34, 16, v32
	v_ashrrev_i32_e32 v35, 31, v34
	v_lshlrev_b64 v[34:35], 7, v[34:35]
	v_lshl_add_u64 v[34:35], s[66:67], 0, v[34:35]
	v_lshl_add_u64 v[34:35], v[34:35], 0, v[36:37]
	global_store_dwordx4 v[34:35], v[68:71], off nt
	global_store_dwordx4 v[34:35], v[64:67], off offset:16 nt
	v_add_u32_e32 v34, 32, v32
	v_ashrrev_i32_e32 v35, 31, v34
	v_lshlrev_b64 v[34:35], 7, v[34:35]
	v_lshl_add_u64 v[34:35], s[66:67], 0, v[34:35]
	v_lshl_add_u64 v[34:35], v[34:35], 0, v[36:37]
	global_store_dwordx4 v[34:35], v[56:59], off nt
	global_store_dwordx4 v[34:35], v[52:55], off offset:16 nt
	v_add_u32_e32 v34, 48, v32
	v_ashrrev_i32_e32 v35, 31, v34
	v_lshlrev_b64 v[34:35], 7, v[34:35]
	v_lshl_add_u64 v[34:35], s[66:67], 0, v[34:35]
	v_lshl_add_u64 v[34:35], v[34:35], 0, v[36:37]
	global_store_dwordx4 v[34:35], v[44:47], off nt
	global_store_dwordx4 v[34:35], v[40:43], off offset:16 nt
	v_add_u32_e32 v34, 0x80, v32
	v_ashrrev_i32_e32 v35, 31, v34
	v_lshlrev_b64 v[34:35], 7, v[34:35]
	v_lshl_add_u64 v[34:35], s[66:67], 0, v[34:35]
	v_lshl_add_u64 v[34:35], v[34:35], 0, v[36:37]
	global_store_dwordx4 v[34:35], v[28:31], off nt
	global_store_dwordx4 v[34:35], v[24:27], off offset:16 nt
	s_nop 1
	v_add_u32_e32 v24, 0x90, v32
	v_ashrrev_i32_e32 v25, 31, v24
	v_lshlrev_b64 v[24:25], 7, v[24:25]
	v_lshl_add_u64 v[24:25], s[66:67], 0, v[24:25]
	v_lshl_add_u64 v[24:25], v[24:25], 0, v[36:37]
	global_store_dwordx4 v[24:25], v[20:23], off nt
	global_store_dwordx4 v[24:25], v[16:19], off offset:16 nt
	s_nop 1
	v_add_u32_e32 v16, 0xa0, v32
	v_ashrrev_i32_e32 v17, 31, v16
	v_lshlrev_b64 v[16:17], 7, v[16:17]
	v_lshl_add_u64 v[16:17], s[66:67], 0, v[16:17]
	v_lshl_add_u64 v[16:17], v[16:17], 0, v[36:37]
	global_store_dwordx4 v[16:17], v[12:15], off nt
	global_store_dwordx4 v[16:17], v[8:11], off offset:16 nt
	s_nop 1
	v_add_u32_e32 v8, 0xb0, v32
	v_ashrrev_i32_e32 v9, 31, v8
	v_lshlrev_b64 v[8:9], 7, v[8:9]
	v_lshl_add_u64 v[8:9], s[66:67], 0, v[8:9]
	v_lshl_add_u64 v[8:9], v[8:9], 0, v[36:37]
	global_store_dwordx4 v[8:9], v[4:7], off nt
	global_store_dwordx4 v[8:9], v[0:3], off offset:16 nt

.LBB0_813:
	s_or_b64 exec, exec, s[46:47]
	s_waitcnt lgkmcnt(0)
	s_barrier
	ds_read_b128 v[18:21], v123
	ds_read_b128 v[22:25], v123 offset:9216
	v_lshl_add_u64 v[26:27], v[186:187], 4, s[42:43]
	s_addk_i32 s50, 0x100
	s_cmpk_eq_i32 s50, 0x800
	s_waitcnt lgkmcnt(1)
	global_store_dwordx4 v[26:27], v[18:21], off nt
	v_mov_b32_e32 v90, v128
	v_mov_b32_e32 v98, v17
	v_add_co_u32_e32 v18, vcc, 0x2000, v26
	s_nop 1
	v_addc_co_u32_e32 v19, vcc, 0, v27, vcc
	s_waitcnt lgkmcnt(0)
	global_store_dwordx4 v[18:19], v[22:25], off nt
	ds_read_b128 v[18:21], v123 offset:18432
	s_nop 0
	v_add_co_u32_e32 v22, vcc, 0x4000, v26
	s_nop 1
	v_addc_co_u32_e32 v23, vcc, 0, v27, vcc
	s_waitcnt lgkmcnt(0)
	global_store_dwordx4 v[22:23], v[18:21], off nt
	s_waitcnt lgkmcnt(0)
	s_barrier
	s_cbranch_scc1 .LBB0_836

.LBB0_834:
	v_lshl_add_u64 v[18:19], v[184:185], 2, s[44:45]
	global_store_dword v[18:19], v129, off nt
	global_store_dword v[18:19], v130, off offset:256 nt
	global_store_dword v[18:19], v117, off offset:512 nt
	s_and_saveexec_b64 s[46:47], s[22:23]
	s_cbranch_execz .LBB0_813
.LBB0_835:
	v_mov_b32_e32 v18, s52
	v_cndmask_b32_e64 v18, 0, v18, s[6:7]
	v_mov_b32_e32 v19, s53
	v_cndmask_b32_e64 v18, v18, v19, s[8:9]
	v_mov_b32_e32 v19, s55
	v_cndmask_b32_e64 v18, v18, v19, s[10:11]
	v_mov_b32_e32 v19, s56
	v_cndmask_b32_e64 v18, v18, v19, s[12:13]
	v_mov_b32_e32 v19, s65
	v_cndmask_b32_e64 v18, v18, v19, s[14:15]
	v_mov_b32_e32 v19, s74
	v_cndmask_b32_e64 v18, v18, v19, s[16:17]
	v_mov_b32_e32 v19, s3
	v_cndmask_b32_e64 v18, v18, v19, s[18:19]
	v_mov_b32_e32 v19, s75
	v_cndmask_b32_e64 v20, v18, v19, s[20:21]
	v_lshl_add_u64 v[18:19], v[114:115], 2, s[44:45]
	global_store_dword v[18:19], v20, off nt
	s_branch .LBB0_813

.LBB0_837:
	s_or_b64 exec, exec, s[46:47]
	s_waitcnt lgkmcnt(0)
	s_barrier
	ds_read_b128 v[16:19], v68
	v_lshl_add_u64 v[20:21], v[42:43], 0, s[74:75]
	v_add_co_u32_e32 v22, vcc, 0x49a80000, v20
	s_add_u32 s74, s74, 0x1020000
	s_nop 0
	v_addc_co_u32_e32 v23, vcc, 0, v21, vcc
	s_waitcnt lgkmcnt(0)
	global_store_dwordx4 v[22:23], v[16:19], off nt
	ds_read_b128 v[16:19], v69
	v_add_co_u32_e32 v22, vcc, 0x49a82000, v20
	s_addc_u32 s75, s75, 0
	s_nop 0
	v_addc_co_u32_e32 v23, vcc, 0, v21, vcc
	s_waitcnt lgkmcnt(0)
	global_store_dwordx4 v[22:23], v[16:19], off nt
	ds_read_b128 v[16:19], v68 offset:17408
	v_add_co_u32_e32 v22, vcc, 0x49a84000, v20
	s_addk_i32 s4, 0x100
	s_nop 0
	v_addc_co_u32_e32 v23, vcc, 0, v21, vcc
	s_waitcnt lgkmcnt(0)
	global_store_dwordx4 v[22:23], v[16:19], off nt
	ds_read_b128 v[16:19], v69 offset:17408
	v_add_co_u32_e32 v22, vcc, 0x49a86000, v20
	s_cmp_eq_u32 s74, 0x8100000
	s_nop 0
	v_addc_co_u32_e32 v23, vcc, 0, v21, vcc
	s_waitcnt lgkmcnt(0)
	global_store_dwordx4 v[22:23], v[16:19], off nt
	ds_read_b128 v[16:19], v68 offset:34816
	v_add_co_u32_e32 v22, vcc, 0x49a88000, v20
	s_nop 1
	v_addc_co_u32_e32 v23, vcc, 0, v21, vcc
	s_waitcnt lgkmcnt(0)
	global_store_dwordx4 v[22:23], v[16:19], off nt
	ds_read_b128 v[16:19], v69 offset:34816
	v_add_co_u32_e32 v22, vcc, 0x49a8a000, v20
	s_nop 1
	v_addc_co_u32_e32 v23, vcc, 0, v21, vcc
	s_waitcnt lgkmcnt(0)
	global_store_dwordx4 v[22:23], v[16:19], off nt
	ds_read_b128 v[16:19], v68 offset:52224
	v_add_co_u32_e32 v22, vcc, 0x49a8c000, v20
	s_nop 1
	v_addc_co_u32_e32 v23, vcc, 0, v21, vcc
	s_waitcnt lgkmcnt(0)
	global_store_dwordx4 v[22:23], v[16:19], off nt
	ds_read_b128 v[16:19], v69 offset:52224
	v_add_co_u32_e32 v20, vcc, 0x49a8e000, v20
	s_nop 1
	v_addc_co_u32_e32 v21, vcc, 0, v21, vcc
	s_waitcnt lgkmcnt(0)
	global_store_dwordx4 v[20:21], v[16:19], off nt
	s_waitcnt lgkmcnt(0)
	s_barrier
	s_cbranch_scc1 .LBB0_842

.LBB0_840:
	s_waitcnt lgkmcnt(0)
	s_barrier
	ds_read_b128 v[28:31], v62 offset:17408
	ds_read_b128 v[20:23], v62 offset:17424
	v_mov_b32_e32 v51, 0
	v_mov_b32_e32 v53, 0
	v_mov_b32_e32 v55, 0
	s_waitcnt lgkmcnt(1)
	v_lshlrev_b32_e32 v16, 16, v28
	v_mul_f32_e32 v16, 0xbfb8aa3b, v16
	v_exp_f32_e32 v44, v16
	ds_read_b128 v[24:27], v62
	ds_read_b128 v[16:19], v62 offset:16
	v_and_b32_e32 v28, 0xffff0000, v28
	v_mul_f32_e32 v28, 0xbfb8aa3b, v28
	v_add_f32_e32 v44, 1.0, v44
	v_rcp_f32_e32 v44, v44
	s_waitcnt lgkmcnt(1)
	v_lshlrev_b32_e32 v45, 16, v24
	v_mul_f32_e32 v46, 0xbfb8aa3b, v45
	v_exp_f32_e32 v46, v46
	v_add_f32_e32 v47, 0x2b8cbccc, v44
	v_cmp_gt_f32_e32 vcc, s5, v47
	v_exp_f32_e32 v28, v28
	v_add_f32_e32 v46, 1.0, v46
	v_cndmask_b32_e64 v48, 0, 32, vcc
	v_ldexp_f32 v47, v47, v48
	v_log_f32_e32 v47, v47
	v_rcp_f32_e32 v46, v46
	v_cndmask_b32_e32 v48, 0, v70, vcc
	v_add_f32_e32 v28, 1.0, v28
	v_mul_f32_e32 v49, 0x3f317217, v47
	v_fma_f32 v49, v47, s51, -v49
	v_fmac_f32_e32 v49, 0x3377d1cf, v47
	v_fmac_f32_e32 v49, 0x3f317217, v47
	v_cmp_lt_f32_e64 vcc, |v47|, s52
	v_mul_f32_e32 v45, v46, v45
	v_mul_f32_e32 v61, 0x3db504f3, v45
	v_cndmask_b32_e32 v47, v47, v49, vcc
	v_sub_f32_e32 v47, v47, v48
	v_and_b32_e32 v24, 0xffff0000, v24
	v_mov_b32_e32 v49, 0
	v_add_f32_dpp v45, v47, v47 row_shr:1 row_mask:0xf bank_mask:0xf bound_ctrl:1
	v_mov_b32_e32 v47, 0
	s_nop 0
	v_add_f32_dpp v45, v45, v45 row_shr:2 row_mask:0xf bank_mask:0xf bound_ctrl:1
	s_nop 1
	v_add_f32_dpp v45, v45, v45 row_shr:4 row_mask:0xf bank_mask:0xf bound_ctrl:1
	s_nop 1
	v_add_f32_dpp v46, v45, v45 row_shr:8 row_mask:0xf bank_mask:0xf bound_ctrl:1
	v_rcp_f32_e32 v45, v28
	s_nop 0
	v_mov_b32_dpp v47, v46 row_bcast:15 row_mask:0xa bank_mask:0xf
	v_add_f32_e32 v28, v46, v47
	v_add_f32_e32 v47, 0x2b8cbccc, v45
	v_cmp_gt_f32_e32 vcc, s5, v47
	v_mov_b32_e32 v46, 0
	s_nop 0
	v_cndmask_b32_e64 v48, 0, 32, vcc
	v_ldexp_f32 v47, v47, v48
	v_log_f32_e32 v47, v47
	v_mov_b32_dpp v46, v28 row_bcast:31 row_mask:0xc bank_mask:0xf
	v_add_f32_e32 v28, v28, v46
	v_mul_f32_e32 v48, 0xbfb8aa3b, v24
	v_mul_f32_e32 v46, 0x3f317217, v47
	v_fma_f32 v46, v47, s51, -v46
	v_exp_f32_e32 v48, v48
	v_fmac_f32_e32 v46, 0x3377d1cf, v47
	v_fmac_f32_e32 v46, 0x3f317217, v47
	v_cmp_lt_f32_e64 s[46:47], |v47|, s52
	v_add_f32_e32 v48, 1.0, v48
	v_rcp_f32_e32 v48, v48
	v_cndmask_b32_e64 v46, v47, v46, s[46:47]
	v_cndmask_b32_e32 v47, 0, v70, vcc
	v_sub_f32_e32 v46, v46, v47
	v_lshlrev_b32_e32 v47, 16, v29
	v_mul_f32_e32 v47, 0xbfb8aa3b, v47
	v_exp_f32_e32 v47, v47
	v_add_f32_dpp v46, v46, v46 row_shr:1 row_mask:0xf bank_mask:0xf bound_ctrl:1
	v_mul_f32_e32 v24, v48, v24
	v_and_b32_e32 v29, 0xffff0000, v29
	v_add_f32_dpp v46, v46, v46 row_shr:2 row_mask:0xf bank_mask:0xf bound_ctrl:1
	v_mul_f32_e32 v29, 0xbfb8aa3b, v29
	v_exp_f32_e32 v29, v29
	v_add_f32_dpp v46, v46, v46 row_shr:4 row_mask:0xf bank_mask:0xf bound_ctrl:1
	v_readlane_b32 s3, v28, 31
	v_mul_f32_e32 v24, 0x3db504f3, v24
	v_add_f32_dpp v48, v46, v46 row_shr:8 row_mask:0xf bank_mask:0xf bound_ctrl:1
	v_add_f32_e32 v46, 1.0, v47
	v_rcp_f32_e32 v46, v46
	v_mov_b32_dpp v49, v48 row_bcast:15 row_mask:0xa bank_mask:0xf
	v_add_f32_e32 v47, v48, v49
	v_mov_b32_e32 v48, 0
	v_add_f32_e32 v49, 0x2b8cbccc, v46
	v_cmp_gt_f32_e32 vcc, s5, v49
	v_mov_b32_dpp v48, v47 row_bcast:31 row_mask:0xc bank_mask:0xf
	v_add_f32_e32 v72, v47, v48
	v_cndmask_b32_e64 v50, 0, 32, vcc
	v_lshlrev_b32_e32 v47, 16, v25
	v_ldexp_f32 v49, v49, v50
	v_mul_f32_e32 v50, 0xbfb8aa3b, v47
	v_log_f32_e32 v49, v49
	v_exp_f32_e32 v50, v50
	v_add_f32_e32 v29, 1.0, v29
	v_and_b32_e32 v25, 0xffff0000, v25
	v_mul_f32_e32 v48, 0x3f317217, v49
	v_add_f32_e32 v50, 1.0, v50
	v_fma_f32 v48, v49, s51, -v48
	v_rcp_f32_e32 v50, v50
	v_fmac_f32_e32 v48, 0x3377d1cf, v49
	v_fmac_f32_e32 v48, 0x3f317217, v49
	v_cmp_lt_f32_e64 s[46:47], |v49|, s52
	v_mul_f32_e32 v47, v50, v47
	v_mul_f32_e32 v71, 0x3db504f3, v47
	v_cndmask_b32_e64 v48, v49, v48, s[46:47]
	v_cndmask_b32_e32 v49, 0, v70, vcc
	v_sub_f32_e32 v48, v48, v49
	v_mov_b32_e32 v49, 0
	s_nop 0
	v_add_f32_dpp v47, v48, v48 row_shr:1 row_mask:0xf bank_mask:0xf bound_ctrl:1
	s_nop 1
	v_add_f32_dpp v47, v47, v47 row_shr:2 row_mask:0xf bank_mask:0xf bound_ctrl:1
	s_nop 1
	v_add_f32_dpp v47, v47, v47 row_shr:4 row_mask:0xf bank_mask:0xf bound_ctrl:1
	s_nop 1
	v_add_f32_dpp v48, v47, v47 row_shr:8 row_mask:0xf bank_mask:0xf bound_ctrl:1
	v_rcp_f32_e32 v47, v29
	s_nop 0
	v_mov_b32_dpp v49, v48 row_bcast:15 row_mask:0xa bank_mask:0xf
	v_add_f32_e32 v29, v48, v49
	v_add_f32_e32 v49, 0x2b8cbccc, v47
	v_cmp_gt_f32_e32 vcc, s5, v49
	v_mov_b32_e32 v48, 0
	s_nop 0
	v_cndmask_b32_e64 v50, 0, 32, vcc
	v_ldexp_f32 v49, v49, v50
	v_log_f32_e32 v49, v49
	v_mov_b32_dpp v48, v29 row_bcast:31 row_mask:0xc bank_mask:0xf
	v_add_f32_e32 v29, v29, v48
	v_mul_f32_e32 v50, 0xbfb8aa3b, v25
	v_mul_f32_e32 v48, 0x3f317217, v49
	v_fma_f32 v48, v49, s51, -v48
	v_exp_f32_e32 v50, v50
	v_fmac_f32_e32 v48, 0x3377d1cf, v49
	v_fmac_f32_e32 v48, 0x3f317217, v49
	v_cmp_lt_f32_e64 s[46:47], |v49|, s52
	v_add_f32_e32 v50, 1.0, v50
	v_rcp_f32_e32 v50, v50
	v_cndmask_b32_e64 v48, v49, v48, s[46:47]
	v_cndmask_b32_e32 v49, 0, v70, vcc
	v_sub_f32_e32 v48, v48, v49
	v_lshlrev_b32_e32 v49, 16, v30
	v_mul_f32_e32 v49, 0xbfb8aa3b, v49
	v_exp_f32_e32 v49, v49
	v_add_f32_dpp v48, v48, v48 row_shr:1 row_mask:0xf bank_mask:0xf bound_ctrl:1
	v_mul_f32_e32 v25, v50, v25
	v_and_b32_e32 v30, 0xffff0000, v30
	v_add_f32_dpp v48, v48, v48 row_shr:2 row_mask:0xf bank_mask:0xf bound_ctrl:1
	v_mul_f32_e32 v30, 0xbfb8aa3b, v30
	v_exp_f32_e32 v30, v30
	v_add_f32_dpp v48, v48, v48 row_shr:4 row_mask:0xf bank_mask:0xf bound_ctrl:1
	v_mul_f32_e32 v25, 0x3db504f3, v25
	v_add_f32_e32 v30, 1.0, v30
	v_add_f32_dpp v50, v48, v48 row_shr:8 row_mask:0xf bank_mask:0xf bound_ctrl:1
	v_add_f32_e32 v48, 1.0, v49
	v_rcp_f32_e32 v48, v48
	v_mov_b32_dpp v51, v50 row_bcast:15 row_mask:0xa bank_mask:0xf
	v_add_f32_e32 v49, v50, v51
	v_mov_b32_e32 v50, 0
	v_add_f32_e32 v51, 0x2b8cbccc, v48
	v_cmp_gt_f32_e32 vcc, s5, v51
	v_mov_b32_dpp v50, v49 row_bcast:31 row_mask:0xc bank_mask:0xf
	v_add_f32_e32 v74, v49, v50
	v_cndmask_b32_e64 v52, 0, 32, vcc
	v_lshlrev_b32_e32 v49, 16, v26
	v_ldexp_f32 v51, v51, v52
	v_mul_f32_e32 v52, 0xbfb8aa3b, v49
	v_log_f32_e32 v51, v51
	v_exp_f32_e32 v52, v52
	v_and_b32_e32 v26, 0xffff0000, v26
	v_mul_f32_e32 v50, 0x3f317217, v51
	v_add_f32_e32 v52, 1.0, v52
	v_fma_f32 v50, v51, s51, -v50
	v_rcp_f32_e32 v52, v52
	v_fmac_f32_e32 v50, 0x3377d1cf, v51
	v_fmac_f32_e32 v50, 0x3f317217, v51
	v_cmp_lt_f32_e64 s[46:47], |v51|, s52
	v_mul_f32_e32 v49, v52, v49
	v_mul_f32_e32 v73, 0x3db504f3, v49
	v_cndmask_b32_e64 v50, v51, v50, s[46:47]
	v_cndmask_b32_e32 v51, 0, v70, vcc
	v_sub_f32_e32 v50, v50, v51
	v_mov_b32_e32 v51, 0
	s_nop 0
	v_add_f32_dpp v49, v50, v50 row_shr:1 row_mask:0xf bank_mask:0xf bound_ctrl:1
	s_nop 1
	v_add_f32_dpp v49, v49, v49 row_shr:2 row_mask:0xf bank_mask:0xf bound_ctrl:1
	s_nop 1
	v_add_f32_dpp v49, v49, v49 row_shr:4 row_mask:0xf bank_mask:0xf bound_ctrl:1
	s_nop 1
	v_add_f32_dpp v50, v49, v49 row_shr:8 row_mask:0xf bank_mask:0xf bound_ctrl:1
	v_rcp_f32_e32 v49, v30
	s_nop 0
	v_mov_b32_dpp v51, v50 row_bcast:15 row_mask:0xa bank_mask:0xf
	v_add_f32_e32 v30, v50, v51
	v_add_f32_e32 v51, 0x2b8cbccc, v49
	v_cmp_gt_f32_e32 vcc, s5, v51
	v_mov_b32_e32 v50, 0
	s_nop 0
	v_cndmask_b32_e64 v52, 0, 32, vcc
	v_ldexp_f32 v51, v51, v52
	v_log_f32_e32 v51, v51
	v_mov_b32_dpp v50, v30 row_bcast:31 row_mask:0xc bank_mask:0xf
	v_add_f32_e32 v30, v30, v50
	v_mul_f32_e32 v52, 0xbfb8aa3b, v26
	v_mul_f32_e32 v50, 0x3f317217, v51
	v_fma_f32 v50, v51, s51, -v50
	v_exp_f32_e32 v52, v52
	v_fmac_f32_e32 v50, 0x3377d1cf, v51
	v_fmac_f32_e32 v50, 0x3f317217, v51
	v_cmp_lt_f32_e64 s[46:47], |v51|, s52
	v_add_f32_e32 v52, 1.0, v52
	v_rcp_f32_e32 v52, v52
	v_cndmask_b32_e64 v50, v51, v50, s[46:47]
	v_cndmask_b32_e32 v51, 0, v70, vcc
	v_sub_f32_e32 v50, v50, v51
	v_lshlrev_b32_e32 v51, 16, v31
	v_mul_f32_e32 v51, 0xbfb8aa3b, v51
	v_exp_f32_e32 v51, v51
	v_add_f32_dpp v50, v50, v50 row_shr:1 row_mask:0xf bank_mask:0xf bound_ctrl:1
	v_mul_f32_e32 v26, v52, v26
	v_and_b32_e32 v31, 0xffff0000, v31
	v_add_f32_dpp v50, v50, v50 row_shr:2 row_mask:0xf bank_mask:0xf bound_ctrl:1
	v_mul_f32_e32 v31, 0xbfb8aa3b, v31
	v_exp_f32_e32 v31, v31
	v_add_f32_dpp v50, v50, v50 row_shr:4 row_mask:0xf bank_mask:0xf bound_ctrl:1
	v_mul_f32_e32 v26, 0x3db504f3, v26
	v_add_f32_e32 v31, 1.0, v31
	v_add_f32_dpp v52, v50, v50 row_shr:8 row_mask:0xf bank_mask:0xf bound_ctrl:1
	v_add_f32_e32 v50, 1.0, v51
	v_rcp_f32_e32 v50, v50
	v_mov_b32_dpp v53, v52 row_bcast:15 row_mask:0xa bank_mask:0xf
	v_add_f32_e32 v51, v52, v53
	v_mov_b32_e32 v52, 0
	v_add_f32_e32 v53, 0x2b8cbccc, v50
	v_cmp_gt_f32_e32 vcc, s5, v53
	v_mov_b32_dpp v52, v51 row_bcast:31 row_mask:0xc bank_mask:0xf
	v_add_f32_e32 v76, v51, v52
	v_cndmask_b32_e64 v54, 0, 32, vcc
	v_lshlrev_b32_e32 v51, 16, v27
	v_ldexp_f32 v53, v53, v54
	v_mul_f32_e32 v54, 0xbfb8aa3b, v51
	v_log_f32_e32 v53, v53
	v_exp_f32_e32 v54, v54
	v_and_b32_e32 v27, 0xffff0000, v27
	v_mul_f32_e32 v52, 0x3f317217, v53
	v_add_f32_e32 v54, 1.0, v54
	v_fma_f32 v52, v53, s51, -v52
	v_rcp_f32_e32 v54, v54
	v_fmac_f32_e32 v52, 0x3377d1cf, v53
	v_fmac_f32_e32 v52, 0x3f317217, v53
	v_cmp_lt_f32_e64 s[46:47], |v53|, s52
	v_mul_f32_e32 v51, v54, v51
	v_mul_f32_e32 v75, 0x3db504f3, v51
	v_cndmask_b32_e64 v52, v53, v52, s[46:47]
	v_cndmask_b32_e32 v53, 0, v70, vcc
	v_sub_f32_e32 v52, v52, v53
	v_mov_b32_e32 v53, 0
	s_nop 0
	v_add_f32_dpp v51, v52, v52 row_shr:1 row_mask:0xf bank_mask:0xf bound_ctrl:1
	s_nop 1
	v_add_f32_dpp v51, v51, v51 row_shr:2 row_mask:0xf bank_mask:0xf bound_ctrl:1
	s_nop 1
	v_add_f32_dpp v51, v51, v51 row_shr:4 row_mask:0xf bank_mask:0xf bound_ctrl:1
	s_nop 1
	v_add_f32_dpp v52, v51, v51 row_shr:8 row_mask:0xf bank_mask:0xf bound_ctrl:1
	v_rcp_f32_e32 v51, v31
	s_nop 0
	v_mov_b32_dpp v53, v52 row_bcast:15 row_mask:0xa bank_mask:0xf
	v_add_f32_e32 v31, v52, v53
	v_add_f32_e32 v53, 0x2b8cbccc, v51
	v_cmp_gt_f32_e32 vcc, s5, v53
	v_mov_b32_e32 v52, 0
	v_pk_add_f32 v[50:51], v[50:51], 1.0 op_sel_hi:[1,0] neg_lo:[1,0] neg_hi:[1,0]
	v_cndmask_b32_e64 v54, 0, 32, vcc
	v_ldexp_f32 v53, v53, v54
	v_log_f32_e32 v53, v53
	v_mov_b32_dpp v52, v31 row_bcast:31 row_mask:0xc bank_mask:0xf
	v_add_f32_e32 v31, v31, v52
	v_mul_f32_e32 v54, 0xbfb8aa3b, v27
	v_mul_f32_e32 v52, 0x3f317217, v53
	v_fma_f32 v52, v53, s51, -v52
	v_exp_f32_e32 v54, v54
	v_fmac_f32_e32 v52, 0x3377d1cf, v53
	v_fmac_f32_e32 v52, 0x3f317217, v53
	v_cmp_lt_f32_e64 s[46:47], |v53|, s52
	v_add_f32_e32 v54, 1.0, v54
	v_rcp_f32_e32 v54, v54
	v_cndmask_b32_e64 v52, v53, v52, s[46:47]
	v_cndmask_b32_e32 v53, 0, v70, vcc
	v_sub_f32_e32 v52, v52, v53
	v_lshlrev_b32_e32 v53, 16, v20
	v_mul_f32_e32 v53, 0xbfb8aa3b, v53
	v_exp_f32_e32 v53, v53
	v_add_f32_dpp v52, v52, v52 row_shr:1 row_mask:0xf bank_mask:0xf bound_ctrl:1
	v_mul_f32_e32 v27, v54, v27
	v_and_b32_e32 v20, 0xffff0000, v20
	v_add_f32_dpp v52, v52, v52 row_shr:2 row_mask:0xf bank_mask:0xf bound_ctrl:1
	v_mul_f32_e32 v20, 0xbfb8aa3b, v20
	v_exp_f32_e32 v20, v20
	v_add_f32_dpp v52, v52, v52 row_shr:4 row_mask:0xf bank_mask:0xf bound_ctrl:1
	v_mul_f32_e32 v27, 0x3db504f3, v27
	v_add_f32_e32 v20, 1.0, v20
	v_add_f32_dpp v54, v52, v52 row_shr:8 row_mask:0xf bank_mask:0xf bound_ctrl:1
	v_add_f32_e32 v52, 1.0, v53
	v_rcp_f32_e32 v52, v52
	v_mov_b32_dpp v55, v54 row_bcast:15 row_mask:0xa bank_mask:0xf
	v_add_f32_e32 v53, v54, v55
	v_mov_b32_e32 v54, 0
	v_add_f32_e32 v55, 0x2b8cbccc, v52
	v_cmp_gt_f32_e32 vcc, s5, v55
	v_mov_b32_dpp v54, v53 row_bcast:31 row_mask:0xc bank_mask:0xf
	v_add_f32_e32 v78, v53, v54
	v_cndmask_b32_e64 v56, 0, 32, vcc
	s_waitcnt lgkmcnt(0)
	v_lshlrev_b32_e32 v53, 16, v16
	v_ldexp_f32 v55, v55, v56
	v_mul_f32_e32 v56, 0xbfb8aa3b, v53
	v_log_f32_e32 v55, v55
	v_exp_f32_e32 v56, v56
	v_and_b32_e32 v16, 0xffff0000, v16
	v_mul_f32_e32 v54, 0x3f317217, v55
	v_add_f32_e32 v56, 1.0, v56
	v_fma_f32 v54, v55, s51, -v54
	v_rcp_f32_e32 v56, v56
	v_fmac_f32_e32 v54, 0x3377d1cf, v55
	v_fmac_f32_e32 v54, 0x3f317217, v55
	v_cmp_lt_f32_e64 s[46:47], |v55|, s52
	v_mul_f32_e32 v53, v56, v53
	v_mul_f32_e32 v77, 0x3db504f3, v53
	v_cndmask_b32_e64 v54, v55, v54, s[46:47]
	v_cndmask_b32_e32 v55, 0, v70, vcc
	v_sub_f32_e32 v54, v54, v55
	v_mov_b32_e32 v55, 0
	s_nop 0
	v_add_f32_dpp v53, v54, v54 row_shr:1 row_mask:0xf bank_mask:0xf bound_ctrl:1
	s_nop 1
	v_add_f32_dpp v53, v53, v53 row_shr:2 row_mask:0xf bank_mask:0xf bound_ctrl:1
	s_nop 1
	v_add_f32_dpp v53, v53, v53 row_shr:4 row_mask:0xf bank_mask:0xf bound_ctrl:1
	s_nop 1
	v_add_f32_dpp v54, v53, v53 row_shr:8 row_mask:0xf bank_mask:0xf bound_ctrl:1
	v_rcp_f32_e32 v53, v20
	s_nop 0
	v_mov_b32_dpp v55, v54 row_bcast:15 row_mask:0xa bank_mask:0xf
	v_add_f32_e32 v20, v54, v55
	v_add_f32_e32 v55, 0x2b8cbccc, v53
	v_mov_b32_e32 v54, 0
	v_cmp_gt_f32_e32 vcc, s5, v55
	v_pk_add_f32 v[52:53], v[52:53], 1.0 op_sel_hi:[1,0] neg_lo:[1,0] neg_hi:[1,0]
	v_mov_b32_dpp v54, v20 row_bcast:31 row_mask:0xc bank_mask:0xf
	v_cndmask_b32_e64 v56, 0, 32, vcc
	v_ldexp_f32 v55, v55, v56
	v_add_f32_e32 v81, v20, v54
	v_mul_f32_e32 v54, 0xbfb8aa3b, v16
	v_log_f32_e32 v55, v55
	v_exp_f32_e32 v54, v54
	v_mul_f32_e32 v20, 0x3f317217, v55
	v_add_f32_e32 v54, 1.0, v54
	v_fma_f32 v20, v55, s51, -v20
	v_rcp_f32_e32 v54, v54
	v_fmac_f32_e32 v20, 0x3377d1cf, v55
	v_fmac_f32_e32 v20, 0x3f317217, v55
	v_cmp_lt_f32_e64 s[46:47], |v55|, s52
	v_mul_f32_e32 v16, v54, v16
	v_mul_f32_e32 v79, 0x3db504f3, v16
	v_cndmask_b32_e64 v20, v55, v20, s[46:47]
	v_cndmask_b32_e32 v55, 0, v70, vcc
	v_sub_f32_e32 v20, v20, v55
	v_mov_b32_e32 v55, 0
	s_nop 0
	v_add_f32_dpp v16, v20, v20 row_shr:1 row_mask:0xf bank_mask:0xf bound_ctrl:1
	v_lshlrev_b32_e32 v20, 16, v21
	v_mul_f32_e32 v20, 0xbfb8aa3b, v20
	v_exp_f32_e32 v20, v20
	v_add_f32_dpp v16, v16, v16 row_shr:2 row_mask:0xf bank_mask:0xf bound_ctrl:1
	v_add_f32_e32 v20, 1.0, v20
	v_rcp_f32_e32 v54, v20
	v_add_f32_dpp v16, v16, v16 row_shr:4 row_mask:0xf bank_mask:0xf bound_ctrl:1
	v_mov_b32_e32 v20, 0
	s_nop 0
	v_add_f32_dpp v16, v16, v16 row_shr:8 row_mask:0xf bank_mask:0xf bound_ctrl:1
	s_nop 1
	v_mov_b32_dpp v55, v16 row_bcast:15 row_mask:0xa bank_mask:0xf
	v_add_f32_e32 v16, v16, v55
	v_add_f32_e32 v55, 0x2b8cbccc, v54
	v_cmp_gt_f32_e32 vcc, s5, v55
	v_mov_b32_dpp v20, v16 row_bcast:31 row_mask:0xc bank_mask:0xf
	v_add_f32_e32 v82, v16, v20
	v_cndmask_b32_e64 v56, 0, 32, vcc
	v_lshlrev_b32_e32 v16, 16, v17
	v_ldexp_f32 v55, v55, v56
	v_mul_f32_e32 v56, 0xbfb8aa3b, v16
	v_log_f32_e32 v55, v55
	v_exp_f32_e32 v56, v56
	v_mul_f32_e32 v20, 0x3f317217, v55
	v_add_f32_e32 v56, 1.0, v56
	v_fma_f32 v20, v55, s51, -v20
	v_rcp_f32_e32 v56, v56
	v_fmac_f32_e32 v20, 0x3377d1cf, v55
	v_fmac_f32_e32 v20, 0x3f317217, v55
	v_cmp_lt_f32_e64 s[46:47], |v55|, s52
	v_mul_f32_e32 v16, v56, v16
	v_mul_f32_e32 v80, 0x3db504f3, v16
	v_cndmask_b32_e64 v20, v55, v20, s[46:47]
	v_cndmask_b32_e32 v55, 0, v70, vcc
	v_sub_f32_e32 v20, v20, v55
	s_nop 1
	v_add_f32_dpp v16, v20, v20 row_shr:1 row_mask:0xf bank_mask:0xf bound_ctrl:1
	v_and_b32_e32 v20, 0xffff0000, v21
	v_mul_f32_e32 v20, 0xbfb8aa3b, v20
	v_exp_f32_e32 v20, v20
	v_add_f32_dpp v16, v16, v16 row_shr:2 row_mask:0xf bank_mask:0xf bound_ctrl:1
	v_mov_b32_e32 v21, 0
	v_add_f32_e32 v20, 1.0, v20
	v_rcp_f32_e32 v55, v20
	v_add_f32_dpp v16, v16, v16 row_shr:4 row_mask:0xf bank_mask:0xf bound_ctrl:1
	v_mov_b32_e32 v20, 0
	s_nop 0
	v_add_f32_dpp v16, v16, v16 row_shr:8 row_mask:0xf bank_mask:0xf bound_ctrl:1
	s_nop 1
	v_mov_b32_dpp v21, v16 row_bcast:15 row_mask:0xa bank_mask:0xf
	v_add_f32_e32 v16, v16, v21
	v_add_f32_e32 v21, 0x2b8cbccc, v55
	v_cmp_gt_f32_e32 vcc, s5, v21
	v_mov_b32_dpp v20, v16 row_bcast:31 row_mask:0xc bank_mask:0xf
	v_add_f32_e32 v85, v16, v20
	v_cndmask_b32_e64 v56, 0, 32, vcc
	v_and_b32_e32 v16, 0xffff0000, v17
	v_ldexp_f32 v21, v21, v56
	v_mul_f32_e32 v20, 0xbfb8aa3b, v16
	v_log_f32_e32 v21, v21
	v_exp_f32_e32 v20, v20
	v_pk_add_f32 v[54:55], v[54:55], 1.0 op_sel_hi:[1,0] neg_lo:[1,0] neg_hi:[1,0]
	v_mul_f32_e32 v17, 0x3f317217, v21
	v_add_f32_e32 v20, 1.0, v20
	v_fma_f32 v17, v21, s51, -v17
	v_rcp_f32_e32 v20, v20
	v_fmac_f32_e32 v17, 0x3377d1cf, v21
	v_fmac_f32_e32 v17, 0x3f317217, v21
	v_cmp_lt_f32_e64 s[46:47], |v21|, s52
	v_mul_f32_e32 v16, v20, v16
	v_mul_f32_e32 v83, 0x3db504f3, v16
	v_cndmask_b32_e64 v17, v21, v17, s[46:47]
	v_cndmask_b32_e32 v21, 0, v70, vcc
	v_sub_f32_e32 v17, v17, v21
	v_mov_b32_e32 v20, 0
	s_nop 0
	v_add_f32_dpp v16, v17, v17 row_shr:1 row_mask:0xf bank_mask:0xf bound_ctrl:1
	v_lshlrev_b32_e32 v17, 16, v22
	v_mul_f32_e32 v17, 0xbfb8aa3b, v17
	v_exp_f32_e32 v17, v17
	v_add_f32_dpp v16, v16, v16 row_shr:2 row_mask:0xf bank_mask:0xf bound_ctrl:1
	v_add_f32_e32 v17, 1.0, v17
	v_rcp_f32_e32 v56, v17
	v_add_f32_dpp v16, v16, v16 row_shr:4 row_mask:0xf bank_mask:0xf bound_ctrl:1
	v_mov_b32_e32 v17, 0
	s_nop 0
	v_add_f32_dpp v16, v16, v16 row_shr:8 row_mask:0xf bank_mask:0xf bound_ctrl:1
	s_nop 1
	v_mov_b32_dpp v20, v16 row_bcast:15 row_mask:0xa bank_mask:0xf
	v_add_f32_e32 v16, v16, v20
	v_add_f32_e32 v20, 0x2b8cbccc, v56
	v_cmp_gt_f32_e32 vcc, s5, v20
	v_mov_b32_dpp v17, v16 row_bcast:31 row_mask:0xc bank_mask:0xf
	v_add_f32_e32 v89, v16, v17
	v_cndmask_b32_e64 v21, 0, 32, vcc
	v_lshlrev_b32_e32 v16, 16, v18
	v_ldexp_f32 v20, v20, v21
	v_mul_f32_e32 v21, 0xbfb8aa3b, v16
	v_log_f32_e32 v20, v20
	v_exp_f32_e32 v21, v21
	v_mul_f32_e32 v17, 0x3f317217, v20
	v_add_f32_e32 v21, 1.0, v21
	v_fma_f32 v17, v20, s51, -v17
	v_rcp_f32_e32 v21, v21
	v_fmac_f32_e32 v17, 0x3377d1cf, v20
	v_fmac_f32_e32 v17, 0x3f317217, v20
	v_cmp_lt_f32_e64 s[46:47], |v20|, s52
	v_mul_f32_e32 v16, v21, v16
	v_mul_f32_e32 v84, 0x3db504f3, v16
	v_cndmask_b32_e64 v17, v20, v17, s[46:47]
	v_cndmask_b32_e32 v20, 0, v70, vcc
	v_sub_f32_e32 v17, v17, v20
	v_mov_b32_e32 v20, 0
	s_nop 0
	v_add_f32_dpp v16, v17, v17 row_shr:1 row_mask:0xf bank_mask:0xf bound_ctrl:1
	v_and_b32_e32 v17, 0xffff0000, v22
	v_mul_f32_e32 v17, 0xbfb8aa3b, v17
	v_exp_f32_e32 v17, v17
	v_add_f32_dpp v16, v16, v16 row_shr:2 row_mask:0xf bank_mask:0xf bound_ctrl:1
	v_add_f32_e32 v17, 1.0, v17
	v_rcp_f32_e32 v57, v17
	v_add_f32_dpp v16, v16, v16 row_shr:4 row_mask:0xf bank_mask:0xf bound_ctrl:1
	v_mov_b32_e32 v17, 0
	s_nop 0
	v_add_f32_dpp v16, v16, v16 row_shr:8 row_mask:0xf bank_mask:0xf bound_ctrl:1
	s_nop 1
	v_mov_b32_dpp v20, v16 row_bcast:15 row_mask:0xa bank_mask:0xf
	v_add_f32_e32 v16, v16, v20
	v_add_f32_e32 v20, 0x2b8cbccc, v57
	v_cmp_gt_f32_e32 vcc, s5, v20
	v_mov_b32_dpp v17, v16 row_bcast:31 row_mask:0xc bank_mask:0xf
	v_add_f32_e32 v90, v16, v17
	v_cndmask_b32_e64 v21, 0, 32, vcc
	v_and_b32_e32 v16, 0xffff0000, v18
	v_ldexp_f32 v20, v20, v21
	v_mul_f32_e32 v18, 0xbfb8aa3b, v16
	v_log_f32_e32 v20, v20
	v_exp_f32_e32 v18, v18
	v_pk_add_f32 v[56:57], v[56:57], 1.0 op_sel_hi:[1,0] neg_lo:[1,0] neg_hi:[1,0]
	v_mul_f32_e32 v17, 0x3f317217, v20
	v_add_f32_e32 v18, 1.0, v18
	v_fma_f32 v17, v20, s51, -v17
	v_rcp_f32_e32 v18, v18
	v_fmac_f32_e32 v17, 0x3377d1cf, v20
	v_fmac_f32_e32 v17, 0x3f317217, v20
	v_cmp_lt_f32_e64 s[46:47], |v20|, s52
	v_mul_f32_e32 v16, v18, v16
	v_mul_f32_e32 v91, 0x3db504f3, v16
	v_cndmask_b32_e64 v17, v20, v17, s[46:47]
	v_cndmask_b32_e32 v20, 0, v70, vcc
	v_sub_f32_e32 v17, v17, v20
	v_mov_b32_e32 v18, 0
	s_nop 0
	v_add_f32_dpp v16, v17, v17 row_shr:1 row_mask:0xf bank_mask:0xf bound_ctrl:1
	v_lshlrev_b32_e32 v17, 16, v23
	v_mul_f32_e32 v17, 0xbfb8aa3b, v17
	v_exp_f32_e32 v17, v17
	v_add_f32_dpp v16, v16, v16 row_shr:2 row_mask:0xf bank_mask:0xf bound_ctrl:1
	v_add_f32_e32 v17, 1.0, v17
	v_rcp_f32_e32 v58, v17
	v_add_f32_dpp v16, v16, v16 row_shr:4 row_mask:0xf bank_mask:0xf bound_ctrl:1
	v_mov_b32_e32 v17, 0
	s_nop 0
	v_add_f32_dpp v16, v16, v16 row_shr:8 row_mask:0xf bank_mask:0xf bound_ctrl:1
	s_nop 1
	v_mov_b32_dpp v18, v16 row_bcast:15 row_mask:0xa bank_mask:0xf
	v_add_f32_e32 v16, v16, v18
	v_add_f32_e32 v18, 0x2b8cbccc, v58
	v_cmp_gt_f32_e32 vcc, s5, v18
	v_mov_b32_dpp v17, v16 row_bcast:31 row_mask:0xc bank_mask:0xf
	v_add_f32_e32 v92, v16, v17
	v_cndmask_b32_e64 v20, 0, 32, vcc
	v_lshlrev_b32_e32 v16, 16, v19
	v_ldexp_f32 v18, v18, v20
	v_mul_f32_e32 v20, 0xbfb8aa3b, v16
	v_log_f32_e32 v18, v18
	v_exp_f32_e32 v20, v20
	v_mul_f32_e32 v17, 0x3f317217, v18
	v_add_f32_e32 v20, 1.0, v20
	v_fma_f32 v17, v18, s51, -v17
	v_rcp_f32_e32 v20, v20
	v_fmac_f32_e32 v17, 0x3377d1cf, v18
	v_fmac_f32_e32 v17, 0x3f317217, v18
	v_cmp_lt_f32_e64 s[46:47], |v18|, s52
	v_mul_f32_e32 v16, v20, v16
	v_mul_f32_e32 v93, 0x3db504f3, v16
	v_cndmask_b32_e64 v17, v18, v17, s[46:47]
	v_cndmask_b32_e32 v18, 0, v70, vcc
	v_sub_f32_e32 v17, v17, v18
	v_mov_b32_e32 v18, 0
	s_nop 0
	v_add_f32_dpp v16, v17, v17 row_shr:1 row_mask:0xf bank_mask:0xf bound_ctrl:1
	v_and_b32_e32 v17, 0xffff0000, v23
	v_mul_f32_e32 v17, 0xbfb8aa3b, v17
	v_exp_f32_e32 v17, v17
	v_add_f32_dpp v16, v16, v16 row_shr:2 row_mask:0xf bank_mask:0xf bound_ctrl:1
	v_add_f32_e32 v17, 1.0, v17
	v_rcp_f32_e32 v59, v17
	v_add_f32_dpp v16, v16, v16 row_shr:4 row_mask:0xf bank_mask:0xf bound_ctrl:1
	v_mov_b32_e32 v17, 0
	s_nop 0
	v_add_f32_dpp v16, v16, v16 row_shr:8 row_mask:0xf bank_mask:0xf bound_ctrl:1
	s_nop 1
	v_mov_b32_dpp v18, v16 row_bcast:15 row_mask:0xa bank_mask:0xf
	v_add_f32_e32 v16, v16, v18
	v_add_f32_e32 v18, 0x2b8cbccc, v59
	v_cmp_gt_f32_e32 vcc, s5, v18
	v_mov_b32_dpp v17, v16 row_bcast:31 row_mask:0xc bank_mask:0xf
	v_add_f32_e32 v94, v16, v17
	v_cndmask_b32_e64 v20, 0, 32, vcc
	v_and_b32_e32 v16, 0xffff0000, v19
	v_ldexp_f32 v18, v18, v20
	v_mul_f32_e32 v19, 0xbfb8aa3b, v16
	v_log_f32_e32 v18, v18
	v_exp_f32_e32 v19, v19
	v_pk_add_f32 v[58:59], v[58:59], 1.0 op_sel_hi:[1,0] neg_lo:[1,0] neg_hi:[1,0]
	v_mul_f32_e32 v17, 0x3f317217, v18
	v_add_f32_e32 v19, 1.0, v19
	v_fma_f32 v17, v18, s51, -v17
	v_rcp_f32_e32 v19, v19
	v_fmac_f32_e32 v17, 0x3377d1cf, v18
	v_fmac_f32_e32 v17, 0x3f317217, v18
	v_cmp_lt_f32_e64 s[46:47], |v18|, s52
	v_mul_f32_e32 v16, v19, v16
	v_mul_f32_e32 v95, 0x3db504f3, v16
	v_cndmask_b32_e64 v17, v18, v17, s[46:47]
	v_cndmask_b32_e32 v18, 0, v70, vcc
	v_sub_f32_e32 v17, v17, v18
	v_mov_b32_e32 v18, 0
	s_nop 0
	v_add_f32_dpp v16, v17, v17 row_shr:1 row_mask:0xf bank_mask:0xf bound_ctrl:1
	v_mov_b32_e32 v17, 0
	s_nop 0
	v_add_f32_dpp v16, v16, v16 row_shr:2 row_mask:0xf bank_mask:0xf bound_ctrl:1
	s_nop 1
	v_add_f32_dpp v16, v16, v16 row_shr:4 row_mask:0xf bank_mask:0xf bound_ctrl:1
	s_nop 1
	v_add_f32_dpp v16, v16, v16 row_shr:8 row_mask:0xf bank_mask:0xf bound_ctrl:1
	s_nop 1
	v_mov_b32_dpp v17, v16 row_bcast:15 row_mask:0xa bank_mask:0xf
	v_add_f32_e32 v17, v16, v17
	v_subrev_f32_e32 v16, s3, v28
	v_cndmask_b32_e64 v16, v16, v28, s[24:25]
	v_max_f32_e32 v16, 0xc2a00000, v16
	v_mul_f32_e32 v16, 0x3fb8aa3b, v16
	v_exp_f32_e32 v19, v16
	v_sub_f32_e32 v16, s3, v28
	v_min_f32_e32 v16, 0x42a00000, v16
	v_mul_f32_e32 v16, 0x3fb8aa3b, v16
	v_exp_f32_e32 v16, v16
	v_mov_b32_dpp v18, v17 row_bcast:31 row_mask:0xc bank_mask:0xf
	v_readlane_b32 s53, v19, 31
	v_add_f32_e32 v96, v17, v18
	v_readlane_b32 s3, v16, 63
	v_mul_f32_e32 v17, s53, v19
	v_cndmask_b32_e64 v17, v17, v19, s[24:25]
	v_rcp_f32_e32 v60, s3
	v_readlane_b32 s3, v72, 31
	v_mul_f32_e32 v28, v61, v17
	v_rcp_f32_e32 v20, v19
	v_subrev_f32_e32 v17, s3, v72
	v_cndmask_b32_e64 v17, v17, v72, s[24:25]
	v_max_f32_e32 v17, 0xc2a00000, v17
	v_mul_f32_e32 v17, 0x3fb8aa3b, v17
	v_exp_f32_e32 v18, v17
	v_sub_f32_e32 v17, s3, v72
	v_min_f32_e32 v17, 0x42a00000, v17
	v_mul_f32_e32 v17, 0x3fb8aa3b, v17
	v_exp_f32_e32 v17, v17
	v_readlane_b32 s55, v18, 31
	v_mul_f32_e32 v21, v61, v19
	v_rcp_f32_e32 v86, v18
	v_mul_f32_e32 v19, s55, v18
	v_cndmask_b32_e64 v19, v19, v18, s[24:25]
	v_readlane_b32 s3, v17, 63
	v_mul_f32_e32 v72, v24, v19
	v_mul_f32_e32 v24, v24, v18
	v_pk_add_f32 v[18:19], v[44:45], 1.0 op_sel_hi:[1,0] neg_lo:[1,0] neg_hi:[1,0]
	v_rcp_f32_e32 v61, s3
	v_mul_f32_e32 v20, v18, v20
	v_readlane_b32 s3, v29, 31
	v_cndmask_b32_e64 v44, v21, v20, s[24:25]
	v_pk_mul_f32 v[20:21], v[18:19], v[16:17]
	v_subrev_f32_e32 v17, s3, v29
	v_cndmask_b32_e64 v17, v17, v29, s[24:25]
	v_max_f32_e32 v17, 0xc2a00000, v17
	v_sub_f32_e32 v18, s3, v29
	v_mul_f32_e32 v17, 0x3fb8aa3b, v17
	v_min_f32_e32 v18, 0x42a00000, v18
	v_exp_f32_e32 v17, v17
	v_mul_f32_e32 v18, 0x3fb8aa3b, v18
	v_exp_f32_e32 v18, v18
	v_mul_f32_e32 v16, v19, v86
	v_readlane_b32 s56, v17, 31
	v_cndmask_b32_e64 v16, v24, v16, s[24:25]
	v_readlane_b32 s3, v18, 63
	v_mul_f32_e32 v19, s56, v17
	v_cvt_pk_bf16_f32 v16, v44, v16
	v_rcp_f32_e32 v44, s3
	v_cndmask_b32_e64 v19, v19, v17, s[24:25]
	v_readlane_b32 s3, v74, 31
	v_pk_mul_f32 v[22:23], v[60:61], v[20:21]
	v_cvt_pk_bf16_f32 v24, v28, v72
	v_cvt_pk_bf16_f32 v28, v20, v21
	v_mul_f32_e32 v21, v71, v19
	v_subrev_f32_e32 v19, s3, v74
	v_cndmask_b32_e64 v19, v19, v74, s[24:25]
	v_max_f32_e32 v19, 0xc2a00000, v19
	v_mul_f32_e32 v19, 0x3fb8aa3b, v19
	v_cvt_pk_bf16_f32 v20, v22, v23
	v_exp_f32_e32 v22, v19
	v_sub_f32_e32 v19, s3, v74
	v_min_f32_e32 v19, 0x42a00000, v19
	v_mul_f32_e32 v19, 0x3fb8aa3b, v19
	v_exp_f32_e32 v19, v19
	v_rcp_f32_e32 v29, v17
	v_readlane_b32 s65, v22, 31
	v_rcp_f32_e32 v72, v22
	v_mul_f32_e32 v17, v71, v17
	v_mul_f32_e32 v23, s65, v22
	v_cndmask_b32_e64 v23, v23, v22, s[24:25]
	v_readlane_b32 s3, v19, 63
	v_mul_f32_e32 v71, v25, v23
	v_mul_f32_e32 v25, v25, v22
	v_pk_add_f32 v[22:23], v[46:47], 1.0 op_sel_hi:[1,0] neg_lo:[1,0] neg_hi:[1,0]
	v_rcp_f32_e32 v45, s3
	v_mul_f32_e32 v29, v22, v29
	v_pk_mul_f32 v[18:19], v[22:23], v[18:19]
	v_mul_f32_e32 v22, v23, v72
	v_readlane_b32 s3, v30, 31
	v_cndmask_b32_e64 v22, v25, v22, s[24:25]
	v_cvt_pk_bf16_f32 v25, v21, v71
	v_subrev_f32_e32 v21, s3, v30
	v_cndmask_b32_e64 v21, v21, v30, s[24:25]
	v_max_f32_e32 v21, 0xc2a00000, v21
	v_mul_f32_e32 v21, 0x3fb8aa3b, v21
	v_exp_f32_e32 v71, v21
	v_sub_f32_e32 v21, s3, v30
	v_min_f32_e32 v21, 0x42a00000, v21
	v_cndmask_b32_e64 v17, v17, v29, s[24:25]
	v_mul_f32_e32 v21, 0x3fb8aa3b, v21
	v_cvt_pk_bf16_f32 v17, v17, v22
	v_exp_f32_e32 v22, v21
	v_readlane_b32 s78, v71, 31
	v_pk_mul_f32 v[46:47], v[44:45], v[18:19]
	v_cvt_pk_bf16_f32 v29, v18, v19
	v_readlane_b32 s3, v22, 63
	v_mul_f32_e32 v18, s78, v71
	v_cvt_pk_bf16_f32 v21, v46, v47
	v_rcp_f32_e32 v46, s3
	v_cndmask_b32_e64 v18, v18, v71, s[24:25]
	v_readlane_b32 s3, v76, 31
	v_mul_f32_e32 v30, v73, v18
	v_rcp_f32_e32 v72, v71
	v_subrev_f32_e32 v18, s3, v76
	v_cndmask_b32_e64 v18, v18, v76, s[24:25]
	v_max_f32_e32 v18, 0xc2a00000, v18
	v_mul_f32_e32 v18, 0x3fb8aa3b, v18
	v_exp_f32_e32 v18, v18
	v_sub_f32_e32 v19, s3, v76
	v_min_f32_e32 v19, 0x42a00000, v19
	v_mul_f32_e32 v19, 0x3fb8aa3b, v19
	v_exp_f32_e32 v23, v19
	v_readlane_b32 s79, v18, 31
	v_rcp_f32_e32 v74, v18
	v_mul_f32_e32 v71, v73, v71
	v_mul_f32_e32 v19, s79, v18
	v_cndmask_b32_e64 v19, v19, v18, s[24:25]
	v_readlane_b32 s3, v23, 63
	v_mul_f32_e32 v73, v26, v19
	v_mul_f32_e32 v26, v26, v18
	v_pk_add_f32 v[18:19], v[48:49], 1.0 op_sel_hi:[1,0] neg_lo:[1,0] neg_hi:[1,0]
	v_rcp_f32_e32 v47, s3
	v_mul_f32_e32 v48, v18, v72
	v_pk_mul_f32 v[22:23], v[18:19], v[22:23]
	v_mul_f32_e32 v18, v19, v74
	v_readlane_b32 s3, v31, 31
	v_cndmask_b32_e64 v18, v26, v18, s[24:25]
	v_cvt_pk_bf16_f32 v26, v30, v73
	v_sub_f32_e32 v30, s3, v31
	v_min_f32_e32 v30, 0x42a00000, v30
	v_mul_f32_e32 v30, 0x3fb8aa3b, v30
	v_exp_f32_e32 v72, v30
	v_cndmask_b32_e64 v71, v71, v48, s[24:25]
	v_pk_mul_f32 v[48:49], v[46:47], v[22:23]
	v_subrev_f32_e32 v19, s3, v31
	v_readlane_b32 s3, v72, 63
	v_cvt_pk_bf16_f32 v30, v22, v23
	v_cvt_pk_bf16_f32 v22, v48, v49
	v_rcp_f32_e32 v48, s3
	v_readlane_b32 s3, v78, 31
	v_cndmask_b32_e64 v19, v19, v31, s[24:25]
	v_max_f32_e32 v19, 0xc2a00000, v19
	v_subrev_f32_e32 v31, s3, v78
	v_cndmask_b32_e64 v31, v31, v78, s[24:25]
	v_mul_f32_e32 v19, 0x3fb8aa3b, v19
	v_max_f32_e32 v31, 0xc2a00000, v31
	v_exp_f32_e32 v19, v19
	v_mul_f32_e32 v31, 0x3fb8aa3b, v31
	v_exp_f32_e32 v31, v31
	v_sub_f32_e32 v49, s3, v78
	v_min_f32_e32 v49, 0x42a00000, v49
	v_mul_f32_e32 v49, 0x3fb8aa3b, v49
	v_cvt_pk_bf16_f32 v18, v71, v18
	v_exp_f32_e32 v73, v49
	v_rcp_f32_e32 v71, v19
	v_readlane_b32 s80, v31, 31
	v_rcp_f32_e32 v78, v31
	v_readlane_b32 s86, v19, 31
	v_mul_f32_e32 v74, s80, v31
	v_cndmask_b32_e64 v74, v74, v31, s[24:25]
	v_mul_f32_e32 v23, s86, v19
	v_cndmask_b32_e64 v23, v23, v19, s[24:25]
	v_mul_f32_e32 v19, v75, v19
	v_readlane_b32 s3, v73, 63
	v_mul_f32_e32 v76, v27, v74
	v_mul_f32_e32 v27, v27, v31
	v_mul_f32_e32 v31, v50, v71
	v_mul_f32_e32 v23, v75, v23
	v_rcp_f32_e32 v49, s3
	v_cndmask_b32_e64 v19, v19, v31, s[24:25]
	v_mul_f32_e32 v31, v51, v78
	v_readlane_b32 s3, v81, 31
	v_cndmask_b32_e64 v31, v27, v31, s[24:25]
	v_cvt_pk_bf16_f32 v27, v23, v76
	v_subrev_f32_e32 v23, s3, v81
	v_cndmask_b32_e64 v23, v23, v81, s[24:25]
	v_max_f32_e32 v23, 0xc2a00000, v23
	v_mul_f32_e32 v23, 0x3fb8aa3b, v23
	v_pk_mul_f32 v[72:73], v[50:51], v[72:73]
	v_exp_f32_e32 v51, v23
	v_sub_f32_e32 v23, s3, v81
	v_min_f32_e32 v23, 0x42a00000, v23
	v_mul_f32_e32 v23, 0x3fb8aa3b, v23
	v_exp_f32_e32 v86, v23
	v_pk_mul_f32 v[74:75], v[48:49], v[72:73]
	v_cvt_pk_bf16_f32 v19, v19, v31
	v_cvt_pk_bf16_f32 v31, v72, v73
	v_readlane_b32 s3, v86, 63
	v_readlane_b32 s87, v51, 31
	v_cvt_pk_bf16_f32 v23, v74, v75
	v_rcp_f32_e32 v50, s3
	v_readlane_b32 s3, v82, 31
	v_mul_f32_e32 v71, s87, v51
	v_cndmask_b32_e64 v71, v71, v51, s[24:25]
	v_subrev_f32_e32 v72, s3, v82
	v_cndmask_b32_e64 v72, v72, v82, s[24:25]
	v_max_f32_e32 v72, 0xc2a00000, v72
	v_mul_f32_e32 v72, 0x3fb8aa3b, v72
	v_exp_f32_e32 v72, v72
	v_sub_f32_e32 v73, s3, v82
	v_min_f32_e32 v73, 0x42a00000, v73
	v_mul_f32_e32 v73, 0x3fb8aa3b, v73
	v_exp_f32_e32 v87, v73
	v_rcp_f32_e32 v73, v51
	v_mul_f32_e32 v71, v77, v71
	v_mul_f32_e32 v74, v77, v51
	v_rcp_f32_e32 v77, v72
	v_readlane_b32 s88, v72, 31
	v_mul_f32_e32 v73, v52, v73
	v_readlane_b32 s3, v87, 63
	v_mul_f32_e32 v75, s88, v72
	v_cndmask_b32_e64 v75, v75, v72, s[24:25]
	v_mul_f32_e32 v76, v79, v75
	v_mul_f32_e32 v72, v79, v72
	v_cndmask_b32_e64 v73, v74, v73, s[24:25]
	v_pk_mul_f32 v[74:75], v[52:53], v[86:87]
	v_mul_f32_e32 v52, v53, v77
	v_rcp_f32_e32 v51, s3
	v_cndmask_b32_e64 v52, v72, v52, s[24:25]
	v_readlane_b32 s3, v85, 31
	v_cvt_pk_bf16_f32 v72, v71, v76
	v_cvt_pk_bf16_f32 v76, v73, v52
	v_subrev_f32_e32 v52, s3, v85
	v_cndmask_b32_e64 v52, v52, v85, s[24:25]
	v_max_f32_e32 v52, 0xc2a00000, v52
	v_mul_f32_e32 v52, 0x3fb8aa3b, v52
	v_exp_f32_e32 v53, v52
	v_sub_f32_e32 v52, s3, v85
	v_min_f32_e32 v52, 0x42a00000, v52
	v_mul_f32_e32 v52, 0x3fb8aa3b, v52
	v_exp_f32_e32 v88, v52
	v_pk_mul_f32 v[78:79], v[50:51], v[74:75]
	v_cvt_pk_bf16_f32 v82, v74, v75
	v_readlane_b32 s97, v53, 31
	v_readlane_b32 s3, v88, 63
	v_mul_f32_e32 v75, v80, v53
	v_mul_f32_e32 v71, s97, v53
	v_rcp_f32_e32 v52, s3
	v_readlane_b32 s3, v89, 31
	v_cndmask_b32_e64 v71, v71, v53, s[24:25]
	v_mul_f32_e32 v71, v80, v71
	v_subrev_f32_e32 v73, s3, v89
	v_cndmask_b32_e64 v73, v73, v89, s[24:25]
	v_max_f32_e32 v73, 0xc2a00000, v73
	v_mul_f32_e32 v73, 0x3fb8aa3b, v73
	v_exp_f32_e32 v73, v73
	v_sub_f32_e32 v74, s3, v89
	v_min_f32_e32 v74, 0x42a00000, v74
	v_mul_f32_e32 v74, 0x3fb8aa3b, v74
	v_exp_f32_e32 v89, v74
	v_rcp_f32_e32 v74, v53
	v_rcp_f32_e32 v80, v73
	v_readlane_b32 s95, v73, 31
	v_readlane_b32 s3, v89, 63
	v_mul_f32_e32 v74, v54, v74
	v_mul_f32_e32 v77, s95, v73
	v_cndmask_b32_e64 v77, v77, v73, s[24:25]
	v_mul_f32_e32 v73, v83, v73
	v_cndmask_b32_e64 v81, v75, v74, s[24:25]
	v_pk_mul_f32 v[74:75], v[54:55], v[88:89]
	v_mul_f32_e32 v54, v55, v80
	v_rcp_f32_e32 v53, s3
	v_mul_f32_e32 v77, v83, v77
	v_cndmask_b32_e64 v54, v73, v54, s[24:25]
	v_readlane_b32 s3, v90, 31
	v_cvt_pk_bf16_f32 v73, v71, v77
	v_cvt_pk_bf16_f32 v77, v81, v54
	v_subrev_f32_e32 v54, s3, v90
	v_cndmask_b32_e64 v54, v54, v90, s[24:25]
	v_max_f32_e32 v54, 0xc2a00000, v54
	v_mul_f32_e32 v54, 0x3fb8aa3b, v54
	v_exp_f32_e32 v55, v54
	v_sub_f32_e32 v54, s3, v90
	v_min_f32_e32 v54, 0x42a00000, v54
	v_mul_f32_e32 v54, 0x3fb8aa3b, v54
	v_exp_f32_e32 v80, v54
	v_cvt_pk_bf16_f32 v86, v78, v79
	v_pk_mul_f32 v[78:79], v[52:53], v[74:75]
	v_cvt_pk_bf16_f32 v83, v74, v75
	v_readlane_b32 s3, v80, 63
	v_readlane_b32 s96, v55, 31
	v_cvt_pk_bf16_f32 v87, v78, v79
	v_rcp_f32_e32 v54, s3
	v_readlane_b32 s3, v92, 31
	v_mul_f32_e32 v71, s96, v55
	v_cndmask_b32_e64 v71, v71, v55, s[24:25]
	v_subrev_f32_e32 v74, s3, v92
	v_cndmask_b32_e64 v74, v74, v92, s[24:25]
	v_max_f32_e32 v74, 0xc2a00000, v74
	v_mul_f32_e32 v74, 0x3fb8aa3b, v74
	v_exp_f32_e32 v74, v74
	v_sub_f32_e32 v75, s3, v92
	v_min_f32_e32 v75, 0x42a00000, v75
	v_mul_f32_e32 v75, 0x3fb8aa3b, v75
	v_mul_f32_e32 v71, v84, v71
	v_exp_f32_e32 v81, v75
	v_rcp_f32_e32 v75, v55
	v_mul_f32_e32 v78, v84, v55
	v_rcp_f32_e32 v84, v74
	v_readlane_b32 s93, v74, 31
	v_readlane_b32 s3, v81, 63
	v_mul_f32_e32 v75, v56, v75
	v_mul_f32_e32 v79, s93, v74
	v_cndmask_b32_e64 v79, v79, v74, s[24:25]
	v_mul_f32_e32 v74, v91, v74
	v_pk_mul_f32 v[80:81], v[56:57], v[80:81]
	v_mul_f32_e32 v56, v57, v84
	v_rcp_f32_e32 v55, s3
	v_cndmask_b32_e64 v75, v78, v75, s[24:25]
	v_cndmask_b32_e64 v56, v74, v56, s[24:25]
	v_readlane_b32 s3, v94, 31
	v_cvt_pk_bf16_f32 v78, v75, v56
	v_mul_f32_e32 v79, v91, v79
	v_subrev_f32_e32 v56, s3, v94
	v_cndmask_b32_e64 v56, v56, v94, s[24:25]
	v_max_f32_e32 v56, 0xc2a00000, v56
	v_mul_f32_e32 v56, 0x3fb8aa3b, v56
	v_exp_f32_e32 v57, v56
	v_sub_f32_e32 v56, s3, v94
	v_min_f32_e32 v56, 0x42a00000, v56
	v_mul_f32_e32 v56, 0x3fb8aa3b, v56
	v_exp_f32_e32 v90, v56
	v_cvt_pk_bf16_f32 v74, v71, v79
	v_pk_mul_f32 v[88:89], v[54:55], v[80:81]
	v_readlane_b32 s3, v57, 31
	v_readlane_b32 s46, v90, 63
	v_cvt_pk_bf16_f32 v88, v88, v89
	v_mul_f32_e32 v71, s3, v57
	v_rcp_f32_e32 v56, s46
	v_readlane_b32 s46, v96, 31
	v_cvt_pk_bf16_f32 v84, v80, v81
	v_cndmask_b32_e64 v71, v71, v57, s[24:25]
	v_subrev_f32_e32 v75, s46, v96
	v_cndmask_b32_e64 v75, v75, v96, s[24:25]
	v_sub_f32_e32 v79, s46, v96
	v_max_f32_e32 v75, 0xc2a00000, v75
	v_min_f32_e32 v79, 0x42a00000, v79
	v_mul_f32_e32 v75, 0x3fb8aa3b, v75
	v_mul_f32_e32 v79, 0x3fb8aa3b, v79
	v_exp_f32_e32 v75, v75
	v_exp_f32_e32 v91, v79
	v_rcp_f32_e32 v79, v57
	v_mul_f32_e32 v80, v93, v57
	v_rcp_f32_e32 v89, v75
	v_readlane_b32 s46, v91, 63
	v_readlane_b32 s94, v75, 31
	v_mul_f32_e32 v79, v58, v79
	v_rcp_f32_e32 v57, s46
	v_mul_f32_e32 v81, s94, v75
	v_cndmask_b32_e64 v81, v81, v75, s[24:25]
	v_mul_f32_e32 v85, v95, v81
	v_mul_f32_e32 v75, v95, v75
	v_cndmask_b32_e64 v79, v80, v79, s[24:25]
	v_pk_mul_f32 v[80:81], v[58:59], v[90:91]
	v_mul_f32_e32 v58, v59, v89
	v_mul_f32_e32 v71, v93, v71
	v_pk_mul_f32 v[90:91], v[56:57], v[80:81]
	v_cndmask_b32_e64 v58, v75, v58, s[24:25]
	v_cvt_pk_bf16_f32 v75, v71, v85
	v_cvt_pk_bf16_f32 v79, v79, v58
	v_cvt_pk_bf16_f32 v85, v80, v81
	v_cvt_pk_bf16_f32 v89, v90, v91
	ds_write_b128 v63, v[24:27]
	ds_write_b128 v63, v[16:19] offset:17408
	ds_write_b128 v63, v[28:31] offset:34816
	ds_write_b128 v63, v[20:23] offset:52224
	ds_write_b128 v63, v[72:75] offset:16
	ds_write_b128 v63, v[76:79] offset:17424
	ds_write_b128 v63, v[82:85] offset:34832
	ds_write_b128 v63, v[86:89] offset:52240
	s_and_saveexec_b64 s[46:47], s[26:27]
	s_cbranch_execz .LBB0_837
	v_mul_f32_e32 v30, s53, v60
	v_mul_f32_e32 v29, s55, v61
	v_cndmask_b32_e64 v30, 0, v30, s[6:7]
	v_mul_f32_e32 v28, s56, v44
	v_cndmask_b32_e64 v29, v30, v29, s[8:9]
	v_mul_f32_e32 v27, s65, v45
	v_cndmask_b32_e64 v28, v29, v28, s[10:11]
	v_mul_f32_e32 v26, s78, v46
	v_cndmask_b32_e64 v27, v28, v27, s[12:13]
	v_mul_f32_e32 v25, s79, v47
	v_cndmask_b32_e64 v26, v27, v26, s[14:15]
	v_mul_f32_e32 v24, s86, v48
	v_cndmask_b32_e64 v25, v26, v25, s[16:17]
	v_mul_f32_e32 v23, s80, v49
	v_cndmask_b32_e64 v24, v25, v24, s[18:19]
	v_mul_f32_e32 v22, s87, v50
	v_cndmask_b32_e64 v23, v24, v23, s[20:21]
	v_mul_f32_e32 v21, s88, v51
	v_cndmask_b32_e64 v22, v23, v22, s[42:43]
	v_mul_f32_e32 v20, s97, v52
	v_cndmask_b32_e64 v21, v22, v21, s[40:41]
	v_mul_f32_e32 v19, s95, v53
	v_cndmask_b32_e64 v20, v21, v20, s[38:39]
	v_mul_f32_e32 v18, s96, v54
	v_cndmask_b32_e64 v19, v20, v19, s[36:37]
	v_mul_f32_e32 v17, s93, v55
	v_cndmask_b32_e64 v18, v19, v18, s[34:35]
	v_mul_f32_e32 v16, s3, v56
	v_cndmask_b32_e64 v17, v18, v17, s[30:31]
	v_cndmask_b32_e64 v16, v17, v16, s[28:29]
	v_mul_f32_e32 v17, s94, v57
	v_cndmask_b32_e64 v18, v16, v17, s[44:45]
	v_lshl_add_u64 v[16:17], v[40:41], 0, s[74:75]
	global_store_dword v[16:17], v18, off nt
	s_branch .LBB0_837

.LBB0_843:
	s_or_b64 exec, exec, s[28:29]
	s_waitcnt lgkmcnt(0)
	s_barrier
	ds_read_b128 v[24:27], v202
	ds_read_b128 v[28:31], v202 offset:9216
	v_lshl_add_u64 v[32:33], v[186:187], 4, s[26:27]
	s_addk_i32 s35, 0x100
	v_mov_b64_e32 v[42:43], v[22:23]
	s_waitcnt lgkmcnt(1)
	global_store_dwordx4 v[32:33], v[24:27], off nt
	v_mov_b64_e32 v[38:39], v[18:19]
	s_cmpk_lg_i32 s35, 0x800
	v_add_co_u32_e32 v24, vcc, 0x2000, v32
	v_mov_b64_e32 v[40:41], v[20:21]
	s_nop 0
	v_addc_co_u32_e32 v25, vcc, 0, v33, vcc
	s_waitcnt lgkmcnt(0)
	global_store_dwordx4 v[24:25], v[28:31], off nt
	ds_read_b128 v[24:27], v202 offset:18432
	ds_read_b128 v[28:31], v202 offset:27648
	v_add_co_u32_e32 v34, vcc, 0x4000, v32
	v_mov_b64_e32 v[36:37], v[16:17]
	s_nop 0
	v_addc_co_u32_e32 v35, vcc, 0, v33, vcc
	s_waitcnt lgkmcnt(1)
	global_store_dwordx4 v[34:35], v[24:27], off nt
	s_nop 1
	v_add_co_u32_e32 v24, vcc, 0x6000, v32
	s_nop 1
	v_addc_co_u32_e32 v25, vcc, 0, v33, vcc
	s_waitcnt lgkmcnt(0)
	global_store_dwordx4 v[24:25], v[28:31], off nt
	s_waitcnt lgkmcnt(0)
	s_barrier
	v_mov_b64_e32 v[34:35], v[14:15]
	v_mov_b64_e32 v[30:31], v[10:11]
	v_mov_b64_e32 v[32:33], v[12:13]
	v_mov_b64_e32 v[28:29], v[8:9]
	s_cbranch_scc0 .LBB0_848

.LBB0_846:
	s_bfe_u32 s37, s36, 0x20007
	s_lshl_b32 s30, s37, 8
	s_or_b32 s30, s30, s54
	s_waitcnt lgkmcnt(0)
	s_barrier
	v_mov_b32_e32 v24, s30
	s_waitcnt lgkmcnt(0)
	global_load_dwordx4 v[116:119], v24, s[28:29]
	s_add_u32 s30, s26, s30
	s_addc_u32 s31, s27, 0
	global_load_dwordx4 v[120:123], v24, s[26:27]
	global_load_dwordx4 v[124:127], v24, s[26:27] offset:1024
	global_load_dwordx4 v[128:131], v198, s[30:31] offset:2048
	global_load_dwordx4 v[132:135], v198, s[30:31] offset:3072
	global_load_dwordx4 v[136:139], v199, s[30:31]
	global_load_dwordx4 v[140:143], v199, s[30:31] offset:1024
	global_load_dwordx4 v[144:147], v199, s[30:31] offset:2048
	global_load_dwordx4 v[148:151], v199, s[30:31] offset:3072
	global_load_dwordx4 v[152:155], v200, s[30:31]
	global_load_dwordx4 v[156:159], v200, s[30:31] offset:1024
	global_load_dwordx4 v[160:163], v200, s[30:31] offset:2048
	global_load_dwordx4 v[164:167], v200, s[30:31] offset:3072
	global_load_dwordx4 v[180:183], v24, s[26:27] offset:2048
	global_load_dwordx4 v[176:179], v24, s[26:27] offset:3072
	global_load_dwordx4 v[172:175], v198, s[30:31]
	global_load_dwordx4 v[168:171], v198, s[30:31] offset:1024
	global_load_dwordx4 v[48:51], v24, s[28:29] offset:16
	global_load_dwordx4 v[64:67], v24, s[26:27] offset:16
	global_load_dwordx4 v[56:59], v24, s[26:27] offset:1040
	ds_read_b128 v[44:47], v195
	global_load_dwordx4 v[60:63], v24, s[26:27] offset:2064
	global_load_dwordx4 v[52:55], v24, s[26:27] offset:3088
	s_add_u32 s26, s30, 0x1000
	s_addc_u32 s27, s31, 0
	s_add_u32 s28, s30, 0x1400
	s_addc_u32 s29, s31, 0
	ds_read_b128 v[24:27], v195 offset:9216
	global_load_dwordx4 v[72:75], v197, s[26:27] offset:16
	global_load_dwordx4 v[68:71], v197, s[28:29] offset:16
	s_add_u32 s26, s30, 0x1800
	s_addc_u32 s27, s31, 0
	s_add_u32 s28, s30, 0x1c00
	s_addc_u32 s29, s31, 0
	global_load_dwordx4 v[80:83], v197, s[26:27] offset:16
	global_load_dwordx4 v[76:79], v197, s[28:29] offset:16
	s_add_u32 s26, s30, 0x2000
	s_addc_u32 s27, s31, 0
	s_add_u32 s28, s30, 0x2400
	s_addc_u32 s29, s31, 0
	global_load_dwordx4 v[88:91], v197, s[26:27] offset:16
	global_load_dwordx4 v[84:87], v197, s[28:29] offset:16
	s_add_u32 s26, s30, 0x2800
	s_addc_u32 s27, s31, 0
	s_add_u32 s28, s30, 0x2c00
	s_addc_u32 s29, s31, 0
	global_load_dwordx4 v[96:99], v197, s[26:27] offset:16
	global_load_dwordx4 v[92:95], v197, s[28:29] offset:16
	s_add_u32 s26, s30, 0x3000
	s_addc_u32 s27, s31, 0
	s_add_u32 s28, s30, 0x3400
	s_addc_u32 s29, s31, 0
	global_load_dwordx4 v[104:107], v197, s[26:27] offset:16
	global_load_dwordx4 v[100:103], v197, s[28:29] offset:16
	s_add_u32 s26, s30, 0x3800
	s_addc_u32 s27, s31, 0
	s_add_u32 s28, s30, 0x3c00
	s_addc_u32 s29, s31, 0
	s_waitcnt lgkmcnt(1)
	v_lshlrev_b32_e32 v208, 16, v44
	v_and_b32_e32 v44, 0xffff0000, v44
	v_mul_f32_e32 v44, 0x3e000000, v44
	s_waitcnt vmcnt(28)
	v_mov_b32_e32 v108, v128
	s_waitcnt vmcnt(27)
	v_mov_b32_e32 v109, v132
	v_pk_mul_f32 v[108:109], v[38:39], v[108:109]
	s_waitcnt vmcnt(26)
	v_mov_b32_e32 v110, v136
	s_waitcnt vmcnt(25)
	v_mov_b32_e32 v111, v140
	v_pk_mul_f32 v[110:111], v[32:33], v[110:111]
	s_waitcnt vmcnt(24)
	v_mov_b32_e32 v112, v144
	s_waitcnt vmcnt(23)
	v_mov_b32_e32 v113, v148
	v_pk_mul_f32 v[112:113], v[34:35], v[112:113]
	s_waitcnt vmcnt(22)
	v_mov_b32_e32 v114, v152
	s_waitcnt vmcnt(21)
	v_mov_b32_e32 v115, v156
	v_pk_mul_f32 v[114:115], v[28:29], v[114:115]
	s_waitcnt vmcnt(20)
	v_mov_b32_e32 v206, v160
	v_fma_f32 v116, v40, v120, v116
	v_fmac_f32_e32 v116, v41, v124
	s_waitcnt vmcnt(18)
	v_fmac_f32_e32 v116, v42, v180
	s_waitcnt vmcnt(17)
	v_fmac_f32_e32 v116, v43, v176
	s_waitcnt vmcnt(16)
	v_fmac_f32_e32 v116, v36, v172
	s_waitcnt vmcnt(15)
	v_fmac_f32_e32 v116, v37, v168
	v_add_f32_e32 v108, v116, v108
	v_add_f32_e32 v108, v108, v109
	v_add_f32_e32 v108, v108, v110
	v_add_f32_e32 v108, v108, v111
	v_add_f32_e32 v108, v108, v112
	v_add_f32_e32 v108, v108, v113
	v_mov_b32_e32 v207, v164
	v_add_f32_e32 v108, v108, v114
	v_pk_mul_f32 v[206:207], v[30:31], v[206:207]
	v_add_f32_e32 v108, v108, v115
	v_add_f32_e32 v108, v108, v206
	v_add_f32_e32 v116, v108, v207
	v_mul_f32_e64 v108, |v116|, s2
	v_exp_f32_e32 v120, v108
	v_min_f32_e32 v116, 0, v116
	v_fma_f32 v117, v40, v121, v117
	v_fmac_f32_e32 v117, v41, v125
	v_add_f32_e32 v124, 1.0, v120
	v_add_f32_e32 v128, -1.0, v124
	v_sub_f32_e32 v132, v128, v124
	v_sub_f32_e32 v128, v120, v128
	v_add_f32_e32 v132, 1.0, v132
	v_add_f32_e32 v128, v128, v132
	v_frexp_mant_f32_e32 v132, v124
	v_cvt_f64_f32_e32 v[206:207], v124
	v_frexp_exp_i32_f64_e32 v136, v[206:207]
	v_cmp_gt_f32_e32 vcc, s4, v132
	v_fmac_f32_e32 v117, v42, v181
	v_fmac_f32_e32 v117, v43, v177
	v_subbrev_co_u32_e32 v132, vcc, 0, v136, vcc
	v_sub_u32_e32 v136, 0, v132
	v_ldexp_f32 v124, v124, v136
	v_ldexp_f32 v128, v128, v136
	v_add_f32_e32 v136, -1.0, v124
	v_add_f32_e32 v148, 1.0, v124
	v_add_f32_e32 v140, 1.0, v136
	v_add_f32_e32 v152, -1.0, v148
	v_sub_f32_e32 v140, v124, v140
	v_sub_f32_e32 v124, v124, v152
	v_add_f32_e32 v124, v128, v124
	v_add_f32_e32 v140, v128, v140
	v_add_f32_e32 v128, v148, v124
	v_rcp_f32_e32 v152, v128
	v_add_f32_e32 v144, v136, v140
	v_sub_f32_e32 v136, v144, v136
	v_sub_f32_e32 v136, v140, v136
	v_sub_f32_e32 v140, v128, v148
	v_sub_f32_e32 v124, v124, v140
	v_mul_f32_e32 v140, v144, v152
	v_mul_f32_e32 v148, v128, v140
	v_fma_f32 v156, v140, v128, -v148
	v_fmac_f32_e32 v156, v140, v124
	v_add_f32_e32 v160, v148, v156
	v_sub_f32_e32 v164, v144, v160
	v_sub_f32_e32 v144, v144, v164
	v_sub_f32_e32 v148, v160, v148
	v_sub_f32_e32 v144, v144, v160
	v_add_f32_e32 v136, v136, v144
	v_sub_f32_e32 v144, v148, v156
	v_add_f32_e32 v136, v144, v136
	v_add_f32_e32 v144, v164, v136
	v_mul_f32_e32 v148, v152, v144
	v_mul_f32_e32 v156, v128, v148
	v_fma_f32 v128, v148, v128, -v156
	v_fmac_f32_e32 v128, v148, v124
	v_sub_f32_e32 v124, v164, v144
	v_add_f32_e32 v124, v136, v124
	v_add_f32_e32 v136, v156, v128
	v_sub_f32_e32 v160, v144, v136
	v_sub_f32_e32 v144, v144, v160
	v_sub_f32_e32 v156, v136, v156
	v_sub_f32_e32 v136, v144, v136
	v_add_f32_e32 v124, v124, v136
	v_sub_f32_e32 v128, v156, v128
	v_cvt_f32_i32_e32 v132, v132
	v_add_f32_e32 v124, v128, v124
	v_add_f32_e32 v128, v140, v148
	v_add_f32_e32 v124, v160, v124
	v_sub_f32_e32 v136, v128, v140
	v_mul_f32_e32 v124, v152, v124
	v_sub_f32_e32 v136, v148, v136
	v_add_f32_e32 v124, v136, v124
	v_mul_f32_e32 v148, 0x3f317218, v132
	v_add_f32_e32 v136, v128, v124
	v_fma_f32 v152, v132, s5, -v148
	v_mul_f32_e32 v140, v136, v136
	v_fmac_f32_e32 v152, 0xb102e308, v132
	v_sub_f32_e32 v128, v136, v128
	v_fmamk_f32 v144, v140, 0x3e9b6dac, v201
	v_sub_f32_e32 v124, v124, v128
	v_add_f32_e32 v128, v148, v152
	v_fmaak_f32 v144, v140, v144, 0x3f2aaada
	v_sub_f32_e32 v132, v128, v148
	v_ldexp_f32 v148, v136, 1
	v_mul_f32_e32 v136, v136, v140
	v_mul_f32_e32 v136, v136, v144
	v_add_f32_e32 v140, v148, v136
	v_sub_f32_e32 v144, v140, v148
	v_ldexp_f32 v124, v124, 1
	v_sub_f32_e32 v136, v136, v144
	v_add_f32_e32 v124, v124, v136
	v_add_f32_e32 v136, v140, v124
	v_sub_f32_e32 v140, v136, v140
	v_sub_f32_e32 v124, v124, v140
	v_add_f32_e32 v140, v128, v136
	v_sub_f32_e32 v144, v140, v128
	v_sub_f32_e32 v148, v140, v144
	v_sub_f32_e32 v132, v152, v132
	v_sub_f32_e32 v128, v128, v148
	v_sub_f32_e32 v136, v136, v144
	v_add_f32_e32 v128, v136, v128
	v_add_f32_e32 v136, v132, v124
	v_sub_f32_e32 v144, v136, v132
	v_sub_f32_e32 v148, v136, v144
	v_sub_f32_e32 v132, v132, v148
	v_sub_f32_e32 v124, v124, v144
	v_add_f32_e32 v128, v136, v128
	v_add_f32_e32 v124, v124, v132
	v_add_f32_e32 v132, v140, v128
	v_sub_f32_e32 v136, v132, v140
	v_sub_f32_e32 v128, v128, v136
	v_add_f32_e32 v124, v124, v128
	v_add_f32_e32 v124, v132, v124
	v_cmp_neq_f32_e32 vcc, s33, v120
	v_fmac_f32_e32 v117, v36, v173
	v_mov_b32_e32 v132, v129
	v_cndmask_b32_e32 v124, v203, v124, vcc
	v_cmp_ngt_f32_e32 vcc, -1.0, v120
	v_fmac_f32_e32 v117, v37, v169
	v_mov_b32_e32 v140, v137
	v_cndmask_b32_e32 v124, v204, v124, vcc
	v_cmp_neq_f32_e32 vcc, -1.0, v120
	v_mov_b32_e32 v148, v145
	v_mov_b32_e32 v156, v153
	v_cndmask_b32_e32 v124, v205, v124, vcc
	v_cmp_lt_f32_e64 vcc, |v120|, s34
	v_mov_b32_e32 v164, v161
	v_mov_b32_e32 v128, 0
	v_cndmask_b32_e32 v120, v124, v120, vcc
	v_sub_f32_e32 v120, v116, v120
	v_mul_f32_e32 v124, 0x3d800000, v120
	v_fma_f32 v118, v40, v122, v118
	v_fmac_f32_e32 v118, v41, v126
	v_mov_b32_dpp v124, v124 row_shr:1 row_mask:0xf bank_mask:0xf bound_ctrl:1
	v_fmac_f32_e32 v124, 0x3d800000, v120
	v_fmac_f32_e32 v118, v42, v182
	v_fmac_f32_e32 v118, v43, v178
	v_add_f32_dpp v120, v124, v124 row_shr:2 row_mask:0xf bank_mask:0xf bound_ctrl:1
	v_mov_b32_e32 v124, 0
	v_fmac_f32_e32 v118, v36, v174
	v_add_f32_dpp v120, v120, v120 row_shr:4 row_mask:0xf bank_mask:0xf bound_ctrl:1
	v_fmac_f32_e32 v118, v37, v170
	v_fmac_f32_e32 v119, v40, v123
	v_add_f32_dpp v120, v120, v120 row_shr:8 row_mask:0xf bank_mask:0xf bound_ctrl:1
	v_fmac_f32_e32 v119, v41, v127
	v_fmac_f32_e32 v119, v42, v183
	v_mov_b32_dpp v124, v120 row_bcast:15 row_mask:0xa bank_mask:0xf
	v_add_f32_e32 v124, v120, v124
	v_pk_mul_f32 v[120:121], v[38:39], v[132:133]
	v_fmac_f32_e32 v119, v43, v179
	v_add_f32_e32 v117, v117, v120
	v_add_f32_e32 v117, v117, v121
	v_pk_mul_f32 v[120:121], v[32:33], v[140:141]
	v_mov_b32_dpp v128, v124 row_bcast:31 row_mask:0xc bank_mask:0xf
	v_add_f32_e32 v117, v117, v120
	v_add_f32_e32 v117, v117, v121
	v_pk_mul_f32 v[120:121], v[34:35], v[148:149]
	v_fmac_f32_e32 v119, v36, v175
	v_add_f32_e32 v117, v117, v120
	v_add_f32_e32 v117, v117, v121
	v_pk_mul_f32 v[120:121], v[28:29], v[156:157]
	v_fmac_f32_e32 v119, v37, v171
	v_add_f32_e32 v117, v117, v120
	v_add_f32_e32 v117, v117, v121
	v_pk_mul_f32 v[120:121], v[30:31], v[164:165]
	global_load_dwordx4 v[112:115], v197, s[26:27] offset:16
	global_load_dwordx4 v[108:111], v197, s[28:29] offset:16
	v_add_f32_e32 v117, v117, v120
	v_add_f32_e32 v120, v117, v121
	v_mul_f32_e64 v117, |v120|, s2
	v_exp_f32_e32 v125, v117
	v_add_f32_e32 v117, v124, v128
	v_min_f32_e32 v124, 0, v120
	s_waitcnt vmcnt(15)
	v_fma_f32 v48, v40, v64, v48
	v_add_f32_e32 v128, 1.0, v125
	v_add_f32_e32 v120, -1.0, v128
	v_sub_f32_e32 v121, v120, v128
	v_add_f32_e32 v121, 1.0, v121
	v_sub_f32_e32 v120, v125, v120
	v_add_f32_e32 v129, v120, v121
	v_frexp_mant_f32_e32 v132, v128
	v_cvt_f64_f32_e32 v[120:121], v128
	v_frexp_exp_i32_f64_e32 v120, v[120:121]
	v_cmp_gt_f32_e32 vcc, s4, v132
	s_waitcnt vmcnt(14)
	v_fmac_f32_e32 v48, v41, v56
	s_waitcnt vmcnt(13)
	v_fmac_f32_e32 v48, v42, v60
	v_subbrev_co_u32_e32 v120, vcc, 0, v120, vcc
	v_sub_u32_e32 v121, 0, v120
	v_ldexp_f32 v128, v128, v121
	v_ldexp_f32 v121, v129, v121
	v_add_f32_e32 v129, -1.0, v128
	v_add_f32_e32 v136, 1.0, v128
	v_add_f32_e32 v132, 1.0, v129
	v_add_f32_e32 v137, -1.0, v136
	v_sub_f32_e32 v132, v128, v132
	v_sub_f32_e32 v128, v128, v137
	v_add_f32_e32 v132, v121, v132
	v_add_f32_e32 v121, v121, v128
	v_add_f32_e32 v128, v136, v121
	v_rcp_f32_e32 v137, v128
	v_add_f32_e32 v133, v129, v132
	v_sub_f32_e32 v129, v133, v129
	v_sub_f32_e32 v129, v132, v129
	v_sub_f32_e32 v132, v128, v136
	v_sub_f32_e32 v121, v121, v132
	v_mul_f32_e32 v132, v133, v137
	v_mul_f32_e32 v136, v128, v132
	v_fma_f32 v140, v132, v128, -v136
	v_fmac_f32_e32 v140, v132, v121
	v_add_f32_e32 v141, v136, v140
	v_sub_f32_e32 v144, v133, v141
	v_sub_f32_e32 v133, v133, v144
	v_sub_f32_e32 v136, v141, v136
	v_sub_f32_e32 v133, v133, v141
	v_add_f32_e32 v129, v129, v133
	v_sub_f32_e32 v133, v136, v140
	v_add_f32_e32 v129, v133, v129
	v_add_f32_e32 v133, v144, v129
	v_mul_f32_e32 v136, v137, v133
	v_mul_f32_e32 v140, v128, v136
	v_fma_f32 v128, v136, v128, -v140
	v_fmac_f32_e32 v128, v136, v121
	v_sub_f32_e32 v121, v144, v133
	v_add_f32_e32 v121, v129, v121
	v_add_f32_e32 v129, v140, v128
	v_sub_f32_e32 v141, v133, v129
	v_sub_f32_e32 v133, v133, v141
	v_sub_f32_e32 v140, v129, v140
	v_sub_f32_e32 v129, v133, v129
	v_add_f32_e32 v121, v121, v129
	v_sub_f32_e32 v128, v140, v128
	v_cvt_f32_i32_e32 v120, v120
	v_add_f32_e32 v121, v128, v121
	v_add_f32_e32 v128, v132, v136
	v_add_f32_e32 v121, v141, v121
	v_sub_f32_e32 v129, v128, v132
	v_mul_f32_e32 v121, v137, v121
	v_sub_f32_e32 v129, v136, v129
	v_add_f32_e32 v121, v129, v121
	v_mul_f32_e32 v136, 0x3f317218, v120
	v_add_f32_e32 v129, v128, v121
	v_fma_f32 v137, v120, s5, -v136
	v_mul_f32_e32 v132, v129, v129
	v_fmac_f32_e32 v137, 0xb102e308, v120
	v_sub_f32_e32 v120, v129, v128
	v_fmamk_f32 v133, v132, 0x3e9b6dac, v201
	v_sub_f32_e32 v120, v121, v120
	v_add_f32_e32 v121, v136, v137
	v_fmaak_f32 v133, v132, v133, 0x3f2aaada
	v_sub_f32_e32 v128, v121, v136
	v_ldexp_f32 v136, v129, 1
	v_mul_f32_e32 v129, v129, v132
	v_mul_f32_e32 v129, v129, v133
	v_add_f32_e32 v132, v136, v129
	v_sub_f32_e32 v133, v132, v136
	v_ldexp_f32 v120, v120, 1
	v_sub_f32_e32 v129, v129, v133
	v_add_f32_e32 v120, v120, v129
	v_add_f32_e32 v129, v132, v120
	v_sub_f32_e32 v132, v129, v132
	v_sub_f32_e32 v120, v120, v132
	v_add_f32_e32 v132, v121, v129
	v_sub_f32_e32 v133, v132, v121
	v_sub_f32_e32 v136, v132, v133
	v_sub_f32_e32 v128, v137, v128
	v_sub_f32_e32 v121, v121, v136
	v_sub_f32_e32 v129, v129, v133
	v_add_f32_e32 v121, v129, v121
	v_add_f32_e32 v129, v128, v120
	v_sub_f32_e32 v133, v129, v128
	v_sub_f32_e32 v136, v129, v133
	v_sub_f32_e32 v128, v128, v136
	v_sub_f32_e32 v120, v120, v133
	v_add_f32_e32 v121, v129, v121
	v_add_f32_e32 v120, v120, v128
	v_add_f32_e32 v128, v132, v121
	v_sub_f32_e32 v129, v128, v132
	v_sub_f32_e32 v121, v121, v129
	v_add_f32_e32 v120, v120, v121
	v_add_f32_e32 v120, v128, v120
	v_cmp_neq_f32_e32 vcc, s33, v125
	s_waitcnt vmcnt(12)
	v_fmac_f32_e32 v48, v43, v52
	s_waitcnt vmcnt(11)
	v_fmac_f32_e32 v48, v36, v72
	v_cndmask_b32_e32 v120, v203, v120, vcc
	v_cmp_ngt_f32_e32 vcc, -1.0, v125
	s_waitcnt vmcnt(10)
	v_fmac_f32_e32 v48, v37, v68
	v_lshlrev_b32_e32 v60, 16, v46
	v_cndmask_b32_e32 v120, v204, v120, vcc
	v_cmp_neq_f32_e32 vcc, -1.0, v125
	v_fma_f32 v49, v40, v65, v49
	v_fmac_f32_e32 v49, v41, v57
	v_cndmask_b32_e32 v120, v205, v120, vcc
	v_cmp_lt_f32_e64 vcc, |v125|, s34
	v_fmac_f32_e32 v49, v42, v61
	v_fmac_f32_e32 v49, v43, v53
	v_cndmask_b32_e32 v120, v120, v125, vcc
	v_sub_f32_e32 v120, v124, v120
	v_mul_f32_e32 v121, 0x3d800000, v120
	v_mov_b32_e32 v125, 0
	v_fmac_f32_e32 v49, v36, v73
	v_mov_b32_dpp v121, v121 row_shr:1 row_mask:0xf bank_mask:0xf bound_ctrl:1
	v_fmac_f32_e32 v121, 0x3d800000, v120
	v_fmac_f32_e32 v49, v37, v69
	v_fma_f32 v50, v40, v66, v50
	v_add_f32_dpp v120, v121, v121 row_shr:2 row_mask:0xf bank_mask:0xf bound_ctrl:1
	v_mov_b32_e32 v121, 0
	v_fmac_f32_e32 v50, v41, v58
	v_add_f32_dpp v120, v120, v120 row_shr:4 row_mask:0xf bank_mask:0xf bound_ctrl:1
	v_fmac_f32_e32 v50, v42, v62
	v_fmac_f32_e32 v50, v43, v54
	v_add_f32_dpp v120, v120, v120 row_shr:8 row_mask:0xf bank_mask:0xf bound_ctrl:1
	v_fmac_f32_e32 v50, v36, v74
	v_fmac_f32_e32 v50, v37, v70
	v_mov_b32_dpp v121, v120 row_bcast:15 row_mask:0xa bank_mask:0xf
	v_add_f32_e32 v124, v120, v121
	v_mov_b32_e32 v120, v130
	v_mov_b32_e32 v121, v134
	v_pk_mul_f32 v[120:121], v[38:39], v[120:121]
	v_mov_b32_dpp v125, v124 row_bcast:31 row_mask:0xc bank_mask:0xf
	v_add_f32_e32 v118, v118, v120
	v_add_f32_e32 v118, v118, v121
	v_mov_b32_e32 v120, v138
	v_mov_b32_e32 v121, v142
	v_pk_mul_f32 v[120:121], v[32:33], v[120:121]
	v_mov_b32_e32 v142, v139
	v_add_f32_e32 v118, v118, v120
	v_add_f32_e32 v118, v118, v121
	v_mov_b32_e32 v120, v146
	v_mov_b32_e32 v121, v150
	v_pk_mul_f32 v[120:121], v[34:35], v[120:121]
	v_mov_b32_e32 v150, v147
	v_add_f32_e32 v118, v118, v120
	v_add_f32_e32 v118, v118, v121
	v_mov_b32_e32 v120, v154
	v_mov_b32_e32 v121, v158
	v_pk_mul_f32 v[120:121], v[28:29], v[120:121]
	v_mov_b32_e32 v158, v155
	v_add_f32_e32 v118, v118, v120
	v_add_f32_e32 v118, v118, v121
	v_mov_b32_e32 v120, v162
	v_mov_b32_e32 v121, v166
	v_pk_mul_f32 v[120:121], v[30:31], v[120:121]
	v_mov_b32_e32 v166, v163
	v_add_f32_e32 v118, v118, v120
	v_add_f32_e32 v120, v118, v121
	v_mul_f32_e64 v118, |v120|, s2
	v_exp_f32_e32 v122, v118
	v_add_f32_e32 v118, v124, v125
	v_min_f32_e32 v125, 0, v120
	v_lshlrev_b32_e32 v124, 16, v45
	v_add_f32_e32 v126, 1.0, v122
	v_add_f32_e32 v120, -1.0, v126
	v_sub_f32_e32 v121, v120, v126
	v_add_f32_e32 v121, 1.0, v121
	v_sub_f32_e32 v120, v122, v120
	v_add_f32_e32 v128, v120, v121
	v_frexp_mant_f32_e32 v129, v126
	v_cvt_f64_f32_e32 v[120:121], v126
	v_frexp_exp_i32_f64_e32 v120, v[120:121]
	v_cmp_gt_f32_e32 vcc, s4, v129
	v_fmac_f32_e32 v51, v40, v67
	v_fmac_f32_e32 v51, v41, v59
	v_subbrev_co_u32_e32 v120, vcc, 0, v120, vcc
	v_sub_u32_e32 v121, 0, v120
	v_ldexp_f32 v126, v126, v121
	v_ldexp_f32 v121, v128, v121
	v_add_f32_e32 v128, -1.0, v126
	v_add_f32_e32 v132, 1.0, v126
	v_add_f32_e32 v129, 1.0, v128
	v_add_f32_e32 v133, -1.0, v132
	v_sub_f32_e32 v129, v126, v129
	v_sub_f32_e32 v126, v126, v133
	v_add_f32_e32 v129, v121, v129
	v_add_f32_e32 v121, v121, v126
	v_add_f32_e32 v126, v132, v121
	v_rcp_f32_e32 v133, v126
	v_add_f32_e32 v130, v128, v129
	v_sub_f32_e32 v128, v130, v128
	v_sub_f32_e32 v128, v129, v128
	v_sub_f32_e32 v129, v126, v132
	v_sub_f32_e32 v121, v121, v129
	v_mul_f32_e32 v129, v130, v133
	v_mul_f32_e32 v132, v126, v129
	v_fma_f32 v134, v129, v126, -v132
	v_fmac_f32_e32 v134, v129, v121
	v_add_f32_e32 v136, v132, v134
	v_sub_f32_e32 v137, v130, v136
	v_sub_f32_e32 v130, v130, v137
	v_sub_f32_e32 v132, v136, v132
	v_sub_f32_e32 v130, v130, v136
	v_add_f32_e32 v128, v128, v130
	v_sub_f32_e32 v130, v132, v134
	v_add_f32_e32 v128, v130, v128
	v_add_f32_e32 v130, v137, v128
	v_mul_f32_e32 v132, v133, v130
	v_mul_f32_e32 v134, v126, v132
	v_fma_f32 v126, v132, v126, -v134
	v_fmac_f32_e32 v126, v132, v121
	v_sub_f32_e32 v121, v137, v130
	v_add_f32_e32 v121, v128, v121
	v_add_f32_e32 v128, v134, v126
	v_sub_f32_e32 v136, v130, v128
	v_sub_f32_e32 v130, v130, v136
	v_sub_f32_e32 v134, v128, v134
	v_sub_f32_e32 v128, v130, v128
	v_add_f32_e32 v121, v121, v128
	v_sub_f32_e32 v126, v134, v126
	v_cvt_f32_i32_e32 v120, v120
	v_add_f32_e32 v121, v126, v121
	v_add_f32_e32 v126, v129, v132
	v_add_f32_e32 v121, v136, v121
	v_sub_f32_e32 v128, v126, v129
	v_mul_f32_e32 v121, v133, v121
	v_sub_f32_e32 v128, v132, v128
	v_add_f32_e32 v121, v128, v121
	v_mul_f32_e32 v132, 0x3f317218, v120
	v_add_f32_e32 v128, v126, v121
	v_fma_f32 v133, v120, s5, -v132
	v_mul_f32_e32 v129, v128, v128
	v_fmac_f32_e32 v133, 0xb102e308, v120
	v_sub_f32_e32 v120, v128, v126
	v_fmamk_f32 v130, v129, 0x3e9b6dac, v201
	v_sub_f32_e32 v120, v121, v120
	v_add_f32_e32 v121, v132, v133
	v_fmaak_f32 v130, v129, v130, 0x3f2aaada
	v_sub_f32_e32 v126, v121, v132
	v_ldexp_f32 v132, v128, 1
	v_mul_f32_e32 v128, v128, v129
	v_mul_f32_e32 v128, v128, v130
	v_add_f32_e32 v129, v132, v128
	v_sub_f32_e32 v130, v129, v132
	v_ldexp_f32 v120, v120, 1
	v_sub_f32_e32 v128, v128, v130
	v_add_f32_e32 v120, v120, v128
	v_add_f32_e32 v128, v129, v120
	v_sub_f32_e32 v129, v128, v129
	v_sub_f32_e32 v120, v120, v129
	v_add_f32_e32 v129, v121, v128
	v_sub_f32_e32 v130, v129, v121
	v_sub_f32_e32 v132, v129, v130
	v_sub_f32_e32 v126, v133, v126
	v_sub_f32_e32 v121, v121, v132
	v_sub_f32_e32 v128, v128, v130
	v_add_f32_e32 v121, v128, v121
	v_add_f32_e32 v128, v126, v120
	v_sub_f32_e32 v130, v128, v126
	v_sub_f32_e32 v132, v128, v130
	v_sub_f32_e32 v126, v126, v132
	v_sub_f32_e32 v120, v120, v130
	v_add_f32_e32 v121, v128, v121
	v_add_f32_e32 v120, v120, v126
	v_add_f32_e32 v126, v129, v121
	v_sub_f32_e32 v128, v126, v129
	v_sub_f32_e32 v121, v121, v128
	v_add_f32_e32 v120, v120, v121
	v_add_f32_e32 v120, v126, v120
	v_cmp_neq_f32_e32 vcc, s33, v122
	v_mov_b32_e32 v134, v131
	v_fmac_f32_e32 v51, v42, v63
	v_cndmask_b32_e32 v120, v203, v120, vcc
	v_cmp_ngt_f32_e32 vcc, -1.0, v122
	v_fmac_f32_e32 v51, v43, v55
	v_fmac_f32_e32 v51, v36, v75
	v_cndmask_b32_e32 v120, v204, v120, vcc
	v_cmp_neq_f32_e32 vcc, -1.0, v122
	v_fmac_f32_e32 v51, v37, v71
	v_readlane_b32 s26, v117, 31
	v_cndmask_b32_e32 v120, v205, v120, vcc
	v_cmp_lt_f32_e64 vcc, |v122|, s34
	v_mul_f32_e32 v116, 0x3e000000, v208
	v_and_b32_e32 v45, 0xffff0000, v45
	v_cndmask_b32_e32 v120, v120, v122, vcc
	v_sub_f32_e32 v121, v125, v120
	v_mul_f32_e32 v122, 0x3d800000, v121
	v_mul_f32_e32 v120, 0x3e000000, v124
	v_mov_b32_e32 v124, 0
	v_mov_b32_dpp v122, v122 row_shr:1 row_mask:0xf bank_mask:0xf bound_ctrl:1
	v_fmac_f32_e32 v122, 0x3d800000, v121
	v_mul_f32_e32 v45, 0x3e000000, v45
	v_and_b32_e32 v46, 0xffff0000, v46
	v_add_f32_dpp v121, v122, v122 row_shr:2 row_mask:0xf bank_mask:0xf bound_ctrl:1
	v_mov_b32_e32 v122, 0
	v_mul_f32_e32 v46, 0x3e000000, v46
	v_add_f32_dpp v121, v121, v121 row_shr:4 row_mask:0xf bank_mask:0xf bound_ctrl:1
	v_lshlrev_b32_e32 v58, 16, v47
	s_lshl_b32 s27, s37, 7
	v_add_f32_dpp v121, v121, v121 row_shr:8 row_mask:0xf bank_mask:0xf bound_ctrl:1
	s_nop 1
	v_mov_b32_dpp v122, v121 row_bcast:15 row_mask:0xa bank_mask:0xf
	v_add_f32_e32 v121, v121, v122
	v_pk_mul_f32 v[122:123], v[38:39], v[134:135]
	s_nop 0
	v_add_f32_e32 v119, v119, v122
	v_add_f32_e32 v119, v119, v123
	v_pk_mul_f32 v[122:123], v[32:33], v[142:143]
	v_mov_b32_dpp v124, v121 row_bcast:31 row_mask:0xc bank_mask:0xf
	v_add_f32_e32 v119, v119, v122
	v_add_f32_e32 v119, v119, v123
	v_pk_mul_f32 v[122:123], v[34:35], v[150:151]
	s_nop 0
	v_add_f32_e32 v119, v119, v122
	v_add_f32_e32 v119, v119, v123
	v_pk_mul_f32 v[122:123], v[28:29], v[158:159]
	s_nop 0
	v_add_f32_e32 v119, v119, v122
	v_add_f32_e32 v119, v119, v123
	v_pk_mul_f32 v[122:123], v[30:31], v[166:167]
	s_nop 0
	v_add_f32_e32 v119, v119, v122
	v_add_f32_e32 v122, v119, v123
	v_mul_f32_e64 v119, |v122|, s2
	v_exp_f32_e32 v125, v119
	v_add_f32_e32 v119, v121, v124
	v_min_f32_e32 v121, 0, v122
	v_add_f32_e32 v124, 1.0, v125
	v_add_f32_e32 v122, -1.0, v124
	v_sub_f32_e32 v123, v122, v124
	v_add_f32_e32 v123, 1.0, v123
	v_sub_f32_e32 v122, v125, v122
	v_add_f32_e32 v126, v122, v123
	v_frexp_mant_f32_e32 v127, v124
	v_cvt_f64_f32_e32 v[122:123], v124
	v_frexp_exp_i32_f64_e32 v122, v[122:123]
	v_cmp_gt_f32_e32 vcc, s4, v127
	s_nop 1
	v_subbrev_co_u32_e32 v122, vcc, 0, v122, vcc
	v_sub_u32_e32 v123, 0, v122
	v_ldexp_f32 v124, v124, v123
	v_ldexp_f32 v123, v126, v123
	v_add_f32_e32 v126, -1.0, v124
	v_add_f32_e32 v129, 1.0, v124
	v_add_f32_e32 v127, 1.0, v126
	v_add_f32_e32 v130, -1.0, v129
	v_sub_f32_e32 v127, v124, v127
	v_sub_f32_e32 v124, v124, v130
	v_add_f32_e32 v127, v123, v127
	v_add_f32_e32 v123, v123, v124
	v_add_f32_e32 v124, v129, v123
	v_rcp_f32_e32 v130, v124
	v_add_f32_e32 v128, v126, v127
	v_sub_f32_e32 v126, v128, v126
	v_sub_f32_e32 v126, v127, v126
	v_sub_f32_e32 v127, v124, v129
	v_sub_f32_e32 v123, v123, v127
	v_mul_f32_e32 v127, v128, v130
	v_mul_f32_e32 v129, v124, v127
	v_fma_f32 v131, v127, v124, -v129
	v_fmac_f32_e32 v131, v127, v123
	v_add_f32_e32 v132, v129, v131
	v_sub_f32_e32 v133, v128, v132
	v_sub_f32_e32 v128, v128, v133
	v_sub_f32_e32 v129, v132, v129
	v_sub_f32_e32 v128, v128, v132
	v_add_f32_e32 v126, v126, v128
	v_sub_f32_e32 v128, v129, v131
	v_add_f32_e32 v126, v128, v126
	v_add_f32_e32 v128, v133, v126
	v_mul_f32_e32 v129, v130, v128
	v_mul_f32_e32 v131, v124, v129
	v_fma_f32 v124, v129, v124, -v131
	v_fmac_f32_e32 v124, v129, v123
	v_sub_f32_e32 v123, v133, v128
	v_add_f32_e32 v123, v126, v123
	v_add_f32_e32 v126, v131, v124
	v_sub_f32_e32 v132, v128, v126
	v_sub_f32_e32 v128, v128, v132
	v_sub_f32_e32 v131, v126, v131
	v_sub_f32_e32 v126, v128, v126
	v_add_f32_e32 v123, v123, v126
	v_sub_f32_e32 v124, v131, v124
	v_cvt_f32_i32_e32 v122, v122
	v_add_f32_e32 v123, v124, v123
	v_add_f32_e32 v124, v127, v129
	v_add_f32_e32 v123, v132, v123
	v_sub_f32_e32 v126, v124, v127
	v_mul_f32_e32 v123, v130, v123
	v_sub_f32_e32 v126, v129, v126
	v_add_f32_e32 v123, v126, v123
	v_mul_f32_e32 v129, 0x3f317218, v122
	v_add_f32_e32 v126, v124, v123
	v_fma_f32 v130, v122, s5, -v129
	v_mul_f32_e32 v127, v126, v126
	v_fmac_f32_e32 v130, 0xb102e308, v122
	v_sub_f32_e32 v122, v126, v124
	v_fmamk_f32 v128, v127, 0x3e9b6dac, v201
	v_sub_f32_e32 v122, v123, v122
	v_add_f32_e32 v123, v129, v130
	v_fmaak_f32 v128, v127, v128, 0x3f2aaada
	v_sub_f32_e32 v124, v123, v129
	v_ldexp_f32 v129, v126, 1
	v_mul_f32_e32 v126, v126, v127
	v_mul_f32_e32 v126, v126, v128
	v_add_f32_e32 v127, v129, v126
	v_sub_f32_e32 v128, v127, v129
	v_ldexp_f32 v122, v122, 1
	v_sub_f32_e32 v126, v126, v128
	v_add_f32_e32 v122, v122, v126
	v_add_f32_e32 v126, v127, v122
	v_sub_f32_e32 v127, v126, v127
	v_sub_f32_e32 v122, v122, v127
	v_add_f32_e32 v127, v123, v126
	v_sub_f32_e32 v128, v127, v123
	v_sub_f32_e32 v129, v127, v128
	v_sub_f32_e32 v124, v130, v124
	v_sub_f32_e32 v123, v123, v129
	v_sub_f32_e32 v126, v126, v128
	v_add_f32_e32 v123, v126, v123
	v_add_f32_e32 v126, v124, v122
	v_sub_f32_e32 v128, v126, v124
	v_sub_f32_e32 v129, v126, v128
	v_sub_f32_e32 v124, v124, v129
	v_sub_f32_e32 v122, v122, v128
	v_add_f32_e32 v123, v126, v123
	v_add_f32_e32 v122, v122, v124
	v_add_f32_e32 v124, v127, v123
	v_sub_f32_e32 v126, v124, v127
	v_sub_f32_e32 v123, v123, v126
	v_add_f32_e32 v122, v122, v123
	v_add_f32_e32 v122, v124, v122
	v_cmp_neq_f32_e32 vcc, s33, v125
	s_waitcnt vmcnt(8)
	v_mov_b32_e32 v123, v76
	v_mov_b32_e32 v124, 0
	v_cndmask_b32_e32 v122, v203, v122, vcc
	v_cmp_ngt_f32_e32 vcc, -1.0, v125
	s_nop 1
	v_cndmask_b32_e32 v122, v204, v122, vcc
	v_cmp_neq_f32_e32 vcc, -1.0, v125
	s_nop 1
	v_cndmask_b32_e32 v122, v205, v122, vcc
	v_cmp_lt_f32_e64 vcc, |v125|, s34
	s_nop 1
	v_cndmask_b32_e32 v122, v122, v125, vcc
	v_sub_f32_e32 v121, v121, v122
	v_mul_f32_e32 v122, 0x3d800000, v121
	s_nop 1
	v_mov_b32_dpp v122, v122 row_shr:1 row_mask:0xf bank_mask:0xf bound_ctrl:1
	v_fmac_f32_e32 v122, 0x3d800000, v121
	s_nop 1
	v_add_f32_dpp v121, v122, v122 row_shr:2 row_mask:0xf bank_mask:0xf bound_ctrl:1
	v_mov_b32_e32 v122, 0
	s_nop 0
	v_add_f32_dpp v121, v121, v121 row_shr:4 row_mask:0xf bank_mask:0xf bound_ctrl:1
	s_nop 1
	v_add_f32_dpp v121, v121, v121 row_shr:8 row_mask:0xf bank_mask:0xf bound_ctrl:1
	s_nop 1
	v_mov_b32_dpp v122, v121 row_bcast:15 row_mask:0xa bank_mask:0xf
	v_add_f32_e32 v121, v121, v122
	v_mov_b32_e32 v122, v80
	v_pk_mul_f32 v[122:123], v[38:39], v[122:123]
	v_mov_b32_dpp v124, v121 row_bcast:31 row_mask:0xc bank_mask:0xf
	v_add_f32_e32 v48, v48, v122
	v_add_f32_e32 v48, v48, v123
	s_waitcnt vmcnt(7)
	v_mov_b32_e32 v122, v88
	s_waitcnt vmcnt(6)
	v_mov_b32_e32 v123, v84
	v_pk_mul_f32 v[122:123], v[32:33], v[122:123]
	s_nop 0
	v_add_f32_e32 v48, v48, v122
	v_add_f32_e32 v48, v48, v123
	s_waitcnt vmcnt(5)
	v_mov_b32_e32 v122, v96
	s_waitcnt vmcnt(4)
	v_mov_b32_e32 v123, v92
	v_pk_mul_f32 v[122:123], v[34:35], v[122:123]
	s_nop 0
	v_add_f32_e32 v48, v48, v122
	v_add_f32_e32 v48, v48, v123
	s_waitcnt vmcnt(3)
	v_mov_b32_e32 v122, v104
	s_waitcnt vmcnt(2)
	v_mov_b32_e32 v123, v100
	v_pk_mul_f32 v[122:123], v[28:29], v[122:123]
	s_nop 0
	v_add_f32_e32 v48, v48, v122
	v_add_f32_e32 v48, v48, v123
	s_waitcnt vmcnt(1)
	v_mov_b32_e32 v122, v112
	s_waitcnt vmcnt(0)
	v_mov_b32_e32 v123, v108
	v_pk_mul_f32 v[122:123], v[30:31], v[122:123]
	v_mov_b32_e32 v108, v113
	v_add_f32_e32 v48, v48, v122
	v_add_f32_e32 v52, v48, v123
	v_mul_f32_e64 v48, |v52|, s2
	v_exp_f32_e32 v56, v48
	v_min_f32_e32 v52, 0, v52
	v_add_f32_e32 v48, v121, v124
	v_add_f32_e32 v64, 1.0, v56
	v_add_f32_e32 v68, -1.0, v64
	v_sub_f32_e32 v72, v68, v64
	v_add_f32_e32 v72, 1.0, v72
	v_sub_f32_e32 v68, v56, v68
	v_add_f32_e32 v68, v68, v72
	v_frexp_mant_f32_e32 v72, v64
	v_cvt_f64_f32_e32 v[122:123], v64
	v_frexp_exp_i32_f64_e32 v76, v[122:123]
	v_cmp_gt_f32_e32 vcc, s4, v72
	s_nop 1
	v_subbrev_co_u32_e32 v72, vcc, 0, v76, vcc
	v_sub_u32_e32 v76, 0, v72
	v_ldexp_f32 v64, v64, v76
	v_ldexp_f32 v68, v68, v76
	v_add_f32_e32 v76, -1.0, v64
	v_add_f32_e32 v88, 1.0, v64
	v_add_f32_e32 v80, 1.0, v76
	v_add_f32_e32 v92, -1.0, v88
	v_sub_f32_e32 v80, v64, v80
	v_sub_f32_e32 v64, v64, v92
	v_add_f32_e32 v64, v68, v64
	v_add_f32_e32 v80, v68, v80
	v_add_f32_e32 v68, v88, v64
	v_rcp_f32_e32 v92, v68
	v_add_f32_e32 v84, v76, v80
	v_sub_f32_e32 v76, v84, v76
	v_sub_f32_e32 v76, v80, v76
	v_sub_f32_e32 v80, v68, v88
	v_sub_f32_e32 v64, v64, v80
	v_mul_f32_e32 v80, v84, v92
	v_mul_f32_e32 v88, v68, v80
	v_fma_f32 v96, v80, v68, -v88
	v_fmac_f32_e32 v96, v80, v64
	v_add_f32_e32 v100, v88, v96
	v_sub_f32_e32 v104, v84, v100
	v_sub_f32_e32 v84, v84, v104
	v_sub_f32_e32 v88, v100, v88
	v_sub_f32_e32 v84, v84, v100
	v_add_f32_e32 v76, v76, v84
	v_sub_f32_e32 v84, v88, v96
	v_add_f32_e32 v76, v84, v76
	v_add_f32_e32 v84, v104, v76
	v_mul_f32_e32 v88, v92, v84
	v_mul_f32_e32 v96, v68, v88
	v_fma_f32 v68, v88, v68, -v96
	v_fmac_f32_e32 v68, v88, v64
	v_sub_f32_e32 v64, v104, v84
	v_add_f32_e32 v64, v76, v64
	v_add_f32_e32 v76, v96, v68
	v_sub_f32_e32 v100, v84, v76
	v_sub_f32_e32 v84, v84, v100
	v_sub_f32_e32 v96, v76, v96
	v_sub_f32_e32 v76, v84, v76
	v_add_f32_e32 v64, v64, v76
	v_sub_f32_e32 v68, v96, v68
	v_cvt_f32_i32_e32 v72, v72
	v_add_f32_e32 v64, v68, v64
	v_add_f32_e32 v68, v80, v88
	v_add_f32_e32 v64, v100, v64
	v_sub_f32_e32 v76, v68, v80
	v_mul_f32_e32 v64, v92, v64
	v_sub_f32_e32 v76, v88, v76
	v_add_f32_e32 v64, v76, v64
	v_mul_f32_e32 v88, 0x3f317218, v72
	v_add_f32_e32 v76, v68, v64
	v_fma_f32 v92, v72, s5, -v88
	v_mul_f32_e32 v80, v76, v76
	v_fmac_f32_e32 v92, 0xb102e308, v72
	v_sub_f32_e32 v68, v76, v68
	v_fmamk_f32 v84, v80, 0x3e9b6dac, v201
	v_sub_f32_e32 v64, v64, v68
	v_add_f32_e32 v68, v88, v92
	v_fmaak_f32 v84, v80, v84, 0x3f2aaada
	v_sub_f32_e32 v72, v68, v88
	v_ldexp_f32 v88, v76, 1
	v_mul_f32_e32 v76, v76, v80
	v_mul_f32_e32 v76, v76, v84
	v_add_f32_e32 v80, v88, v76
	v_sub_f32_e32 v84, v80, v88
	v_ldexp_f32 v64, v64, 1
	v_sub_f32_e32 v76, v76, v84
	v_add_f32_e32 v64, v64, v76
	v_add_f32_e32 v76, v80, v64
	v_sub_f32_e32 v80, v76, v80
	v_sub_f32_e32 v64, v64, v80
	v_add_f32_e32 v80, v68, v76
	v_sub_f32_e32 v84, v80, v68
	v_sub_f32_e32 v88, v80, v84
	v_sub_f32_e32 v72, v92, v72
	v_sub_f32_e32 v68, v68, v88
	v_sub_f32_e32 v76, v76, v84
	v_add_f32_e32 v68, v76, v68
	v_add_f32_e32 v76, v72, v64
	v_sub_f32_e32 v84, v76, v72
	v_sub_f32_e32 v88, v76, v84
	v_sub_f32_e32 v72, v72, v88
	v_sub_f32_e32 v64, v64, v84
	v_add_f32_e32 v68, v76, v68
	v_add_f32_e32 v64, v64, v72
	v_add_f32_e32 v72, v80, v68
	v_sub_f32_e32 v76, v72, v80
	v_sub_f32_e32 v68, v68, v76
	v_add_f32_e32 v64, v64, v68
	v_add_f32_e32 v64, v72, v64
	v_cmp_neq_f32_e32 vcc, s33, v56
	v_mov_b32_e32 v76, v81
	v_mov_b32_e32 v84, v89
	v_cndmask_b32_e32 v64, v203, v64, vcc
	v_cmp_ngt_f32_e32 vcc, -1.0, v56
	v_mov_b32_e32 v92, v97
	v_mov_b32_e32 v100, v105
	v_cndmask_b32_e32 v64, v204, v64, vcc
	v_cmp_neq_f32_e32 vcc, -1.0, v56
	s_nop 1
	v_cndmask_b32_e32 v64, v205, v64, vcc
	v_cmp_lt_f32_e64 vcc, |v56|, s34
	s_nop 1
	v_cndmask_b32_e32 v56, v64, v56, vcc
	v_sub_f32_e32 v56, v52, v56
	v_mul_f32_e32 v64, 0x3d800000, v56
	v_mul_f32_e32 v52, 0x3e000000, v60
	s_nop 0
	v_mov_b32_dpp v60, v64 row_shr:1 row_mask:0xf bank_mask:0xf bound_ctrl:1
	v_fmac_f32_e32 v60, 0x3d800000, v56
	v_mov_b32_e32 v64, 0
	s_nop 0
	v_add_f32_dpp v56, v60, v60 row_shr:2 row_mask:0xf bank_mask:0xf bound_ctrl:1
	v_mov_b32_e32 v60, 0
	s_nop 0
	v_add_f32_dpp v56, v56, v56 row_shr:4 row_mask:0xf bank_mask:0xf bound_ctrl:1
	s_nop 1
	v_add_f32_dpp v56, v56, v56 row_shr:8 row_mask:0xf bank_mask:0xf bound_ctrl:1
	s_nop 1
	v_mov_b32_dpp v60, v56 row_bcast:15 row_mask:0xa bank_mask:0xf
	v_add_f32_e32 v60, v56, v60
	v_pk_mul_f32 v[56:57], v[38:39], v[76:77]
	s_nop 0
	v_add_f32_e32 v49, v49, v56
	v_add_f32_e32 v49, v49, v57
	v_pk_mul_f32 v[56:57], v[32:33], v[84:85]
	v_mov_b32_dpp v64, v60 row_bcast:31 row_mask:0xc bank_mask:0xf
	v_add_f32_e32 v49, v49, v56
	v_add_f32_e32 v49, v49, v57
	v_pk_mul_f32 v[56:57], v[34:35], v[92:93]
	s_nop 0
	v_add_f32_e32 v49, v49, v56
	v_add_f32_e32 v49, v49, v57
	v_pk_mul_f32 v[56:57], v[28:29], v[100:101]
	s_nop 0
	v_add_f32_e32 v49, v49, v56
	v_add_f32_e32 v49, v49, v57
	v_pk_mul_f32 v[56:57], v[30:31], v[108:109]
	s_nop 0
	v_add_f32_e32 v49, v49, v56
	v_add_f32_e32 v53, v49, v57
	v_mul_f32_e64 v49, |v53|, s2
	v_exp_f32_e32 v61, v49
	v_add_f32_e32 v49, v60, v64
	v_min_f32_e32 v53, 0, v53
	v_add_f32_e32 v60, 1.0, v61
	v_add_f32_e32 v56, -1.0, v60
	v_sub_f32_e32 v57, v56, v60
	v_add_f32_e32 v57, 1.0, v57
	v_sub_f32_e32 v56, v61, v56
	v_add_f32_e32 v64, v56, v57
	v_frexp_mant_f32_e32 v65, v60
	v_cvt_f64_f32_e32 v[56:57], v60
	v_frexp_exp_i32_f64_e32 v56, v[56:57]
	v_cmp_gt_f32_e32 vcc, s4, v65
	s_nop 1
	v_subbrev_co_u32_e32 v56, vcc, 0, v56, vcc
	v_sub_u32_e32 v57, 0, v56
	v_ldexp_f32 v60, v60, v57
	v_ldexp_f32 v57, v64, v57
	v_add_f32_e32 v64, -1.0, v60
	v_add_f32_e32 v69, 1.0, v60
	v_add_f32_e32 v65, 1.0, v64
	v_add_f32_e32 v72, -1.0, v69
	v_sub_f32_e32 v65, v60, v65
	v_sub_f32_e32 v60, v60, v72
	v_add_f32_e32 v65, v57, v65
	v_add_f32_e32 v57, v57, v60
	v_add_f32_e32 v60, v69, v57
	v_rcp_f32_e32 v72, v60
	v_add_f32_e32 v68, v64, v65
	v_sub_f32_e32 v64, v68, v64
	v_sub_f32_e32 v64, v65, v64
	v_sub_f32_e32 v65, v60, v69
	v_sub_f32_e32 v57, v57, v65
	v_mul_f32_e32 v65, v68, v72
	v_mul_f32_e32 v69, v60, v65
	v_fma_f32 v73, v65, v60, -v69
	v_fmac_f32_e32 v73, v65, v57
	v_add_f32_e32 v76, v69, v73
	v_sub_f32_e32 v77, v68, v76
	v_sub_f32_e32 v68, v68, v77
	v_sub_f32_e32 v69, v76, v69
	v_sub_f32_e32 v68, v68, v76
	v_add_f32_e32 v64, v64, v68
	v_sub_f32_e32 v68, v69, v73
	v_add_f32_e32 v64, v68, v64
	v_add_f32_e32 v68, v77, v64
	v_mul_f32_e32 v69, v72, v68
	v_mul_f32_e32 v73, v60, v69
	v_fma_f32 v60, v69, v60, -v73
	v_fmac_f32_e32 v60, v69, v57
	v_sub_f32_e32 v57, v77, v68
	v_add_f32_e32 v57, v64, v57
	v_add_f32_e32 v64, v73, v60
	v_sub_f32_e32 v76, v68, v64
	v_sub_f32_e32 v68, v68, v76
	v_sub_f32_e32 v73, v64, v73
	v_sub_f32_e32 v64, v68, v64
	v_add_f32_e32 v57, v57, v64
	v_sub_f32_e32 v60, v73, v60
	v_cvt_f32_i32_e32 v56, v56
	v_add_f32_e32 v57, v60, v57
	v_add_f32_e32 v60, v65, v69
	v_add_f32_e32 v57, v76, v57
	v_sub_f32_e32 v64, v60, v65
	v_mul_f32_e32 v57, v72, v57
	v_sub_f32_e32 v64, v69, v64
	v_add_f32_e32 v57, v64, v57
	v_mul_f32_e32 v69, 0x3f317218, v56
	v_add_f32_e32 v64, v60, v57
	v_fma_f32 v72, v56, s5, -v69
	v_mul_f32_e32 v65, v64, v64
	v_fmac_f32_e32 v72, 0xb102e308, v56
	v_sub_f32_e32 v56, v64, v60
	v_fmamk_f32 v68, v65, 0x3e9b6dac, v201
	v_sub_f32_e32 v56, v57, v56
	v_add_f32_e32 v57, v69, v72
	v_fmaak_f32 v68, v65, v68, 0x3f2aaada
	v_sub_f32_e32 v60, v57, v69
	v_ldexp_f32 v69, v64, 1
	v_mul_f32_e32 v64, v64, v65
	v_mul_f32_e32 v64, v64, v68
	v_add_f32_e32 v65, v69, v64
	v_sub_f32_e32 v68, v65, v69
	v_ldexp_f32 v56, v56, 1
	v_sub_f32_e32 v64, v64, v68
	v_add_f32_e32 v56, v56, v64
	v_add_f32_e32 v64, v65, v56
	v_sub_f32_e32 v65, v64, v65
	v_sub_f32_e32 v56, v56, v65
	v_add_f32_e32 v65, v57, v64
	v_sub_f32_e32 v68, v65, v57
	v_sub_f32_e32 v69, v65, v68
	v_sub_f32_e32 v60, v72, v60
	v_sub_f32_e32 v57, v57, v69
	v_sub_f32_e32 v64, v64, v68
	v_add_f32_e32 v57, v64, v57
	v_add_f32_e32 v64, v60, v56
	v_sub_f32_e32 v68, v64, v60
	v_sub_f32_e32 v69, v64, v68
	v_sub_f32_e32 v60, v60, v69
	v_sub_f32_e32 v56, v56, v68
	v_add_f32_e32 v57, v64, v57
	v_add_f32_e32 v56, v56, v60
	v_add_f32_e32 v60, v65, v57
	v_sub_f32_e32 v64, v60, v65
	v_sub_f32_e32 v57, v57, v64
	v_add_f32_e32 v56, v56, v57
	v_add_f32_e32 v56, v60, v56
	v_cmp_neq_f32_e32 vcc, s33, v61
	v_mov_b32_e32 v57, v78
	v_mov_b32_e32 v60, 0
	v_cndmask_b32_e32 v56, v203, v56, vcc
	v_cmp_ngt_f32_e32 vcc, -1.0, v61
	v_mov_b32_e32 v78, v83
	v_pk_mul_f32 v[36:37], v[38:39], v[78:79]
	v_cndmask_b32_e32 v56, v204, v56, vcc
	v_cmp_neq_f32_e32 vcc, -1.0, v61
	v_add_f32_e32 v36, v51, v36
	v_add_f32_e32 v36, v36, v37
	v_cndmask_b32_e32 v56, v205, v56, vcc
	v_cmp_lt_f32_e64 vcc, |v61|, s34
	s_nop 1
	v_cndmask_b32_e32 v56, v56, v61, vcc
	v_sub_f32_e32 v53, v53, v56
	v_mul_f32_e32 v56, 0x3d800000, v53
	s_nop 1
	v_mov_b32_dpp v56, v56 row_shr:1 row_mask:0xf bank_mask:0xf bound_ctrl:1
	v_fmac_f32_e32 v56, 0x3d800000, v53
	s_nop 1
	v_add_f32_dpp v53, v56, v56 row_shr:2 row_mask:0xf bank_mask:0xf bound_ctrl:1
	v_mov_b32_e32 v56, 0
	s_nop 0
	v_add_f32_dpp v53, v53, v53 row_shr:4 row_mask:0xf bank_mask:0xf bound_ctrl:1
	s_nop 1
	v_add_f32_dpp v53, v53, v53 row_shr:8 row_mask:0xf bank_mask:0xf bound_ctrl:1
	s_nop 1
	v_mov_b32_dpp v56, v53 row_bcast:15 row_mask:0xa bank_mask:0xf
	v_add_f32_e32 v53, v53, v56
	v_mov_b32_e32 v56, v82
	v_pk_mul_f32 v[56:57], v[38:39], v[56:57]
	v_mov_b32_dpp v60, v53 row_bcast:31 row_mask:0xc bank_mask:0xf
	v_add_f32_e32 v50, v50, v56
	v_add_f32_e32 v50, v50, v57
	v_mov_b32_e32 v56, v90
	v_mov_b32_e32 v57, v86
	v_pk_mul_f32 v[56:57], v[32:33], v[56:57]
	v_add_f32_e32 v53, v53, v60
	v_add_f32_e32 v50, v50, v56
	v_add_f32_e32 v50, v50, v57
	v_mov_b32_e32 v56, v98
	v_mov_b32_e32 v57, v94
	v_pk_mul_f32 v[56:57], v[34:35], v[56:57]
	v_mov_b32_e32 v86, v91
	v_add_f32_e32 v50, v50, v56
	v_add_f32_e32 v50, v50, v57
	v_mov_b32_e32 v56, v106
	v_mov_b32_e32 v57, v102
	v_pk_mul_f32 v[56:57], v[28:29], v[56:57]
	v_pk_mul_f32 v[32:33], v[32:33], v[86:87]
	v_add_f32_e32 v50, v50, v56
	v_add_f32_e32 v50, v50, v57
	v_mov_b32_e32 v56, v114
	v_mov_b32_e32 v57, v110
	v_pk_mul_f32 v[56:57], v[30:31], v[56:57]
	v_add_f32_e32 v32, v36, v32
	v_add_f32_e32 v50, v50, v56
	v_add_f32_e32 v50, v50, v57
	v_mul_f32_e64 v54, |v50|, s2
	v_exp_f32_e32 v54, v54
	v_mov_b32_e32 v94, v99
	v_add_f32_e32 v36, v32, v33
	v_pk_mul_f32 v[32:33], v[34:35], v[94:95]
	v_add_f32_e32 v60, 1.0, v54
	v_add_f32_e32 v56, -1.0, v60
	v_sub_f32_e32 v57, v56, v60
	v_add_f32_e32 v57, 1.0, v57
	v_sub_f32_e32 v56, v54, v56
	v_add_f32_e32 v61, v56, v57
	v_frexp_mant_f32_e32 v62, v60
	v_cvt_f64_f32_e32 v[56:57], v60
	v_frexp_exp_i32_f64_e32 v56, v[56:57]
	v_cmp_gt_f32_e32 vcc, s4, v62
	v_add_f32_e32 v32, v36, v32
	v_mov_b32_e32 v102, v107
	v_subbrev_co_u32_e32 v56, vcc, 0, v56, vcc
	v_sub_u32_e32 v57, 0, v56
	v_ldexp_f32 v60, v60, v57
	v_ldexp_f32 v57, v61, v57
	v_add_f32_e32 v61, -1.0, v60
	v_add_f32_e32 v65, 1.0, v60
	v_add_f32_e32 v62, 1.0, v61
	v_add_f32_e32 v66, -1.0, v65
	v_sub_f32_e32 v62, v60, v62
	v_sub_f32_e32 v60, v60, v66
	v_add_f32_e32 v62, v57, v62
	v_add_f32_e32 v57, v57, v60
	v_add_f32_e32 v60, v65, v57
	v_rcp_f32_e32 v66, v60
	v_add_f32_e32 v64, v61, v62
	v_sub_f32_e32 v61, v64, v61
	v_sub_f32_e32 v61, v62, v61
	v_sub_f32_e32 v62, v60, v65
	v_sub_f32_e32 v57, v57, v62
	v_mul_f32_e32 v62, v64, v66
	v_mul_f32_e32 v65, v60, v62
	v_fma_f32 v68, v62, v60, -v65
	v_fmac_f32_e32 v68, v62, v57
	v_add_f32_e32 v69, v65, v68
	v_sub_f32_e32 v70, v64, v69
	v_sub_f32_e32 v64, v64, v70
	v_sub_f32_e32 v65, v69, v65
	v_sub_f32_e32 v64, v64, v69
	v_add_f32_e32 v61, v61, v64
	v_sub_f32_e32 v64, v65, v68
	v_add_f32_e32 v61, v64, v61
	v_add_f32_e32 v64, v70, v61
	v_mul_f32_e32 v65, v66, v64
	v_mul_f32_e32 v68, v60, v65
	v_fma_f32 v60, v65, v60, -v68
	v_fmac_f32_e32 v60, v65, v57
	v_sub_f32_e32 v57, v70, v64
	v_add_f32_e32 v57, v61, v57
	v_add_f32_e32 v61, v68, v60
	v_sub_f32_e32 v69, v64, v61
	v_sub_f32_e32 v64, v64, v69
	v_sub_f32_e32 v68, v61, v68
	v_sub_f32_e32 v61, v64, v61
	v_add_f32_e32 v57, v57, v61
	v_sub_f32_e32 v60, v68, v60
	v_cvt_f32_i32_e32 v56, v56
	v_add_f32_e32 v57, v60, v57
	v_add_f32_e32 v60, v62, v65
	v_add_f32_e32 v57, v69, v57
	v_sub_f32_e32 v61, v60, v62
	v_mul_f32_e32 v57, v66, v57
	v_sub_f32_e32 v61, v65, v61
	v_add_f32_e32 v57, v61, v57
	v_mul_f32_e32 v65, 0x3f317218, v56
	v_add_f32_e32 v61, v60, v57
	v_fma_f32 v66, v56, s5, -v65
	v_mul_f32_e32 v62, v61, v61
	v_fmac_f32_e32 v66, 0xb102e308, v56
	v_sub_f32_e32 v56, v61, v60
	v_fmamk_f32 v64, v62, 0x3e9b6dac, v201
	v_sub_f32_e32 v56, v57, v56
	v_add_f32_e32 v57, v65, v66
	v_fmaak_f32 v64, v62, v64, 0x3f2aaada
	v_sub_f32_e32 v60, v57, v65
	v_ldexp_f32 v65, v61, 1
	v_mul_f32_e32 v61, v61, v62
	v_mul_f32_e32 v61, v61, v64
	v_add_f32_e32 v62, v65, v61
	v_sub_f32_e32 v64, v62, v65
	v_ldexp_f32 v56, v56, 1
	v_sub_f32_e32 v61, v61, v64
	v_add_f32_e32 v56, v56, v61
	v_add_f32_e32 v61, v62, v56
	v_sub_f32_e32 v62, v61, v62
	v_sub_f32_e32 v56, v56, v62
	v_add_f32_e32 v62, v57, v61
	v_sub_f32_e32 v64, v62, v57
	v_add_f32_e32 v32, v32, v33
	v_pk_mul_f32 v[28:29], v[28:29], v[102:103]
	v_sub_f32_e32 v65, v62, v64
	v_add_f32_e32 v28, v32, v28
	v_mov_b32_e32 v110, v115
	v_sub_f32_e32 v60, v66, v60
	v_sub_f32_e32 v57, v57, v65
	v_sub_f32_e32 v61, v61, v64
	v_add_f32_e32 v32, v28, v29
	v_pk_mul_f32 v[28:29], v[30:31], v[110:111]
	v_add_f32_e32 v57, v61, v57
	v_add_f32_e32 v61, v60, v56
	v_add_f32_e32 v28, v32, v28
	v_sub_f32_e32 v64, v61, v60
	v_add_f32_e32 v28, v28, v29
	v_sub_f32_e32 v65, v61, v64
	v_mul_f32_e64 v29, |v28|, s2
	v_sub_f32_e32 v60, v60, v65
	v_sub_f32_e32 v56, v56, v64
	v_add_f32_e32 v57, v61, v57
	v_exp_f32_e32 v30, v29
	v_add_f32_e32 v56, v56, v60
	v_add_f32_e32 v60, v62, v57
	v_sub_f32_e32 v61, v60, v62
	v_sub_f32_e32 v57, v57, v61
	v_add_f32_e32 v56, v56, v57
	v_add_f32_e32 v33, 1.0, v30
	v_add_f32_e32 v56, v60, v56
	v_cmp_neq_f32_e32 vcc, s33, v54
	v_min_f32_e32 v32, 0, v28
	v_add_f32_e32 v28, -1.0, v33
	v_cndmask_b32_e32 v56, v203, v56, vcc
	v_cmp_ngt_f32_e32 vcc, -1.0, v54
	v_sub_f32_e32 v29, v28, v33
	v_add_f32_e32 v29, 1.0, v29
	v_cndmask_b32_e32 v56, v204, v56, vcc
	v_cmp_neq_f32_e32 vcc, -1.0, v54
	v_sub_f32_e32 v28, v30, v28
	v_add_f32_e32 v34, v28, v29
	v_cndmask_b32_e32 v56, v205, v56, vcc
	v_cmp_lt_f32_e64 vcc, |v54|, s34
	v_frexp_mant_f32_e32 v35, v33
	v_cvt_f64_f32_e32 v[28:29], v33
	v_cndmask_b32_e32 v54, v56, v54, vcc
	v_frexp_exp_i32_f64_e32 v28, v[28:29]
	v_cmp_gt_f32_e32 vcc, s4, v35
	v_and_b32_e32 v31, 0xffff0000, v47
	v_mul_f32_e32 v55, 0x3e000000, v31
	v_subbrev_co_u32_e32 v28, vcc, 0, v28, vcc
	v_sub_u32_e32 v29, 0, v28
	v_ldexp_f32 v33, v33, v29
	v_ldexp_f32 v29, v34, v29
	v_add_f32_e32 v34, -1.0, v33
	v_add_f32_e32 v37, 1.0, v33
	v_add_f32_e32 v35, 1.0, v34
	v_add_f32_e32 v38, -1.0, v37
	v_sub_f32_e32 v35, v33, v35
	v_sub_f32_e32 v33, v33, v38
	v_add_f32_e32 v35, v29, v35
	v_add_f32_e32 v29, v29, v33
	v_add_f32_e32 v33, v37, v29
	v_rcp_f32_e32 v38, v33
	v_add_f32_e32 v36, v34, v35
	v_sub_f32_e32 v34, v36, v34
	v_sub_f32_e32 v34, v35, v34
	v_sub_f32_e32 v35, v33, v37
	v_sub_f32_e32 v29, v29, v35
	v_mul_f32_e32 v35, v36, v38
	v_mul_f32_e32 v37, v33, v35
	v_fma_f32 v39, v35, v33, -v37
	v_fmac_f32_e32 v39, v35, v29
	v_add_f32_e32 v40, v37, v39
	v_sub_f32_e32 v41, v36, v40
	v_sub_f32_e32 v36, v36, v41
	v_sub_f32_e32 v37, v40, v37
	v_sub_f32_e32 v36, v36, v40
	v_add_f32_e32 v34, v34, v36
	v_sub_f32_e32 v36, v37, v39
	v_add_f32_e32 v34, v36, v34
	v_add_f32_e32 v36, v41, v34
	v_mul_f32_e32 v37, v38, v36
	v_mul_f32_e32 v39, v33, v37
	v_fma_f32 v33, v37, v33, -v39
	v_fmac_f32_e32 v33, v37, v29
	v_sub_f32_e32 v29, v41, v36
	v_add_f32_e32 v29, v34, v29
	v_add_f32_e32 v34, v39, v33
	v_sub_f32_e32 v40, v36, v34
	v_sub_f32_e32 v36, v36, v40
	v_sub_f32_e32 v39, v34, v39
	v_sub_f32_e32 v34, v36, v34
	v_add_f32_e32 v29, v29, v34
	v_sub_f32_e32 v33, v39, v33
	v_cvt_f32_i32_e32 v28, v28
	v_add_f32_e32 v29, v33, v29
	v_add_f32_e32 v33, v35, v37
	v_add_f32_e32 v29, v40, v29
	v_sub_f32_e32 v34, v33, v35
	v_mul_f32_e32 v29, v38, v29
	v_sub_f32_e32 v34, v37, v34
	v_add_f32_e32 v29, v34, v29
	v_mul_f32_e32 v37, 0x3f317218, v28
	v_add_f32_e32 v34, v33, v29
	v_fma_f32 v38, v28, s5, -v37
	v_mul_f32_e32 v35, v34, v34
	v_fmac_f32_e32 v38, 0xb102e308, v28
	v_sub_f32_e32 v28, v34, v33
	v_fmamk_f32 v36, v35, 0x3e9b6dac, v201
	v_sub_f32_e32 v28, v29, v28
	v_add_f32_e32 v29, v37, v38
	v_fmaak_f32 v36, v35, v36, 0x3f2aaada
	v_sub_f32_e32 v33, v29, v37
	v_ldexp_f32 v37, v34, 1
	v_mul_f32_e32 v34, v34, v35
	v_mul_f32_e32 v34, v34, v36
	v_add_f32_e32 v35, v37, v34
	v_sub_f32_e32 v36, v35, v37
	v_ldexp_f32 v28, v28, 1
	v_sub_f32_e32 v34, v34, v36
	v_add_f32_e32 v28, v28, v34
	v_add_f32_e32 v34, v35, v28
	v_sub_f32_e32 v35, v34, v35
	v_sub_f32_e32 v28, v28, v35
	v_add_f32_e32 v35, v29, v34
	v_sub_f32_e32 v36, v35, v29
	v_sub_f32_e32 v37, v35, v36
	v_sub_f32_e32 v33, v38, v33
	v_sub_f32_e32 v29, v29, v37
	v_sub_f32_e32 v34, v34, v36
	v_add_f32_e32 v29, v34, v29
	v_add_f32_e32 v34, v33, v28
	v_sub_f32_e32 v36, v34, v33
	v_sub_f32_e32 v37, v34, v36
	v_sub_f32_e32 v33, v33, v37
	v_sub_f32_e32 v28, v28, v36
	v_add_f32_e32 v29, v34, v29
	v_add_f32_e32 v28, v28, v33
	v_add_f32_e32 v33, v35, v29
	v_sub_f32_e32 v34, v33, v35
	v_sub_f32_e32 v29, v29, v34
	v_add_f32_e32 v28, v28, v29
	v_add_f32_e32 v28, v33, v28
	v_cmp_neq_f32_e32 vcc, s33, v30
	v_min_f32_e32 v50, 0, v50
	v_sub_f32_e32 v50, v50, v54
	v_cndmask_b32_e32 v28, v203, v28, vcc
	v_cmp_ngt_f32_e32 vcc, -1.0, v30
	v_mul_f32_e32 v54, 0x3d800000, v50
	v_mul_f32_e32 v56, 0x3e000000, v58
	v_cndmask_b32_e32 v28, v204, v28, vcc
	v_cmp_neq_f32_e32 vcc, -1.0, v30
	v_mov_b32_dpp v54, v54 row_shr:1 row_mask:0xf bank_mask:0xf bound_ctrl:1
	v_fmac_f32_e32 v54, 0x3d800000, v50
	v_cndmask_b32_e32 v28, v205, v28, vcc
	v_cmp_lt_f32_e64 vcc, |v30|, s34
	v_add_f32_dpp v50, v54, v54 row_shr:2 row_mask:0xf bank_mask:0xf bound_ctrl:1
	v_mov_b32_e32 v54, 0
	v_cndmask_b32_e32 v28, v28, v30, vcc
	v_subrev_f32_e32 v30, s26, v117
	v_sub_f32_e32 v28, v32, v28
	v_cndmask_b32_e64 v30, v30, v117, s[24:25]
	v_mul_f32_e32 v29, 0x3d800000, v28
	v_max_f32_e32 v30, 0xc2a00000, v30
	v_mul_f32_e32 v30, 0x3fb8aa3b, v30
	v_mov_b32_dpp v29, v29 row_shr:1 row_mask:0xf bank_mask:0xf bound_ctrl:1
	v_fmac_f32_e32 v29, 0x3d800000, v28
	v_exp_f32_e32 v32, v30
	v_sub_f32_e32 v30, s26, v117
	v_add_f32_dpp v28, v29, v29 row_shr:2 row_mask:0xf bank_mask:0xf bound_ctrl:1
	v_min_f32_e32 v30, 0x42a00000, v30
	v_mul_f32_e32 v30, 0x3fb8aa3b, v30
	v_add_f32_dpp v28, v28, v28 row_shr:4 row_mask:0xf bank_mask:0xf bound_ctrl:1
	v_mov_b32_e32 v29, 0
	v_exp_f32_e32 v30, v30
	v_add_f32_dpp v28, v28, v28 row_shr:8 row_mask:0xf bank_mask:0xf bound_ctrl:1
	v_readlane_b32 s30, v32, 31
	v_rcp_f32_e32 v35, v32
	v_mov_b32_dpp v29, v28 row_bcast:15 row_mask:0xa bank_mask:0xf
	v_add_f32_e32 v28, v28, v29
	v_mov_b32_e32 v29, 0
	v_readlane_b32 s26, v30, 63
	v_mul_f32_e32 v36, v116, v32
	v_mov_b32_dpp v29, v28 row_bcast:31 row_mask:0xc bank_mask:0xf
	v_add_f32_e32 v57, v28, v29
	v_mul_f32_e32 v29, s30, v32
	v_rcp_f32_e32 v28, s26
	v_cndmask_b32_e64 v29, v29, v32, s[24:25]
	v_readlane_b32 s26, v118, 31
	v_mul_f32_e32 v34, v116, v29
	v_add_f32_dpp v50, v50, v50 row_shr:4 row_mask:0xf bank_mask:0xf bound_ctrl:1
	v_subrev_f32_e32 v29, s26, v118
	v_cndmask_b32_e64 v29, v29, v118, s[24:25]
	v_max_f32_e32 v29, 0xc2a00000, v29
	v_mul_f32_e32 v29, 0x3fb8aa3b, v29
	v_exp_f32_e32 v33, v29
	v_sub_f32_e32 v29, s26, v118
	v_min_f32_e32 v29, 0x42a00000, v29
	v_mul_f32_e32 v29, 0x3fb8aa3b, v29
	v_exp_f32_e32 v31, v29
	v_readlane_b32 s31, v33, 31
	v_rcp_f32_e32 v39, v33
	v_mul_f32_e32 v40, v44, v33
	v_mul_f32_e32 v32, s31, v33
	v_cndmask_b32_e64 v32, v32, v33, s[24:25]
	v_mul_f32_e32 v38, v44, v32
	s_waitcnt lgkmcnt(0)
	v_lshlrev_b32_e32 v32, 16, v24
	v_and_b32_e32 v33, 0xffff0000, v24
	v_readlane_b32 s26, v31, 63
	v_mul_f32_e32 v24, v35, v32
	v_pk_mul_f32 v[30:31], v[30:31], v[32:33]
	v_mul_f32_e32 v32, v39, v33
	v_rcp_f32_e32 v29, s26
	v_cndmask_b32_e64 v24, v36, v24, s[24:25]
	v_cndmask_b32_e64 v32, v40, v32, s[24:25]
	v_readlane_b32 s26, v119, 31
	v_cvt_pk_bf16_f32 v34, v34, v38
	v_cvt_pk_bf16_f32 v38, v24, v32
	v_subrev_f32_e32 v24, s26, v119
	v_cndmask_b32_e64 v24, v24, v119, s[24:25]
	v_max_f32_e32 v24, 0xc2a00000, v24
	v_sub_f32_e32 v32, s26, v119
	v_mul_f32_e32 v24, 0x3fb8aa3b, v24
	v_min_f32_e32 v32, 0x42a00000, v32
	v_exp_f32_e32 v24, v24
	v_mul_f32_e32 v32, 0x3fb8aa3b, v32
	v_exp_f32_e32 v32, v32
	v_pk_mul_f32 v[36:37], v[28:29], v[30:31]
	v_readlane_b32 s38, v24, 31
	v_cvt_pk_bf16_f32 v42, v30, v31
	v_readlane_b32 s26, v32, 63
	v_mul_f32_e32 v31, s38, v24
	v_cndmask_b32_e64 v31, v31, v24, s[24:25]
	v_rcp_f32_e32 v30, s26
	v_readlane_b32 s26, v48, 31
	v_add_f32_dpp v50, v50, v50 row_shr:8 row_mask:0xf bank_mask:0xf bound_ctrl:1
	v_mul_f32_e32 v35, v120, v31
	v_subrev_f32_e32 v31, s26, v48
	v_mov_b32_dpp v54, v50 row_bcast:15 row_mask:0xa bank_mask:0xf
	v_cndmask_b32_e64 v31, v31, v48, s[24:25]
	v_add_f32_e32 v50, v50, v54
	v_mov_b32_e32 v54, 0
	v_max_f32_e32 v31, 0xc2a00000, v31
	v_mul_f32_e32 v31, 0x3fb8aa3b, v31
	v_mov_b32_dpp v54, v50 row_bcast:31 row_mask:0xc bank_mask:0xf
	v_add_f32_e32 v54, v50, v54
	v_cvt_pk_bf16_f32 v50, v36, v37
	v_exp_f32_e32 v36, v31
	v_sub_f32_e32 v31, s26, v48
	v_min_f32_e32 v31, 0x42a00000, v31
	v_mul_f32_e32 v31, 0x3fb8aa3b, v31
	v_exp_f32_e32 v33, v31
	v_rcp_f32_e32 v37, v24
	v_readlane_b32 s39, v36, 31
	v_rcp_f32_e32 v41, v36
	v_mul_f32_e32 v39, v120, v24
	v_mul_f32_e32 v24, s39, v36
	v_cndmask_b32_e64 v24, v24, v36, s[24:25]
	v_mul_f32_e32 v40, v45, v24
	v_lshlrev_b32_e32 v24, 16, v25
	v_and_b32_e32 v25, 0xffff0000, v25
	v_readlane_b32 s26, v33, 63
	v_mul_f32_e32 v43, v45, v36
	v_mul_f32_e32 v36, v37, v24
	v_pk_mul_f32 v[32:33], v[32:33], v[24:25]
	v_mul_f32_e32 v24, v41, v25
	v_rcp_f32_e32 v31, s26
	v_cndmask_b32_e64 v39, v39, v36, s[24:25]
	v_cndmask_b32_e64 v24, v43, v24, s[24:25]
	v_readlane_b32 s26, v49, 31
	v_cvt_pk_bf16_f32 v39, v39, v24
	v_cvt_pk_bf16_f32 v35, v35, v40
	v_subrev_f32_e32 v24, s26, v49
	v_cndmask_b32_e64 v24, v24, v49, s[24:25]
	v_max_f32_e32 v24, 0xc2a00000, v24
	v_mul_f32_e32 v24, 0x3fb8aa3b, v24
	v_exp_f32_e32 v25, v24
	v_sub_f32_e32 v24, s26, v49
	v_min_f32_e32 v24, 0x42a00000, v24
	v_mul_f32_e32 v24, 0x3fb8aa3b, v24
	v_exp_f32_e32 v40, v24
	v_readlane_b32 s40, v25, 31
	v_pk_mul_f32 v[36:37], v[30:31], v[32:33]
	v_cvt_pk_bf16_f32 v43, v32, v33
	v_readlane_b32 s26, v40, 63
	v_mul_f32_e32 v32, s40, v25
	v_cndmask_b32_e64 v32, v32, v25, s[24:25]
	v_rcp_f32_e32 v24, s26
	v_readlane_b32 s26, v53, 31
	v_cvt_pk_bf16_f32 v51, v36, v37
	v_mul_f32_e32 v36, v52, v32
	v_subrev_f32_e32 v32, s26, v53
	v_cndmask_b32_e64 v32, v32, v53, s[24:25]
	v_max_f32_e32 v32, 0xc2a00000, v32
	v_mul_f32_e32 v32, 0x3fb8aa3b, v32
	v_exp_f32_e32 v32, v32
	v_sub_f32_e32 v33, s26, v53
	v_min_f32_e32 v33, 0x42a00000, v33
	v_mul_f32_e32 v33, 0x3fb8aa3b, v33
	v_rcp_f32_e32 v37, v25
	v_exp_f32_e32 v41, v33
	v_readlane_b32 s41, v32, 31
	v_rcp_f32_e32 v49, v32
	v_mul_f32_e32 v44, v52, v25
	v_mul_f32_e32 v33, s41, v32
	v_cndmask_b32_e64 v33, v33, v32, s[24:25]
	v_mul_f32_e32 v52, v46, v32
	v_lshlrev_b32_e32 v32, 16, v26
	v_mul_f32_e32 v48, v46, v33
	v_and_b32_e32 v33, 0xffff0000, v26
	v_mul_f32_e32 v26, v37, v32
	v_readlane_b32 s26, v41, 63
	v_cndmask_b32_e64 v26, v44, v26, s[24:25]
	v_pk_mul_f32 v[44:45], v[40:41], v[32:33]
	v_mul_f32_e32 v32, v49, v33
	v_rcp_f32_e32 v25, s26
	v_cndmask_b32_e64 v32, v52, v32, s[24:25]
	v_readlane_b32 s26, v54, 31
	v_cvt_pk_bf16_f32 v40, v26, v32
	v_cvt_pk_bf16_f32 v36, v36, v48
	v_subrev_f32_e32 v26, s26, v54
	v_cndmask_b32_e64 v26, v26, v54, s[24:25]
	v_max_f32_e32 v26, 0xc2a00000, v26
	v_sub_f32_e32 v32, s26, v54
	v_mul_f32_e32 v26, 0x3fb8aa3b, v26
	v_min_f32_e32 v32, 0x42a00000, v32
	v_exp_f32_e32 v26, v26
	v_mul_f32_e32 v32, 0x3fb8aa3b, v32
	v_exp_f32_e32 v48, v32
	v_pk_mul_f32 v[46:47], v[24:25], v[44:45]
	v_readlane_b32 s42, v26, 31
	v_cvt_pk_bf16_f32 v44, v44, v45
	v_readlane_b32 s26, v48, 63
	v_mul_f32_e32 v33, s42, v26
	v_cndmask_b32_e64 v33, v33, v26, s[24:25]
	v_rcp_f32_e32 v32, s26
	v_readlane_b32 s26, v57, 31
	v_mul_f32_e32 v37, v56, v33
	v_rcp_f32_e32 v45, v26
	v_subrev_f32_e32 v33, s26, v57
	v_cndmask_b32_e64 v33, v33, v57, s[24:25]
	v_max_f32_e32 v33, 0xc2a00000, v33
	v_mul_f32_e32 v33, 0x3fb8aa3b, v33
	v_exp_f32_e32 v41, v33
	v_sub_f32_e32 v33, s26, v57
	v_min_f32_e32 v33, 0x42a00000, v33
	v_mul_f32_e32 v33, 0x3fb8aa3b, v33
	v_exp_f32_e32 v49, v33
	v_readlane_b32 s43, v41, 31
	v_cvt_pk_bf16_f32 v52, v46, v47
	v_mul_f32_e32 v46, v56, v26
	v_readlane_b32 s26, v49, 63
	v_mul_f32_e32 v26, s43, v41
	v_rcp_f32_e32 v54, v41
	v_rcp_f32_e32 v33, s26
	s_and_b32 s26, s36, 0xfffffe00
	v_cndmask_b32_e64 v26, v26, v41, s[24:25]
	s_or_b32 s26, s27, s26
	v_mul_f32_e32 v53, v55, v26
	v_lshlrev_b32_e32 v26, 16, v27
	s_or_b32 s26, s26, s85
	v_and_b32_e32 v27, 0xffff0000, v27
	v_mul_f32_e32 v45, v45, v26
	s_mul_hi_i32 s27, s26, 0x8100
	s_mul_i32 s26, s26, 0x8100
	v_mul_f32_e32 v41, v55, v41
	v_cndmask_b32_e64 v45, v46, v45, s[24:25]
	v_pk_mul_f32 v[46:47], v[48:49], v[26:27]
	v_mul_f32_e32 v26, v54, v27
	s_add_u32 s26, s87, s26
	v_pk_mul_f32 v[48:49], v[32:33], v[46:47]
	v_cndmask_b32_e64 v26, v41, v26, s[24:25]
	v_cvt_pk_bf16_f32 v37, v37, v53
	s_addc_u32 s27, s53, s27
	v_cvt_pk_bf16_f32 v41, v45, v26
	v_cvt_pk_bf16_f32 v45, v46, v47
	v_cvt_pk_bf16_f32 v53, v48, v49
	ds_write_b128 v194, v[34:37]
	ds_write_b128 v194, v[38:41] offset:9216
	ds_write_b128 v194, v[42:45] offset:18432
	ds_write_b128 v194, v[50:53] offset:27648
	s_and_saveexec_b64 s[28:29], s[22:23]
	s_cbranch_execz .LBB0_843
	v_mul_f32_e32 v28, s30, v28
	v_mul_f32_e32 v29, s31, v29
	v_cndmask_b32_e64 v28, 0, v28, s[6:7]
	v_mul_f32_e32 v30, s38, v30
	v_cndmask_b32_e64 v28, v28, v29, s[8:9]
	v_mul_f32_e32 v27, s39, v31
	v_cndmask_b32_e64 v28, v28, v30, s[10:11]
	v_mul_f32_e32 v24, s40, v24
	v_cndmask_b32_e64 v27, v28, v27, s[12:13]
	v_mul_f32_e32 v25, s41, v25
	v_cndmask_b32_e64 v24, v27, v24, s[14:15]
	v_mul_f32_e32 v26, s42, v32
	v_cndmask_b32_e64 v24, v24, v25, s[16:17]
	v_cndmask_b32_e64 v24, v24, v26, s[18:19]
	v_mul_f32_e32 v25, s43, v33
	v_cndmask_b32_e64 v26, v24, v25, s[20:21]
	v_lshl_add_u64 v[24:25], v[188:189], 2, s[26:27]
	v_add_co_u32_e32 v24, vcc, 0x8000, v24
	s_nop 1
	v_addc_co_u32_e32 v25, vcc, 0, v25, vcc
	global_store_dword v[24:25], v26, off nt
	s_branch .LBB0_843

.LBB0_2002:
	v_mov_b32_e32 v144, v150
	s_mov_b32 s19, s33
	v_mov_b32_e32 v156, v151
	s_mov_b32 s17, s39
	s_lshl_b64 s[24:25], s[8:9], 1
	v_lshl_add_u32 v144, s19, 6, v144
	s_add_u32 s24, s60, s24
	v_ashrrev_i32_e32 v145, 31, v144
	s_addc_u32 s25, s61, s25
	v_lshlrev_b64 v[146:147], 9, v[144:145]
	v_lshl_add_u64 v[146:147], s[24:25], 0, v[146:147]
	s_lshl_b32 s24, s17, 5
	s_ashr_i32 s25, s24, 31
	v_lshl_add_u64 v[148:149], s[24:25], 1, v[146:147]
	v_lshlrev_b32_e32 v146, 3, v156
	v_ashrrev_i32_e32 v147, 31, v146
	v_lshl_add_u64 v[148:149], v[146:147], 1, v[148:149]
	v_cvt_pk_bf16_f32 v156, v76, v77
	v_cvt_pk_bf16_f32 v157, v78, v79
	v_cvt_pk_bf16_f32 v158, v72, v73
	v_cvt_pk_bf16_f32 v159, v74, v75
	global_store_dwordx4 v[148:149], v[156:159], off nt
	v_cvt_pk_bf16_f32 v124, v124, v125
	s_movk_i32 s8, 0x2000
	v_cvt_pk_bf16_f32 v125, v126, v127
	v_cvt_pk_bf16_f32 v126, v120, v121
	v_cvt_pk_bf16_f32 v127, v122, v123
	global_store_dwordx4 v[148:149], v[124:127], off offset:256 nt
	v_cvt_pk_bf16_f32 v120, v68, v69
	v_cvt_pk_bf16_f32 v121, v70, v71
	v_cvt_pk_bf16_f32 v122, v64, v65
	v_cvt_pk_bf16_f32 v123, v66, v67
	s_nop 1
	v_add_co_u32_e32 v124, vcc, s8, v148
	s_movk_i32 s8, 0x4000
	s_nop 0
	v_addc_co_u32_e32 v125, vcc, 0, v149, vcc
	global_store_dwordx4 v[124:125], v[120:123], off nt
	v_cvt_pk_bf16_f32 v116, v116, v117
	v_cvt_pk_bf16_f32 v117, v118, v119
	v_cvt_pk_bf16_f32 v118, v112, v113
	v_cvt_pk_bf16_f32 v119, v114, v115
	global_store_dwordx4 v[124:125], v[116:119], off offset:256 nt
	v_cvt_pk_bf16_f32 v112, v56, v57
	v_cvt_pk_bf16_f32 v113, v58, v59
	v_cvt_pk_bf16_f32 v114, v52, v53
	v_cvt_pk_bf16_f32 v115, v54, v55
	s_nop 1
	v_add_co_u32_e32 v116, vcc, s8, v148
	s_movk_i32 s8, 0x6000
	s_nop 0
	v_addc_co_u32_e32 v117, vcc, 0, v149, vcc
	global_store_dwordx4 v[116:117], v[112:115], off nt
	v_cvt_pk_bf16_f32 v108, v108, v109
	v_cvt_pk_bf16_f32 v109, v110, v111
	v_cvt_pk_bf16_f32 v110, v104, v105
	v_cvt_pk_bf16_f32 v111, v106, v107
	global_store_dwordx4 v[116:117], v[108:111], off offset:256 nt
	v_cvt_pk_bf16_f32 v104, v44, v45
	v_cvt_pk_bf16_f32 v105, v46, v47
	v_cvt_pk_bf16_f32 v106, v40, v41
	v_cvt_pk_bf16_f32 v107, v42, v43
	s_nop 1
	v_add_co_u32_e32 v108, vcc, s8, v148
	s_mov_b32 s8, 0x10000
	s_nop 0
	v_addc_co_u32_e32 v109, vcc, 0, v149, vcc
	global_store_dwordx4 v[108:109], v[104:107], off nt
	v_cvt_pk_bf16_f32 v100, v100, v101
	v_cvt_pk_bf16_f32 v101, v102, v103
	v_cvt_pk_bf16_f32 v102, v96, v97
	v_cvt_pk_bf16_f32 v103, v98, v99
	global_store_dwordx4 v[108:109], v[100:103], off offset:256 nt
	v_cvt_pk_bf16_f32 v96, v28, v29
	v_cvt_pk_bf16_f32 v97, v30, v31
	v_cvt_pk_bf16_f32 v98, v24, v25
	v_cvt_pk_bf16_f32 v99, v26, v27
	s_nop 1
	v_add_co_u32_e32 v100, vcc, s8, v148
	s_mov_b32 s8, 0x12000
	s_nop 0
	v_addc_co_u32_e32 v101, vcc, 0, v149, vcc
	global_store_dwordx4 v[100:101], v[96:99], off nt
	v_cvt_pk_bf16_f32 v92, v92, v93
	v_cvt_pk_bf16_f32 v93, v94, v95
	v_cvt_pk_bf16_f32 v94, v88, v89
	v_cvt_pk_bf16_f32 v95, v90, v91
	global_store_dwordx4 v[100:101], v[92:95], off offset:256 nt
	v_cvt_pk_bf16_f32 v88, v20, v21
	v_cvt_pk_bf16_f32 v89, v22, v23
	v_cvt_pk_bf16_f32 v90, v16, v17
	v_cvt_pk_bf16_f32 v91, v18, v19
	s_nop 1
	v_add_co_u32_e32 v92, vcc, s8, v148
	s_mov_b32 s8, 0x14000
	s_nop 0
	v_addc_co_u32_e32 v93, vcc, 0, v149, vcc
	global_store_dwordx4 v[92:93], v[88:91], off nt
	v_cvt_pk_bf16_f32 v84, v84, v85
	v_cvt_pk_bf16_f32 v85, v86, v87
	v_cvt_pk_bf16_f32 v86, v80, v81
	v_cvt_pk_bf16_f32 v87, v82, v83
	global_store_dwordx4 v[92:93], v[84:87], off offset:256 nt
	v_cvt_pk_bf16_f32 v80, v12, v13
	v_cvt_pk_bf16_f32 v81, v14, v15
	v_cvt_pk_bf16_f32 v82, v8, v9
	v_cvt_pk_bf16_f32 v83, v10, v11
	s_nop 1
	v_add_co_u32_e32 v84, vcc, s8, v148
	s_mov_b32 s8, 0x16000
	s_nop 0
	v_addc_co_u32_e32 v85, vcc, 0, v149, vcc
	global_store_dwordx4 v[84:85], v[80:83], off nt
	v_cvt_pk_bf16_f32 v60, v60, v61
	v_cvt_pk_bf16_f32 v61, v62, v63
	v_cvt_pk_bf16_f32 v62, v48, v49
	v_cvt_pk_bf16_f32 v63, v50, v51
	global_store_dwordx4 v[84:85], v[60:63], off offset:256 nt
	v_cvt_pk_bf16_f32 v48, v4, v5
	v_cvt_pk_bf16_f32 v49, v6, v7
	v_cvt_pk_bf16_f32 v50, v0, v1
	v_cvt_pk_bf16_f32 v51, v2, v3
	s_nop 1
	v_add_co_u32_e32 v60, vcc, s8, v148
	s_nop 1
	v_addc_co_u32_e32 v61, vcc, 0, v149, vcc
	s_andn2_b64 vcc, exec, s[14:15]
	global_store_dwordx4 v[60:61], v[48:51], off nt
	v_cvt_pk_bf16_f32 v36, v36, v37
	v_cvt_pk_bf16_f32 v37, v38, v39
	v_cvt_pk_bf16_f32 v38, v32, v33
	v_cvt_pk_bf16_f32 v39, v34, v35
	global_store_dwordx4 v[60:61], v[36:39], off offset:256 nt
	s_cbranch_vccnz .LBB0_2005
	s_cmp_lg_u32 s41, 26
	s_cselect_b64 s[24:25], -1, 0
	s_cmp_lg_u32 s17, 0
	s_cselect_b64 s[26:27], -1, 0
	s_or_b64 s[24:25], s[26:27], s[24:25]
	s_and_b64 vcc, exec, s[24:25]
	s_cbranch_vccnz .LBB0_2005
	v_lshl_add_u32 v32, s40, 8, v144
	v_ashrrev_i32_e32 v33, 31, v32
	v_lshlrev_b64 v[34:35], 7, v[32:33]
	v_lshl_add_u64 v[34:35], s[66:67], 0, v[34:35]
	v_lshlrev_b64 v[36:37], 2, v[146:147]
	v_lshl_add_u64 v[34:35], v[34:35], 0, v[36:37]
	global_store_dwordx4 v[34:35], v[76:79], off nt
	global_store_dwordx4 v[34:35], v[72:75], off offset:16 nt
	v_add_u32_e32 v34, 16, v32
	v_ashrrev_i32_e32 v35, 31, v34
	v_lshlrev_b64 v[34:35], 7, v[34:35]
	v_lshl_add_u64 v[34:35], s[66:67], 0, v[34:35]
	v_lshl_add_u64 v[34:35], v[34:35], 0, v[36:37]
	global_store_dwordx4 v[34:35], v[68:71], off nt
	global_store_dwordx4 v[34:35], v[64:67], off offset:16 nt
	v_add_u32_e32 v34, 32, v32
	v_ashrrev_i32_e32 v35, 31, v34
	v_lshlrev_b64 v[34:35], 7, v[34:35]
	v_lshl_add_u64 v[34:35], s[66:67], 0, v[34:35]
	v_lshl_add_u64 v[34:35], v[34:35], 0, v[36:37]
	global_store_dwordx4 v[34:35], v[56:59], off nt
	global_store_dwordx4 v[34:35], v[52:55], off offset:16 nt
	v_add_u32_e32 v34, 48, v32
	v_ashrrev_i32_e32 v35, 31, v34
	v_lshlrev_b64 v[34:35], 7, v[34:35]
	v_lshl_add_u64 v[34:35], s[66:67], 0, v[34:35]
	v_lshl_add_u64 v[34:35], v[34:35], 0, v[36:37]
	global_store_dwordx4 v[34:35], v[44:47], off nt
	global_store_dwordx4 v[34:35], v[40:43], off offset:16 nt
	v_add_u32_e32 v34, 0x80, v32
	v_ashrrev_i32_e32 v35, 31, v34
	v_lshlrev_b64 v[34:35], 7, v[34:35]
	v_lshl_add_u64 v[34:35], s[66:67], 0, v[34:35]
	v_lshl_add_u64 v[34:35], v[34:35], 0, v[36:37]
	global_store_dwordx4 v[34:35], v[28:31], off nt
	global_store_dwordx4 v[34:35], v[24:27], off offset:16 nt
	s_nop 1
	v_add_u32_e32 v24, 0x90, v32
	v_ashrrev_i32_e32 v25, 31, v24
	v_lshlrev_b64 v[24:25], 7, v[24:25]
	v_lshl_add_u64 v[24:25], s[66:67], 0, v[24:25]
	v_lshl_add_u64 v[24:25], v[24:25], 0, v[36:37]
	global_store_dwordx4 v[24:25], v[20:23], off nt
	global_store_dwordx4 v[24:25], v[16:19], off offset:16 nt
	s_nop 1
	v_add_u32_e32 v16, 0xa0, v32
	v_ashrrev_i32_e32 v17, 31, v16
	v_lshlrev_b64 v[16:17], 7, v[16:17]
	v_lshl_add_u64 v[16:17], s[66:67], 0, v[16:17]
	v_lshl_add_u64 v[16:17], v[16:17], 0, v[36:37]
	global_store_dwordx4 v[16:17], v[12:15], off nt
	global_store_dwordx4 v[16:17], v[8:11], off offset:16 nt
	s_nop 1
	v_add_u32_e32 v8, 0xb0, v32
	v_ashrrev_i32_e32 v9, 31, v8
	v_lshlrev_b64 v[8:9], 7, v[8:9]
	v_lshl_add_u64 v[8:9], s[66:67], 0, v[8:9]
	v_lshl_add_u64 v[8:9], v[8:9], 0, v[36:37]
	global_store_dwordx4 v[8:9], v[4:7], off nt
	global_store_dwordx4 v[8:9], v[0:3], off offset:16 nt

.LBB0_2088:
	s_or_b64 exec, exec, s[46:47]
	s_waitcnt lgkmcnt(0)
	s_barrier
	ds_read_b128 v[18:21], v124
	v_lshl_add_u64 v[22:23], v[186:187], 4, s[42:43]
	v_add_co_u32_e32 v24, vcc, 0x2000, v22
	s_addk_i32 s51, 0x100
	s_waitcnt lgkmcnt(0)
	global_store_dwordx4 v[22:23], v[18:21], off nt
	ds_read_b128 v[18:21], v124 offset:9216
	v_addc_co_u32_e32 v25, vcc, 0, v23, vcc
	v_add_co_u32_e32 v22, vcc, 0x4000, v22
	s_waitcnt lgkmcnt(0)
	global_store_dwordx4 v[24:25], v[18:21], off nt
	ds_read_b128 v[18:21], v124 offset:18432
	v_addc_co_u32_e32 v23, vcc, 0, v23, vcc
	s_cmpk_eq_i32 s51, 0x800
	v_mov_b32_e32 v54, v129
	s_waitcnt lgkmcnt(0)
	global_store_dwordx4 v[22:23], v[18:21], off nt
	s_waitcnt lgkmcnt(0)
	s_barrier
	v_mov_b32_e32 v90, v17
	s_cbranch_scc1 .LBB0_2111

.LBB0_2109:
	v_lshl_add_u64 v[18:19], v[184:185], 2, s[44:45]
	global_store_dword v[18:19], v130, off nt
	global_store_dword v[18:19], v131, off offset:256 nt
	global_store_dword v[18:19], v117, off offset:512 nt
	s_and_saveexec_b64 s[46:47], s[22:23]
	s_cbranch_execz .LBB0_2088
.LBB0_2110:
	v_mov_b32_e32 v18, s3
	v_cndmask_b32_e64 v18, 0, v18, s[6:7]
	v_mov_b32_e32 v19, s53
	v_cndmask_b32_e64 v18, v18, v19, s[8:9]
	v_mov_b32_e32 v19, s55
	v_cndmask_b32_e64 v18, v18, v19, s[10:11]
	v_mov_b32_e32 v19, s56
	v_cndmask_b32_e64 v18, v18, v19, s[12:13]
	v_mov_b32_e32 v19, s68
	v_cndmask_b32_e64 v18, v18, v19, s[14:15]
	v_mov_b32_e32 v19, s69
	v_cndmask_b32_e64 v18, v18, v19, s[16:17]
	v_mov_b32_e32 v19, s70
	v_cndmask_b32_e64 v18, v18, v19, s[18:19]
	v_mov_b32_e32 v19, s71
	v_cndmask_b32_e64 v20, v18, v19, s[20:21]
	v_lshl_add_u64 v[18:19], v[114:115], 2, s[44:45]
	global_store_dword v[18:19], v20, off nt
	s_branch .LBB0_2088

.LBB0_2112:
	s_or_b64 exec, exec, s[76:77]
	s_waitcnt lgkmcnt(0)
	s_barrier
	ds_read_b128 v[16:19], v80
	v_lshl_add_u64 v[20:21], v[186:187], 4, s[46:47]
	v_add_co_u32_e32 v22, vcc, 0x2000, v20
	s_addk_i32 s33, 0x100
	s_waitcnt lgkmcnt(0)
	global_store_dwordx4 v[20:21], v[16:19], off nt
	ds_read_b128 v[16:19], v81
	v_addc_co_u32_e32 v23, vcc, 0, v21, vcc
	s_cmpk_eq_i32 s33, 0x800
	s_waitcnt lgkmcnt(0)
	global_store_dwordx4 v[22:23], v[16:19], off nt
	ds_read_b128 v[16:19], v80 offset:17408
	v_add_co_u32_e32 v22, vcc, 0x4000, v20
	s_nop 1
	v_addc_co_u32_e32 v23, vcc, 0, v21, vcc
	s_waitcnt lgkmcnt(0)
	global_store_dwordx4 v[22:23], v[16:19], off nt
	ds_read_b128 v[16:19], v81 offset:17408
	v_add_co_u32_e32 v22, vcc, 0x6000, v20
	s_nop 1
	v_addc_co_u32_e32 v23, vcc, 0, v21, vcc
	s_waitcnt lgkmcnt(0)
	global_store_dwordx4 v[22:23], v[16:19], off nt
	ds_read_b128 v[16:19], v80 offset:34816
	v_add_co_u32_e32 v22, vcc, 0x8000, v20
	s_nop 1
	v_addc_co_u32_e32 v23, vcc, 0, v21, vcc
	s_waitcnt lgkmcnt(0)
	global_store_dwordx4 v[22:23], v[16:19], off nt
	ds_read_b128 v[16:19], v81 offset:34816
	v_add_co_u32_e32 v22, vcc, 0xa000, v20
	s_nop 1
	v_addc_co_u32_e32 v23, vcc, 0, v21, vcc
	s_waitcnt lgkmcnt(0)
	global_store_dwordx4 v[22:23], v[16:19], off nt
	ds_read_b128 v[16:19], v80 offset:52224
	v_add_co_u32_e32 v22, vcc, 0xc000, v20
	s_nop 1
	v_addc_co_u32_e32 v23, vcc, 0, v21, vcc
	s_waitcnt lgkmcnt(0)
	global_store_dwordx4 v[22:23], v[16:19], off nt
	ds_read_b128 v[16:19], v81 offset:52224
	v_add_co_u32_e32 v20, vcc, 0xe000, v20
	s_nop 1
	v_addc_co_u32_e32 v21, vcc, 0, v21, vcc
	s_waitcnt lgkmcnt(0)
	global_store_dwordx4 v[20:21], v[16:19], off nt
	s_waitcnt lgkmcnt(0)
	s_barrier
	s_cbranch_scc1 .LBB0_2117

.LBB0_2115:
	s_and_b32 s56, s55, 0x180
	s_or_b32 s3, s56, s4
	s_lshl_b32 s3, s3, 2
	s_waitcnt lgkmcnt(0)
	s_barrier
	v_mov_b32_e32 v36, s3
	s_waitcnt lgkmcnt(0)
	global_load_dwordx4 v[40:43], v36, s[46:47]
	global_load_dwordx4 v[44:47], v36, s[76:77] offset:2048
	global_load_dwordx4 v[64:67], v36, s[76:77] offset:2064
	global_load_dwordx4 v[84:87], v36, s[46:47] offset:16
	ds_read_b128 v[58:61], v74
	ds_read_b128 v[16:19], v74 offset:16
	ds_read_b128 v[88:91], v74 offset:17408
	ds_read_b128 v[20:23], v74 offset:17424
	global_load_dwordx4 v[24:27], v36, s[76:77] offset:2096
	global_load_dwordx4 v[32:35], v36, s[76:77] offset:2080
	global_load_dwordx4 v[28:31], v36, s[46:47] offset:48
	s_nop 0
	global_load_dwordx4 v[36:39], v36, s[46:47] offset:32
	s_waitcnt lgkmcnt(3)
	v_lshlrev_b32_e32 v68, 16, v58
	v_and_b32_e32 v69, 0xffff0000, v58
	v_lshlrev_b32_e32 v70, 16, v59
	s_waitcnt lgkmcnt(1)
	v_lshlrev_b32_e32 v62, 16, v88
	v_and_b32_e32 v58, 0xffff0000, v88
	v_and_b32_e32 v71, 0xffff0000, v59
	v_mul_f32_e32 v72, 0xbfb8aa3b, v68
	v_mul_f32_e32 v73, 0xbfb8aa3b, v69
	v_mul_f32_e32 v88, 0xbfb8aa3b, v70
	v_lshlrev_b32_e32 v63, 16, v89
	v_and_b32_e32 v59, 0xffff0000, v89
	v_mul_f32_e32 v89, 0xbfb8aa3b, v71
	v_exp_f32_e32 v72, v72
	v_exp_f32_e32 v73, v73
	v_exp_f32_e32 v88, v88
	v_exp_f32_e32 v89, v89
	v_add_f32_e32 v72, 1.0, v72
	v_add_f32_e32 v73, 1.0, v73
	v_add_f32_e32 v88, 1.0, v88
	v_add_f32_e32 v89, 1.0, v89
	v_rcp_f32_e32 v72, v72
	v_rcp_f32_e32 v73, v73
	v_rcp_f32_e32 v88, v88
	v_rcp_f32_e32 v89, v89
	v_mul_f32_e32 v68, v72, v68
	v_mul_f32_e32 v69, v73, v69
	v_mul_f32_e32 v70, v88, v70
	v_mul_f32_e32 v88, v89, v71
	v_mul_f32_e32 v106, 0x3db504f3, v70
	v_mul_f32_e32 v110, 0x3db504f3, v68
	v_mul_f32_e32 v111, 0x3db504f3, v69
	v_mul_f32_e32 v62, 0xbfb8aa3b, v62
	v_mul_f32_e32 v58, 0xbfb8aa3b, v58
	v_exp_f32_e32 v62, v62
	v_exp_f32_e32 v58, v58
	v_mul_f32_e32 v59, 0xbfb8aa3b, v59
	v_exp_f32_e32 v59, v59
	v_add_f32_e32 v62, 1.0, v62
	v_add_f32_e32 v92, 1.0, v58
	v_rcp_f32_e32 v58, v62
	v_add_f32_e32 v93, 1.0, v59
	v_rcp_f32_e32 v59, v92
	v_mul_f32_e32 v63, 0xbfb8aa3b, v63
	v_exp_f32_e32 v63, v63
	v_mul_f32_e32 v107, 0x3db504f3, v88
	v_add_f32_e32 v63, 1.0, v63
	v_rcp_f32_e32 v62, v63
	v_rcp_f32_e32 v63, v93
	s_waitcnt vmcnt(6)
	v_sub_f32_e32 v40, v44, v40
	v_sub_f32_e32 v41, v45, v41
	v_sub_f32_e32 v42, v46, v42
	v_sub_f32_e32 v43, v47, v43
	v_mul_f32_e32 v40, 0xbfb8aa3b, v40
	v_mul_f32_e32 v41, 0xbfb8aa3b, v41
	v_mul_f32_e32 v42, 0xbfb8aa3b, v42
	v_mul_f32_e32 v43, 0xbfb8aa3b, v43
	v_exp_f32_e32 v40, v40
	v_exp_f32_e32 v41, v41
	v_exp_f32_e32 v42, v42
	v_exp_f32_e32 v43, v43
	s_waitcnt vmcnt(4)
	v_sub_f32_e32 v44, v64, v84
	v_add_f32_e32 v40, 1.0, v40
	v_add_f32_e32 v41, 1.0, v41
	v_mul_f32_e32 v44, 0xbfb8aa3b, v44
	v_add_f32_e32 v42, 1.0, v42
	v_add_f32_e32 v43, 1.0, v43
	v_rcp_f32_e32 v40, v40
	v_rcp_f32_e32 v41, v41
	v_exp_f32_e32 v44, v44
	v_rcp_f32_e32 v42, v42
	v_rcp_f32_e32 v43, v43
	v_med3_f32 v72, v40, 0, v82
	v_med3_f32 v73, v41, 0, v82
	v_lshlrev_b32_e32 v40, 16, v60
	v_lshlrev_b32_e32 v41, 16, v90
	v_med3_f32 v70, v42, 0, v82
	v_med3_f32 v71, v43, 0, v82
	v_add_f32_e32 v42, 1.0, v44
	v_mul_f32_e32 v43, 0xbfb8aa3b, v40
	v_mul_f32_e32 v41, 0xbfb8aa3b, v41
	v_rcp_f32_e32 v42, v42
	v_exp_f32_e32 v43, v43
	v_exp_f32_e32 v41, v41
	s_waitcnt vmcnt(0)
	v_sub_f32_e32 v32, v32, v36
	v_med3_f32 v68, v42, 0, v82
	v_add_f32_e32 v42, 1.0, v43
	v_add_f32_e32 v41, 1.0, v41
	v_rcp_f32_e32 v42, v42
	v_rcp_f32_e32 v64, v41
	v_sub_f32_e32 v41, v65, v85
	v_mul_f32_e32 v41, 0xbfb8aa3b, v41
	v_exp_f32_e32 v41, v41
	v_mul_f32_e32 v40, v42, v40
	v_mul_f32_e32 v102, 0x3db504f3, v40
	v_and_b32_e32 v40, 0xffff0000, v60
	v_add_f32_e32 v41, 1.0, v41
	v_mul_f32_e32 v43, 0xbfb8aa3b, v40
	v_rcp_f32_e32 v41, v41
	v_exp_f32_e32 v43, v43
	v_and_b32_e32 v42, 0xffff0000, v90
	v_mul_f32_e32 v42, 0xbfb8aa3b, v42
	v_med3_f32 v69, v41, 0, v82
	v_add_f32_e32 v41, 1.0, v43
	v_rcp_f32_e32 v41, v41
	v_exp_f32_e32 v42, v42
	v_mul_f32_e32 v32, 0xbfb8aa3b, v32
	v_exp_f32_e32 v32, v32
	v_mul_f32_e32 v40, v41, v40
	v_sub_f32_e32 v41, v66, v86
	v_mul_f32_e32 v41, 0xbfb8aa3b, v41
	v_exp_f32_e32 v41, v41
	v_mul_f32_e32 v103, 0x3db504f3, v40
	v_lshlrev_b32_e32 v40, 16, v61
	v_mul_f32_e32 v43, 0xbfb8aa3b, v40
	v_add_f32_e32 v41, 1.0, v41
	v_rcp_f32_e32 v41, v41
	v_exp_f32_e32 v43, v43
	v_add_f32_e32 v42, 1.0, v42
	v_rcp_f32_e32 v65, v42
	v_med3_f32 v66, v41, 0, v82
	v_add_f32_e32 v41, 1.0, v43
	v_rcp_f32_e32 v41, v41
	v_lshlrev_b32_e32 v42, 16, v91
	v_mul_f32_e32 v42, 0xbfb8aa3b, v42
	v_exp_f32_e32 v42, v42
	v_mul_f32_e32 v40, v41, v40
	v_sub_f32_e32 v41, v67, v87
	v_mul_f32_e32 v41, 0xbfb8aa3b, v41
	v_exp_f32_e32 v41, v41
	v_mul_f32_e32 v98, 0x3db504f3, v40
	v_and_b32_e32 v40, 0xffff0000, v61
	v_mul_f32_e32 v43, 0xbfb8aa3b, v40
	v_add_f32_e32 v41, 1.0, v41
	v_rcp_f32_e32 v41, v41
	v_exp_f32_e32 v43, v43
	v_add_f32_e32 v42, 1.0, v42
	v_rcp_f32_e32 v44, v42
	v_and_b32_e32 v42, 0xffff0000, v91
	v_med3_f32 v67, v41, 0, v82
	v_add_f32_e32 v41, 1.0, v43
	v_mul_f32_e32 v42, 0xbfb8aa3b, v42
	v_rcp_f32_e32 v41, v41
	v_exp_f32_e32 v42, v42
	v_add_f32_e32 v32, 1.0, v32
	v_rcp_f32_e32 v32, v32
	v_mul_f32_e32 v40, v41, v40
	v_lshlrev_b32_e32 v41, 16, v16
	v_add_f32_e32 v42, 1.0, v42
	v_mul_f32_e32 v99, 0x3db504f3, v40
	v_mul_f32_e32 v40, 0xbfb8aa3b, v41
	v_rcp_f32_e32 v45, v42
	v_exp_f32_e32 v42, v40
	v_med3_f32 v40, v32, 0, v82
	v_sub_f32_e32 v33, v33, v37
	v_mul_f32_e32 v33, 0xbfb8aa3b, v33
	v_add_f32_e32 v32, 1.0, v42
	v_rcp_f32_e32 v32, v32
	v_exp_f32_e32 v33, v33
	s_waitcnt lgkmcnt(0)
	v_lshlrev_b32_e32 v36, 16, v20
	v_and_b32_e32 v16, 0xffff0000, v16
	v_mul_f32_e32 v32, v32, v41
	v_and_b32_e32 v20, 0xffff0000, v20
	v_mul_f32_e32 v94, 0x3db504f3, v32
	v_add_f32_e32 v32, 1.0, v33
	v_mul_f32_e32 v33, 0xbfb8aa3b, v16
	v_mul_f32_e32 v20, 0xbfb8aa3b, v20
	v_rcp_f32_e32 v32, v32
	v_exp_f32_e32 v33, v33
	v_exp_f32_e32 v20, v20
	v_max_f32_e32 v89, 0x2b8cbccc, v72
	v_med3_f32 v41, v32, 0, v82
	v_add_f32_e32 v32, 1.0, v33
	v_add_f32_e32 v20, 1.0, v20
	v_rcp_f32_e32 v32, v32
	v_rcp_f32_e32 v37, v20
	v_sub_f32_e32 v20, v34, v38
	v_mul_f32_e32 v20, 0xbfb8aa3b, v20
	v_exp_f32_e32 v20, v20
	v_mul_f32_e32 v16, v32, v16
	v_mul_f32_e32 v95, 0x3db504f3, v16
	v_lshlrev_b32_e32 v16, 16, v17
	v_add_f32_e32 v20, 1.0, v20
	v_mul_f32_e32 v33, 0xbfb8aa3b, v16
	v_rcp_f32_e32 v20, v20
	v_exp_f32_e32 v33, v33
	v_lshlrev_b32_e32 v32, 16, v21
	v_mul_f32_e32 v32, 0xbfb8aa3b, v32
	v_exp_f32_e32 v34, v32
	v_med3_f32 v32, v20, 0, v82
	v_add_f32_e32 v20, 1.0, v33
	v_rcp_f32_e32 v20, v20
	v_add_f32_e32 v33, 1.0, v34
	v_rcp_f32_e32 v46, v33
	v_max_f32_e32 v112, 0x2b8cbccc, v73
	v_mul_f32_e32 v16, v20, v16
	v_sub_f32_e32 v20, v35, v39
	v_mul_f32_e32 v20, 0xbfb8aa3b, v20
	v_exp_f32_e32 v20, v20
	v_mul_f32_e32 v90, 0x3db504f3, v16
	v_and_b32_e32 v16, 0xffff0000, v17
	v_and_b32_e32 v17, 0xffff0000, v21
	v_add_f32_e32 v20, 1.0, v20
	v_mul_f32_e32 v21, 0xbfb8aa3b, v16
	v_mul_f32_e32 v17, 0xbfb8aa3b, v17
	v_rcp_f32_e32 v20, v20
	v_exp_f32_e32 v21, v21
	v_exp_f32_e32 v17, v17
	v_max_f32_e32 v113, 0x2b8cbccc, v70
	v_med3_f32 v33, v20, 0, v82
	v_add_f32_e32 v20, 1.0, v21
	v_add_f32_e32 v17, 1.0, v17
	v_rcp_f32_e32 v20, v20
	v_rcp_f32_e32 v47, v17
	v_sub_f32_e32 v17, v24, v28
	v_mul_f32_e32 v17, 0xbfb8aa3b, v17
	v_exp_f32_e32 v17, v17
	v_mul_f32_e32 v16, v20, v16
	v_mul_f32_e32 v91, 0x3db504f3, v16
	v_lshlrev_b32_e32 v16, 16, v18
	v_add_f32_e32 v17, 1.0, v17
	v_mul_f32_e32 v21, 0xbfb8aa3b, v16
	v_rcp_f32_e32 v17, v17
	v_exp_f32_e32 v21, v21
	v_lshlrev_b32_e32 v20, 16, v22
	v_mul_f32_e32 v20, 0xbfb8aa3b, v20
	v_med3_f32 v42, v17, 0, v82
	v_add_f32_e32 v17, 1.0, v21
	v_rcp_f32_e32 v17, v17
	v_exp_f32_e32 v20, v20
	v_max_f32_e32 v114, 0x2b8cbccc, v71
	v_max_f32_e32 v109, 0x2b8cbccc, v68
	v_mul_f32_e32 v16, v17, v16
	v_sub_f32_e32 v17, v25, v29
	v_mul_f32_e32 v17, 0xbfb8aa3b, v17
	v_exp_f32_e32 v17, v17
	v_add_f32_e32 v20, 1.0, v20
	v_mul_f32_e32 v86, 0x3db504f3, v16
	v_and_b32_e32 v16, 0xffff0000, v18
	v_rcp_f32_e32 v38, v20
	v_add_f32_e32 v17, 1.0, v17
	v_mul_f32_e32 v20, 0xbfb8aa3b, v16
	v_rcp_f32_e32 v17, v17
	v_exp_f32_e32 v20, v20
	v_and_b32_e32 v18, 0xffff0000, v22
	v_mul_f32_e32 v18, 0xbfb8aa3b, v18
	v_med3_f32 v43, v17, 0, v82
	v_add_f32_e32 v17, 1.0, v20
	v_rcp_f32_e32 v17, v17
	v_exp_f32_e32 v18, v18
	v_max_f32_e32 v108, 0x2b8cbccc, v69
	v_max_f32_e32 v105, 0x2b8cbccc, v66
	v_mul_f32_e32 v16, v17, v16
	v_sub_f32_e32 v17, v26, v30
	v_mul_f32_e32 v17, 0xbfb8aa3b, v17
	v_exp_f32_e32 v17, v17
	v_mul_f32_e32 v87, 0x3db504f3, v16
	v_lshlrev_b32_e32 v16, 16, v19
	v_mul_f32_e32 v20, 0xbfb8aa3b, v16
	v_add_f32_e32 v17, 1.0, v17
	v_rcp_f32_e32 v17, v17
	v_exp_f32_e32 v20, v20
	v_add_f32_e32 v18, 1.0, v18
	v_rcp_f32_e32 v39, v18
	v_med3_f32 v34, v17, 0, v82
	v_add_f32_e32 v17, 1.0, v20
	v_rcp_f32_e32 v17, v17
	v_lshlrev_b32_e32 v18, 16, v23
	v_mul_f32_e32 v18, 0xbfb8aa3b, v18
	v_exp_f32_e32 v18, v18
	v_mul_f32_e32 v16, v17, v16
	v_sub_f32_e32 v17, v27, v31
	v_mul_f32_e32 v17, 0xbfb8aa3b, v17
	v_exp_f32_e32 v17, v17
	v_add_f32_e32 v18, 1.0, v18
	v_mul_f32_e32 v84, 0x3db504f3, v16
	v_and_b32_e32 v16, 0xffff0000, v23
	v_rcp_f32_e32 v60, v18
	v_and_b32_e32 v18, 0xffff0000, v19
	v_mul_f32_e32 v16, 0xbfb8aa3b, v16
	v_exp_f32_e32 v16, v16
	v_mul_f32_e32 v19, 0xbfb8aa3b, v18
	v_add_f32_e32 v17, 1.0, v17
	v_exp_f32_e32 v19, v19
	v_rcp_f32_e32 v17, v17
	v_add_f32_e32 v16, 1.0, v16
	v_rcp_f32_e32 v61, v16
	v_add_f32_e32 v16, 1.0, v19
	v_med3_f32 v35, v17, 0, v82
	v_rcp_f32_e32 v19, v16
	v_pk_add_f32 v[16:17], v[72:73], 1.0 op_sel_hi:[1,0] neg_lo:[1,0] neg_hi:[1,0]
	v_pk_add_f32 v[26:27], v[70:71], 1.0 op_sel_hi:[1,0] neg_lo:[1,0] neg_hi:[1,0]
	v_fmac_f32_e32 v89, v58, v16
	v_cmp_gt_f32_e32 vcc, s50, v89
	v_mul_f32_e32 v18, v19, v18
	v_mul_f32_e32 v85, 0x3db504f3, v18
	v_cndmask_b32_e64 v20, 0, 32, vcc
	v_ldexp_f32 v20, v89, v20
	v_log_f32_e32 v20, v20
	v_cndmask_b32_e32 v19, 0, v83, vcc
	v_fmac_f32_e32 v112, v59, v17
	v_cmp_gt_f32_e32 vcc, s50, v112
	v_mul_f32_e32 v18, 0x3f317217, v20
	v_fma_f32 v18, v20, s5, -v18
	v_fmac_f32_e32 v18, 0x3377d1cf, v20
	v_fmac_f32_e32 v18, 0x3f317217, v20
	v_cmp_lt_f32_e64 s[46:47], |v20|, s53
	v_fmac_f32_e32 v113, v62, v26
	v_fmac_f32_e32 v114, v63, v27
	v_cndmask_b32_e64 v18, v20, v18, s[46:47]
	v_sub_f32_e32 v18, v18, v19
	v_mov_b32_e32 v19, 0
	v_mov_b32_e32 v20, 0
	v_add_f32_dpp v18, v18, v18 row_shr:1 row_mask:0xf bank_mask:0xf bound_ctrl:1
	v_max_f32_e32 v104, 0x2b8cbccc, v67
	v_pk_add_f32 v[66:67], v[66:67], 1.0 op_sel_hi:[1,0] neg_lo:[1,0] neg_hi:[1,0]
	v_add_f32_dpp v18, v18, v18 row_shr:2 row_mask:0xf bank_mask:0xf bound_ctrl:1
	v_fmac_f32_e32 v105, v44, v66
	v_fmac_f32_e32 v104, v45, v67
	v_add_f32_dpp v18, v18, v18 row_shr:4 row_mask:0xf bank_mask:0xf bound_ctrl:1
	v_pk_add_f32 v[44:45], v[44:45], 1.0 op_sel_hi:[1,0] neg_lo:[1,0] neg_hi:[1,0]
	v_mul_f32_e32 v36, 0xbfb8aa3b, v36
	v_add_f32_dpp v18, v18, v18 row_shr:8 row_mask:0xf bank_mask:0xf bound_ctrl:1
	v_pk_mul_f32 v[44:45], v[44:45], v[66:67]
	v_exp_f32_e32 v36, v36
	v_mov_b32_dpp v19, v18 row_bcast:15 row_mask:0xa bank_mask:0xf
	v_add_f32_e32 v18, v18, v19
	v_cndmask_b32_e64 v19, 0, 32, vcc
	v_ldexp_f32 v19, v112, v19
	v_log_f32_e32 v19, v19
	v_mov_b32_dpp v20, v18 row_bcast:31 row_mask:0xc bank_mask:0xf
	v_add_f32_e32 v20, v18, v20
	v_add_f32_e32 v36, 1.0, v36
	v_mul_f32_e32 v18, 0x3f317217, v19
	v_fma_f32 v18, v19, s5, -v18
	v_fmac_f32_e32 v18, 0x3377d1cf, v19
	v_fmac_f32_e32 v18, 0x3f317217, v19
	v_cmp_lt_f32_e64 s[46:47], |v19|, s53
	v_readlane_b32 s3, v20, 31
	v_rcp_f32_e32 v36, v36
	v_cndmask_b32_e64 v18, v19, v18, s[46:47]
	v_cndmask_b32_e32 v19, 0, v83, vcc
	v_sub_f32_e32 v21, v18, v19
	v_pk_add_f32 v[18:19], v[58:59], 1.0 op_sel_hi:[1,0] neg_lo:[1,0] neg_hi:[1,0]
	v_cmp_gt_f32_e32 vcc, s50, v113
	v_pk_mul_f32 v[16:17], v[18:19], v[16:17]
	v_add_f32_dpp v18, v21, v21 row_shr:1 row_mask:0xf bank_mask:0xf bound_ctrl:1
	v_mov_b32_e32 v19, 0
	v_mov_b32_e32 v21, 0
	v_add_f32_dpp v18, v18, v18 row_shr:2 row_mask:0xf bank_mask:0xf bound_ctrl:1
	v_max_f32_e32 v101, 0x2b8cbccc, v40
	v_max_f32_e32 v100, 0x2b8cbccc, v41
	v_add_f32_dpp v18, v18, v18 row_shr:4 row_mask:0xf bank_mask:0xf bound_ctrl:1
	v_pk_add_f32 v[40:41], v[40:41], 1.0 op_sel_hi:[1,0] neg_lo:[1,0] neg_hi:[1,0]
	v_max_f32_e32 v97, 0x2b8cbccc, v32
	v_add_f32_dpp v18, v18, v18 row_shr:8 row_mask:0xf bank_mask:0xf bound_ctrl:1
	v_fmac_f32_e32 v101, v36, v40
	v_fmac_f32_e32 v100, v37, v41
	v_mov_b32_dpp v19, v18 row_bcast:15 row_mask:0xa bank_mask:0xf
	v_add_f32_e32 v19, v18, v19
	v_subrev_f32_e32 v18, s3, v20
	v_cndmask_b32_e64 v18, v18, v20, s[24:25]
	v_max_f32_e32 v18, 0xc2a00000, v18
	v_mul_f32_e32 v18, 0x3fb8aa3b, v18
	v_exp_f32_e32 v22, v18
	v_sub_f32_e32 v18, s3, v20
	v_min_f32_e32 v18, 0x42a00000, v18
	v_mul_f32_e32 v18, 0x3fb8aa3b, v18
	v_exp_f32_e32 v18, v18
	v_mov_b32_dpp v21, v19 row_bcast:31 row_mask:0xc bank_mask:0xf
	v_add_f32_e32 v20, v19, v21
	v_readlane_b32 s68, v22, 31
	v_readlane_b32 s3, v18, 63
	v_rcp_f32_e32 v23, v22
	v_mul_f32_e32 v19, s68, v22
	v_rcp_f32_e32 v58, s3
	v_readlane_b32 s3, v20, 31
	v_cndmask_b32_e64 v21, v19, v22, s[24:25]
	v_mul_f32_e32 v23, v16, v23
	v_subrev_f32_e32 v24, s3, v20
	v_sub_f32_e32 v19, s3, v20
	v_cndmask_b32_e64 v20, v24, v20, s[24:25]
	v_min_f32_e32 v19, 0x42a00000, v19
	v_max_f32_e32 v20, 0xc2a00000, v20
	v_mul_f32_e32 v19, 0x3fb8aa3b, v19
	v_mul_f32_e32 v20, 0x3fb8aa3b, v20
	v_exp_f32_e32 v19, v19
	v_exp_f32_e32 v20, v20
	v_mul_f32_e32 v22, v110, v22
	v_cndmask_b32_e64 v24, v22, v23, s[24:25]
	v_readlane_b32 s46, v19, 63
	v_pk_mul_f32 v[18:19], v[16:17], v[18:19]
	v_rcp_f32_e32 v16, v20
	v_rcp_f32_e32 v59, s46
	v_readlane_b32 s69, v20, 31
	v_mul_f32_e32 v21, v110, v21
	v_mul_f32_e32 v16, v17, v16
	v_mul_f32_e32 v17, v111, v20
	v_cndmask_b32_e64 v16, v17, v16, s[24:25]
	v_cndmask_b32_e64 v17, 0, 32, vcc
	v_ldexp_f32 v17, v113, v17
	v_log_f32_e32 v17, v17
	v_pk_mul_f32 v[22:23], v[58:59], v[18:19]
	v_cvt_pk_bf16_f32 v28, v24, v16
	v_cvt_pk_bf16_f32 v24, v18, v19
	v_mul_f32_e32 v18, 0x3f317217, v17
	v_fma_f32 v18, v17, s5, -v18
	v_fmac_f32_e32 v18, 0x3377d1cf, v17
	v_fmac_f32_e32 v18, 0x3f317217, v17
	v_cmp_lt_f32_e64 s[46:47], |v17|, s53
	v_mov_b32_e32 v19, 0
	v_mul_f32_e32 v25, s69, v20
	v_cndmask_b32_e64 v17, v17, v18, s[46:47]
	v_cndmask_b32_e32 v18, 0, v83, vcc
	v_sub_f32_e32 v17, v17, v18
	v_mov_b32_e32 v18, 0
	v_cmp_gt_f32_e32 vcc, s50, v114
	v_add_f32_dpp v17, v17, v17 row_shr:1 row_mask:0xf bank_mask:0xf bound_ctrl:1
	v_cndmask_b32_e64 v25, v25, v20, s[24:25]
	v_mul_f32_e32 v25, v111, v25
	v_add_f32_dpp v17, v17, v17 row_shr:2 row_mask:0xf bank_mask:0xf bound_ctrl:1
	v_cvt_pk_bf16_f32 v20, v21, v25
	v_cvt_pk_bf16_f32 v16, v22, v23
	v_add_f32_dpp v17, v17, v17 row_shr:4 row_mask:0xf bank_mask:0xf bound_ctrl:1
	v_mov_b32_e32 v22, 0
	v_mov_b32_e32 v23, 0
	v_add_f32_dpp v17, v17, v17 row_shr:8 row_mask:0xf bank_mask:0xf bound_ctrl:1
	v_pk_add_f32 v[36:37], v[36:37], 1.0 op_sel_hi:[1,0] neg_lo:[1,0] neg_hi:[1,0]
	v_max_f32_e32 v96, 0x2b8cbccc, v33
	v_mov_b32_dpp v18, v17 row_bcast:15 row_mask:0xa bank_mask:0xf
	v_add_f32_e32 v17, v17, v18
	v_cndmask_b32_e64 v18, 0, 32, vcc
	v_ldexp_f32 v18, v114, v18
	v_log_f32_e32 v18, v18
	v_mov_b32_dpp v19, v17 row_bcast:31 row_mask:0xc bank_mask:0xf
	v_add_f32_e32 v17, v17, v19
	v_pk_mul_f32 v[36:37], v[36:37], v[40:41]
	v_mul_f32_e32 v19, 0x3f317217, v18
	v_fma_f32 v19, v18, s5, -v19
	v_fmac_f32_e32 v19, 0x3377d1cf, v18
	v_fmac_f32_e32 v19, 0x3f317217, v18
	v_cmp_lt_f32_e64 s[46:47], |v18|, s53
	v_readlane_b32 s3, v17, 31
	v_mov_b32_e32 v41, 0
	v_cndmask_b32_e64 v18, v18, v19, s[46:47]
	v_cndmask_b32_e32 v19, 0, v83, vcc
	v_sub_f32_e32 v21, v18, v19
	v_pk_add_f32 v[18:19], v[62:63], 1.0 op_sel_hi:[1,0] neg_lo:[1,0] neg_hi:[1,0]
	v_max_f32_e32 v93, 0x2b8cbccc, v42
	v_add_f32_dpp v21, v21, v21 row_shr:1 row_mask:0xf bank_mask:0xf bound_ctrl:1
	v_pk_mul_f32 v[18:19], v[18:19], v[26:27]
	v_max_f32_e32 v92, 0x2b8cbccc, v43
	v_add_f32_dpp v21, v21, v21 row_shr:2 row_mask:0xf bank_mask:0xf bound_ctrl:1
	v_pk_add_f32 v[42:43], v[42:43], 1.0 op_sel_hi:[1,0] neg_lo:[1,0] neg_hi:[1,0]
	v_max_f32_e32 v88, 0x2b8cbccc, v34
	v_add_f32_dpp v21, v21, v21 row_shr:4 row_mask:0xf bank_mask:0xf bound_ctrl:1
	v_fmac_f32_e32 v93, v38, v42
	v_fmac_f32_e32 v92, v39, v43
	v_add_f32_dpp v21, v21, v21 row_shr:8 row_mask:0xf bank_mask:0xf bound_ctrl:1
	v_pk_add_f32 v[38:39], v[38:39], 1.0 op_sel_hi:[1,0] neg_lo:[1,0] neg_hi:[1,0]
	v_max_f32_e32 v89, 0x2b8cbccc, v35
	v_mov_b32_dpp v22, v21 row_bcast:15 row_mask:0xa bank_mask:0xf
	v_add_f32_e32 v21, v21, v22
	v_subrev_f32_e32 v22, s3, v17
	v_cndmask_b32_e64 v22, v22, v17, s[24:25]
	v_sub_f32_e32 v17, s3, v17
	v_max_f32_e32 v22, 0xc2a00000, v22
	v_min_f32_e32 v17, 0x42a00000, v17
	v_mul_f32_e32 v22, 0x3fb8aa3b, v22
	v_mul_f32_e32 v17, 0x3fb8aa3b, v17
	v_exp_f32_e32 v25, v22
	v_exp_f32_e32 v22, v17
	v_mov_b32_dpp v23, v21 row_bcast:31 row_mask:0xc bank_mask:0xf
	v_add_f32_e32 v17, v21, v23
	v_rcp_f32_e32 v26, v25
	v_readlane_b32 s3, v22, 63
	v_readlane_b32 s70, v25, 31
	v_pk_mul_f32 v[38:39], v[38:39], v[42:43]
	v_rcp_f32_e32 v62, s3
	v_readlane_b32 s3, v17, 31
	v_mul_f32_e32 v26, v18, v26
	v_mul_f32_e32 v21, s70, v25
	v_subrev_f32_e32 v27, s3, v17
	v_sub_f32_e32 v23, s3, v17
	v_cndmask_b32_e64 v17, v27, v17, s[24:25]
	v_min_f32_e32 v23, 0x42a00000, v23
	v_max_f32_e32 v17, 0xc2a00000, v17
	v_mul_f32_e32 v23, 0x3fb8aa3b, v23
	v_mul_f32_e32 v17, 0x3fb8aa3b, v17
	v_exp_f32_e32 v23, v23
	v_exp_f32_e32 v17, v17
	v_cndmask_b32_e64 v21, v21, v25, s[24:25]
	v_mul_f32_e32 v21, v106, v21
	v_readlane_b32 s46, v23, 63
	v_pk_mul_f32 v[22:23], v[18:19], v[22:23]
	v_rcp_f32_e32 v18, v17
	v_readlane_b32 s71, v17, 31
	v_rcp_f32_e32 v63, s46
	v_mul_f32_e32 v25, v106, v25
	v_mul_f32_e32 v29, s71, v17
	v_cndmask_b32_e64 v29, v29, v17, s[24:25]
	v_mul_f32_e32 v18, v19, v18
	v_mul_f32_e32 v17, v107, v17
	v_cndmask_b32_e64 v17, v17, v18, s[24:25]
	v_pk_add_f32 v[18:19], v[68:69], 1.0 op_sel_hi:[1,0] neg_lo:[1,0] neg_hi:[1,0]
	v_mul_f32_e32 v29, v107, v29
	v_fmac_f32_e32 v109, v64, v18
	v_cmp_gt_f32_e32 vcc, s50, v109
	v_cvt_pk_bf16_f32 v21, v21, v29
	v_cndmask_b32_e64 v25, v25, v26, s[24:25]
	v_cndmask_b32_e64 v29, 0, 32, vcc
	v_ldexp_f32 v29, v109, v29
	v_log_f32_e32 v30, v29
	v_pk_mul_f32 v[26:27], v[62:63], v[22:23]
	v_cvt_pk_bf16_f32 v29, v25, v17
	v_cvt_pk_bf16_f32 v25, v22, v23
	v_mul_f32_e32 v22, 0x3f317217, v30
	v_fma_f32 v22, v30, s5, -v22
	v_fmac_f32_e32 v22, 0x3377d1cf, v30
	v_fmac_f32_e32 v22, 0x3f317217, v30
	v_cmp_lt_f32_e64 s[46:47], |v30|, s53
	v_cndmask_b32_e32 v23, 0, v83, vcc
	v_fmac_f32_e32 v108, v65, v19
	v_cndmask_b32_e64 v22, v30, v22, s[46:47]
	v_sub_f32_e32 v22, v22, v23
	v_mov_b32_e32 v23, 0
	v_cmp_gt_f32_e32 vcc, s50, v108
	v_add_f32_dpp v22, v22, v22 row_shr:1 row_mask:0xf bank_mask:0xf bound_ctrl:1
	v_cvt_pk_bf16_f32 v17, v26, v27
	v_mov_b32_e32 v26, 0
	v_add_f32_dpp v22, v22, v22 row_shr:2 row_mask:0xf bank_mask:0xf bound_ctrl:1
	v_mov_b32_e32 v43, 0
	s_nop 0
	v_add_f32_dpp v22, v22, v22 row_shr:4 row_mask:0xf bank_mask:0xf bound_ctrl:1
	s_nop 1
	v_add_f32_dpp v22, v22, v22 row_shr:8 row_mask:0xf bank_mask:0xf bound_ctrl:1
	s_nop 1
	v_mov_b32_dpp v23, v22 row_bcast:15 row_mask:0xa bank_mask:0xf
	v_add_f32_e32 v22, v22, v23
	v_cndmask_b32_e64 v23, 0, 32, vcc
	v_ldexp_f32 v23, v108, v23
	v_log_f32_e32 v23, v23
	v_mov_b32_dpp v26, v22 row_bcast:31 row_mask:0xc bank_mask:0xf
	v_add_f32_e32 v26, v22, v26
	v_mul_f32_e32 v22, 0x3f317217, v23
	v_fma_f32 v22, v23, s5, -v22
	v_fmac_f32_e32 v22, 0x3377d1cf, v23
	v_fmac_f32_e32 v22, 0x3f317217, v23
	v_cmp_lt_f32_e64 s[46:47], |v23|, s53
	v_readlane_b32 s3, v26, 31
	s_nop 0
	v_cndmask_b32_e64 v22, v23, v22, s[46:47]
	v_cndmask_b32_e32 v23, 0, v83, vcc
	v_sub_f32_e32 v27, v22, v23
	v_pk_add_f32 v[22:23], v[64:65], 1.0 op_sel_hi:[1,0] neg_lo:[1,0] neg_hi:[1,0]
	v_cmp_gt_f32_e32 vcc, s50, v105
	v_pk_mul_f32 v[18:19], v[22:23], v[18:19]
	v_add_f32_dpp v22, v27, v27 row_shr:1 row_mask:0xf bank_mask:0xf bound_ctrl:1
	v_mov_b32_e32 v23, 0
	v_mov_b32_e32 v27, 0
	v_add_f32_dpp v22, v22, v22 row_shr:2 row_mask:0xf bank_mask:0xf bound_ctrl:1
	s_nop 1
	v_add_f32_dpp v22, v22, v22 row_shr:4 row_mask:0xf bank_mask:0xf bound_ctrl:1
	s_nop 1
	v_add_f32_dpp v22, v22, v22 row_shr:8 row_mask:0xf bank_mask:0xf bound_ctrl:1
	s_nop 1
	v_mov_b32_dpp v23, v22 row_bcast:15 row_mask:0xa bank_mask:0xf
	v_add_f32_e32 v23, v22, v23
	v_subrev_f32_e32 v22, s3, v26
	v_cndmask_b32_e64 v22, v22, v26, s[24:25]
	v_max_f32_e32 v22, 0xc2a00000, v22
	v_mul_f32_e32 v22, 0x3fb8aa3b, v22
	v_exp_f32_e32 v30, v22
	v_sub_f32_e32 v22, s3, v26
	v_min_f32_e32 v22, 0x42a00000, v22
	v_mul_f32_e32 v22, 0x3fb8aa3b, v22
	v_exp_f32_e32 v22, v22
	v_rcp_f32_e32 v31, v30
	v_mov_b32_dpp v27, v23 row_bcast:31 row_mask:0xc bank_mask:0xf
	v_readlane_b32 s73, v30, 31
	v_add_f32_e32 v26, v23, v27
	v_readlane_b32 s3, v22, 63
	v_mul_f32_e32 v23, s73, v30
	v_cndmask_b32_e64 v27, v23, v30, s[24:25]
	v_rcp_f32_e32 v64, s3
	v_readlane_b32 s3, v26, 31
	v_mul_f32_e32 v70, v102, v27
	v_mul_f32_e32 v27, v18, v31
	v_subrev_f32_e32 v31, s3, v26
	v_sub_f32_e32 v23, s3, v26
	v_cndmask_b32_e64 v26, v31, v26, s[24:25]
	v_min_f32_e32 v23, 0x42a00000, v23
	v_max_f32_e32 v26, 0xc2a00000, v26
	v_mul_f32_e32 v23, 0x3fb8aa3b, v23
	v_mul_f32_e32 v26, 0x3fb8aa3b, v26
	v_exp_f32_e32 v23, v23
	v_exp_f32_e32 v31, v26
	v_mul_f32_e32 v30, v102, v30
	v_cndmask_b32_e64 v30, v30, v27, s[24:25]
	v_pk_mul_f32 v[26:27], v[18:19], v[22:23]
	v_rcp_f32_e32 v18, v31
	v_readlane_b32 s46, v23, 63
	v_readlane_b32 s78, v31, 31
	v_mul_f32_e32 v18, v19, v18
	v_mul_f32_e32 v19, v103, v31
	v_cndmask_b32_e64 v18, v19, v18, s[24:25]
	v_cndmask_b32_e64 v19, 0, 32, vcc
	v_ldexp_f32 v19, v105, v19
	v_log_f32_e32 v19, v19
	v_rcp_f32_e32 v65, s46
	v_mul_f32_e32 v22, s78, v31
	v_cndmask_b32_e64 v22, v22, v31, s[24:25]
	v_mul_f32_e32 v23, 0x3f317217, v19
	v_fma_f32 v23, v19, s5, -v23
	v_fmac_f32_e32 v23, 0x3377d1cf, v19
	v_fmac_f32_e32 v23, 0x3f317217, v19
	v_cmp_lt_f32_e64 s[46:47], |v19|, s53
	v_pk_mul_f32 v[68:69], v[64:65], v[26:27]
	v_cvt_pk_bf16_f32 v26, v26, v27
	v_cndmask_b32_e64 v19, v19, v23, s[46:47]
	v_cndmask_b32_e32 v23, 0, v83, vcc
	v_sub_f32_e32 v19, v19, v23
	v_mov_b32_e32 v23, 0
	v_cmp_gt_f32_e32 vcc, s50, v104
	v_add_f32_dpp v19, v19, v19 row_shr:1 row_mask:0xf bank_mask:0xf bound_ctrl:1
	v_mov_b32_e32 v27, 0
	v_cvt_pk_bf16_f32 v30, v30, v18
	v_add_f32_dpp v19, v19, v19 row_shr:2 row_mask:0xf bank_mask:0xf bound_ctrl:1
	v_cvt_pk_bf16_f32 v18, v68, v69
	v_mul_f32_e32 v22, v103, v22
	v_add_f32_dpp v19, v19, v19 row_shr:4 row_mask:0xf bank_mask:0xf bound_ctrl:1
	v_cvt_pk_bf16_f32 v22, v70, v22
	s_nop 0
	v_add_f32_dpp v19, v19, v19 row_shr:8 row_mask:0xf bank_mask:0xf bound_ctrl:1
	s_nop 1
	v_mov_b32_dpp v23, v19 row_bcast:15 row_mask:0xa bank_mask:0xf
	v_add_f32_e32 v19, v19, v23
	v_cndmask_b32_e64 v23, 0, 32, vcc
	v_ldexp_f32 v23, v104, v23
	v_log_f32_e32 v23, v23
	v_mov_b32_dpp v27, v19 row_bcast:31 row_mask:0xc bank_mask:0xf
	v_add_f32_e32 v19, v19, v27
	v_mul_f32_e32 v27, 0x3f317217, v23
	v_fma_f32 v27, v23, s5, -v27
	v_fmac_f32_e32 v27, 0x3377d1cf, v23
	v_fmac_f32_e32 v27, 0x3f317217, v23
	v_cmp_lt_f32_e64 s[46:47], |v23|, s53
	v_readlane_b32 s3, v19, 31
	s_nop 0
	v_cndmask_b32_e64 v23, v23, v27, s[46:47]
	v_cndmask_b32_e32 v27, 0, v83, vcc
	v_sub_f32_e32 v23, v23, v27
	v_subrev_f32_e32 v31, s3, v19
	v_cndmask_b32_e64 v31, v31, v19, s[24:25]
	v_add_f32_dpp v23, v23, v23 row_shr:1 row_mask:0xf bank_mask:0xf bound_ctrl:1
	v_sub_f32_e32 v19, s3, v19
	v_min_f32_e32 v19, 0x42a00000, v19
	v_add_f32_dpp v23, v23, v23 row_shr:2 row_mask:0xf bank_mask:0xf bound_ctrl:1
	v_mul_f32_e32 v19, 0x3fb8aa3b, v19
	v_mov_b32_e32 v27, 0
	v_add_f32_dpp v23, v23, v23 row_shr:4 row_mask:0xf bank_mask:0xf bound_ctrl:1
	v_exp_f32_e32 v68, v19
	v_max_f32_e32 v31, 0xc2a00000, v31
	v_add_f32_dpp v23, v23, v23 row_shr:8 row_mask:0xf bank_mask:0xf bound_ctrl:1
	v_mul_f32_e32 v31, 0x3fb8aa3b, v31
	v_readlane_b32 s3, v68, 63
	v_mov_b32_dpp v27, v23 row_bcast:15 row_mask:0xa bank_mask:0xf
	v_add_f32_e32 v23, v23, v27
	v_mov_b32_e32 v27, 0
	v_exp_f32_e32 v31, v31
	v_rcp_f32_e32 v66, s3
	v_mov_b32_dpp v27, v23 row_bcast:31 row_mask:0xc bank_mask:0xf
	v_add_f32_e32 v19, v23, v27
	v_rcp_f32_e32 v27, v31
	v_readlane_b32 s3, v19, 31
	v_readlane_b32 s79, v31, 31
	v_cmp_gt_f32_e32 vcc, s50, v101
	v_subrev_f32_e32 v70, s3, v19
	v_sub_f32_e32 v67, s3, v19
	v_cndmask_b32_e64 v19, v70, v19, s[24:25]
	v_max_f32_e32 v19, 0xc2a00000, v19
	v_mul_f32_e32 v19, 0x3fb8aa3b, v19
	v_exp_f32_e32 v19, v19
	v_min_f32_e32 v67, 0x42a00000, v67
	v_mul_f32_e32 v23, s79, v31
	v_mul_f32_e32 v67, 0x3fb8aa3b, v67
	v_cndmask_b32_e64 v23, v23, v31, s[24:25]
	v_exp_f32_e32 v69, v67
	v_mul_f32_e32 v27, v44, v27
	v_mul_f32_e32 v31, v98, v31
	v_cndmask_b32_e64 v27, v31, v27, s[24:25]
	v_rcp_f32_e32 v31, v19
	v_readlane_b32 s88, v19, 31
	v_readlane_b32 s46, v69, 63
	v_pk_mul_f32 v[68:69], v[44:45], v[68:69]
	v_mul_f32_e32 v44, s88, v19
	v_cndmask_b32_e64 v44, v44, v19, s[24:25]
	v_mul_f32_e32 v31, v45, v31
	v_mul_f32_e32 v19, v99, v19
	v_cndmask_b32_e64 v19, v19, v31, s[24:25]
	v_cndmask_b32_e64 v31, 0, 32, vcc
	v_mul_f32_e32 v23, v98, v23
	v_mul_f32_e32 v44, v99, v44
	v_ldexp_f32 v31, v101, v31
	v_cvt_pk_bf16_f32 v23, v23, v44
	v_log_f32_e32 v44, v31
	v_rcp_f32_e32 v67, s46
	v_cvt_pk_bf16_f32 v31, v27, v19
	v_cvt_pk_bf16_f32 v27, v68, v69
	v_mul_f32_e32 v45, 0x3f317217, v44
	v_fma_f32 v45, v44, s5, -v45
	v_fmac_f32_e32 v45, 0x3377d1cf, v44
	v_fmac_f32_e32 v45, 0x3f317217, v44
	v_cmp_lt_f32_e64 s[46:47], |v44|, s53
	v_pk_mul_f32 v[70:71], v[66:67], v[68:69]
	v_mov_b32_e32 v68, 0
	v_cndmask_b32_e64 v44, v44, v45, s[46:47]
	v_cndmask_b32_e32 v45, 0, v83, vcc
	v_sub_f32_e32 v44, v44, v45
	v_mov_b32_e32 v45, 0
	v_cmp_gt_f32_e32 vcc, s50, v100
	v_add_f32_dpp v44, v44, v44 row_shr:1 row_mask:0xf bank_mask:0xf bound_ctrl:1
	v_cvt_pk_bf16_f32 v19, v70, v71
	s_nop 0
	v_add_f32_dpp v44, v44, v44 row_shr:2 row_mask:0xf bank_mask:0xf bound_ctrl:1
	s_nop 1
	v_add_f32_dpp v44, v44, v44 row_shr:4 row_mask:0xf bank_mask:0xf bound_ctrl:1
	s_nop 1
	v_add_f32_dpp v44, v44, v44 row_shr:8 row_mask:0xf bank_mask:0xf bound_ctrl:1
	s_nop 1
	v_mov_b32_dpp v45, v44 row_bcast:15 row_mask:0xa bank_mask:0xf
	v_add_f32_e32 v44, v44, v45
	v_cndmask_b32_e64 v45, 0, 32, vcc
	v_ldexp_f32 v45, v100, v45
	v_log_f32_e32 v45, v45
	v_mov_b32_dpp v68, v44 row_bcast:31 row_mask:0xc bank_mask:0xf
	v_add_f32_e32 v44, v44, v68
	v_mul_f32_e32 v68, 0x3f317217, v45
	v_fma_f32 v68, v45, s5, -v68
	v_fmac_f32_e32 v68, 0x3377d1cf, v45
	v_fmac_f32_e32 v68, 0x3f317217, v45
	v_cmp_lt_f32_e64 s[46:47], |v45|, s53
	v_readlane_b32 s3, v44, 31
	s_nop 0
	v_cndmask_b32_e64 v45, v45, v68, s[46:47]
	v_cndmask_b32_e32 v68, 0, v83, vcc
	v_sub_f32_e32 v45, v45, v68
	s_nop 1
	v_add_f32_dpp v40, v45, v45 row_shr:1 row_mask:0xf bank_mask:0xf bound_ctrl:1
	v_mov_b32_e32 v45, 0
	s_nop 0
	v_add_f32_dpp v40, v40, v40 row_shr:2 row_mask:0xf bank_mask:0xf bound_ctrl:1
	s_nop 1
	v_add_f32_dpp v40, v40, v40 row_shr:4 row_mask:0xf bank_mask:0xf bound_ctrl:1
	s_nop 1
	v_add_f32_dpp v40, v40, v40 row_shr:8 row_mask:0xf bank_mask:0xf bound_ctrl:1
	s_nop 1
	v_mov_b32_dpp v41, v40 row_bcast:15 row_mask:0xa bank_mask:0xf
	v_add_f32_e32 v41, v40, v41
	v_subrev_f32_e32 v40, s3, v44
	v_cndmask_b32_e64 v40, v40, v44, s[24:25]
	v_max_f32_e32 v40, 0xc2a00000, v40
	v_mul_f32_e32 v40, 0x3fb8aa3b, v40
	v_exp_f32_e32 v69, v40
	v_sub_f32_e32 v40, s3, v44
	v_min_f32_e32 v40, 0x42a00000, v40
	v_mul_f32_e32 v40, 0x3fb8aa3b, v40
	v_exp_f32_e32 v40, v40
	v_mov_b32_dpp v45, v41 row_bcast:31 row_mask:0xc bank_mask:0xf
	v_add_f32_e32 v44, v41, v45
	v_readlane_b32 s94, v69, 31
	v_readlane_b32 s3, v40, 63
	v_rcp_f32_e32 v70, v69
	v_mul_f32_e32 v41, s94, v69
	v_rcp_f32_e32 v68, s3
	v_readlane_b32 s3, v44, 31
	v_cndmask_b32_e64 v45, v41, v69, s[24:25]
	v_mul_f32_e32 v70, v36, v70
	v_subrev_f32_e32 v72, s3, v44
	v_sub_f32_e32 v41, s3, v44
	v_cndmask_b32_e64 v44, v72, v44, s[24:25]
	v_min_f32_e32 v41, 0x42a00000, v41
	v_max_f32_e32 v44, 0xc2a00000, v44
	v_mul_f32_e32 v41, 0x3fb8aa3b, v41
	v_mul_f32_e32 v44, 0x3fb8aa3b, v44
	v_exp_f32_e32 v41, v41
	v_exp_f32_e32 v44, v44
	v_mul_f32_e32 v45, v94, v45
	v_mul_f32_e32 v71, v94, v69
	v_readlane_b32 s46, v41, 63
	v_pk_mul_f32 v[40:41], v[36:37], v[40:41]
	v_rcp_f32_e32 v36, v44
	v_readlane_b32 s95, v44, 31
	v_cndmask_b32_e64 v94, v71, v70, s[24:25]
	v_rcp_f32_e32 v69, s46
	v_mul_f32_e32 v72, s95, v44
	v_cndmask_b32_e64 v72, v72, v44, s[24:25]
	v_mul_f32_e32 v72, v95, v72
	v_mul_f32_e32 v36, v37, v36
	v_mul_f32_e32 v37, v95, v44
	v_cndmask_b32_e64 v37, v37, v36, s[24:25]
	v_cvt_pk_bf16_f32 v36, v45, v72
	v_pk_add_f32 v[72:73], v[32:33], 1.0 op_sel_hi:[1,0] neg_lo:[1,0] neg_hi:[1,0]
	v_cvt_pk_bf16_f32 v44, v94, v37
	v_fmac_f32_e32 v97, v46, v72
	v_cmp_gt_f32_e32 vcc, s50, v97
	v_fmac_f32_e32 v96, v47, v73
	v_pk_mul_f32 v[70:71], v[68:69], v[40:41]
	v_cndmask_b32_e64 v32, 0, 32, vcc
	v_ldexp_f32 v32, v97, v32
	v_log_f32_e32 v33, v32
	v_cvt_pk_bf16_f32 v40, v40, v41
	v_mov_b32_e32 v41, 0
	v_pk_add_f32 v[46:47], v[46:47], 1.0 op_sel_hi:[1,0] neg_lo:[1,0] neg_hi:[1,0]
	v_mul_f32_e32 v37, 0x3f317217, v33
	v_fma_f32 v37, v33, s5, -v37
	v_fmac_f32_e32 v37, 0x3377d1cf, v33
	v_fmac_f32_e32 v37, 0x3f317217, v33
	v_cmp_lt_f32_e64 s[46:47], |v33|, s53
	v_pk_mul_f32 v[46:47], v[46:47], v[72:73]
	v_cvt_pk_bf16_f32 v32, v70, v71
	v_cndmask_b32_e64 v33, v33, v37, s[46:47]
	v_cndmask_b32_e32 v37, 0, v83, vcc
	v_sub_f32_e32 v33, v33, v37
	v_mov_b32_e32 v37, 0
	v_cmp_gt_f32_e32 vcc, s50, v96
	v_add_f32_dpp v33, v33, v33 row_shr:1 row_mask:0xf bank_mask:0xf bound_ctrl:1
	s_nop 1
	v_add_f32_dpp v33, v33, v33 row_shr:2 row_mask:0xf bank_mask:0xf bound_ctrl:1
	s_nop 1
	v_add_f32_dpp v33, v33, v33 row_shr:4 row_mask:0xf bank_mask:0xf bound_ctrl:1
	s_nop 1
	v_add_f32_dpp v33, v33, v33 row_shr:8 row_mask:0xf bank_mask:0xf bound_ctrl:1
	s_nop 1
	v_mov_b32_dpp v37, v33 row_bcast:15 row_mask:0xa bank_mask:0xf
	v_add_f32_e32 v33, v33, v37
	v_cndmask_b32_e64 v37, 0, 32, vcc
	v_ldexp_f32 v37, v96, v37
	v_log_f32_e32 v37, v37
	v_mov_b32_dpp v41, v33 row_bcast:31 row_mask:0xc bank_mask:0xf
	v_add_f32_e32 v33, v33, v41
	v_mul_f32_e32 v41, 0x3f317217, v37
	v_fma_f32 v41, v37, s5, -v41
	v_fmac_f32_e32 v41, 0x3377d1cf, v37
	v_fmac_f32_e32 v41, 0x3f317217, v37
	v_cmp_lt_f32_e64 s[46:47], |v37|, s53
	v_readlane_b32 s3, v33, 31
	s_nop 0
	v_cndmask_b32_e64 v37, v37, v41, s[46:47]
	v_cndmask_b32_e32 v41, 0, v83, vcc
	v_subrev_f32_e32 v45, s3, v33
	v_sub_f32_e32 v37, v37, v41
	v_cndmask_b32_e64 v45, v45, v33, s[24:25]
	v_max_f32_e32 v45, 0xc2a00000, v45
	v_add_f32_dpp v37, v37, v37 row_shr:1 row_mask:0xf bank_mask:0xf bound_ctrl:1
	v_sub_f32_e32 v33, s3, v33
	v_mul_f32_e32 v45, 0x3fb8aa3b, v45
	v_add_f32_dpp v37, v37, v37 row_shr:2 row_mask:0xf bank_mask:0xf bound_ctrl:1
	v_min_f32_e32 v33, 0x42a00000, v33
	v_exp_f32_e32 v45, v45
	v_add_f32_dpp v37, v37, v37 row_shr:4 row_mask:0xf bank_mask:0xf bound_ctrl:1
	v_mul_f32_e32 v33, 0x3fb8aa3b, v33
	v_mov_b32_e32 v41, 0
	v_add_f32_dpp v37, v37, v37 row_shr:8 row_mask:0xf bank_mask:0xf bound_ctrl:1
	v_exp_f32_e32 v72, v33
	v_readlane_b32 s3, v45, 31
	v_mov_b32_dpp v41, v37 row_bcast:15 row_mask:0xa bank_mask:0xf
	v_add_f32_e32 v37, v37, v41
	v_mov_b32_e32 v41, 0
	v_readlane_b32 s46, v72, 63
	v_cmp_gt_f32_e32 vcc, s50, v93
	v_mov_b32_dpp v41, v37 row_bcast:31 row_mask:0xc bank_mask:0xf
	v_add_f32_e32 v33, v37, v41
	v_mul_f32_e32 v37, s3, v45
	v_rcp_f32_e32 v70, s46
	v_cndmask_b32_e64 v37, v37, v45, s[24:25]
	v_readlane_b32 s46, v33, 31
	v_rcp_f32_e32 v41, v45
	v_mul_f32_e32 v37, v90, v37
	v_mul_f32_e32 v45, v90, v45
	v_subrev_f32_e32 v90, s46, v33
	v_sub_f32_e32 v71, s46, v33
	v_cndmask_b32_e64 v33, v90, v33, s[24:25]
	v_max_f32_e32 v33, 0xc2a00000, v33
	v_mul_f32_e32 v33, 0x3fb8aa3b, v33
	v_exp_f32_e32 v33, v33
	v_min_f32_e32 v71, 0x42a00000, v71
	v_mul_f32_e32 v71, 0x3fb8aa3b, v71
	v_exp_f32_e32 v73, v71
	v_mul_f32_e32 v41, v46, v41
	v_cndmask_b32_e64 v41, v45, v41, s[24:25]
	v_rcp_f32_e32 v45, v33
	v_readlane_b32 s80, v33, 31
	v_readlane_b32 s47, v73, 63
	v_pk_mul_f32 v[72:73], v[46:47], v[72:73]
	v_mul_f32_e32 v46, s80, v33
	v_cndmask_b32_e64 v46, v46, v33, s[24:25]
	v_mul_f32_e32 v45, v47, v45
	v_mul_f32_e32 v33, v91, v33
	v_cndmask_b32_e64 v33, v33, v45, s[24:25]
	v_cndmask_b32_e64 v45, 0, 32, vcc
	v_mul_f32_e32 v46, v91, v46
	v_ldexp_f32 v45, v93, v45
	v_cvt_pk_bf16_f32 v37, v37, v46
	v_log_f32_e32 v46, v45
	v_rcp_f32_e32 v71, s47
	v_cvt_pk_bf16_f32 v45, v41, v33
	v_cvt_pk_bf16_f32 v41, v72, v73
	v_mul_f32_e32 v47, 0x3f317217, v46
	v_fma_f32 v47, v46, s5, -v47
	v_fmac_f32_e32 v47, 0x3377d1cf, v46
	v_fmac_f32_e32 v47, 0x3f317217, v46
	v_cmp_lt_f32_e64 s[46:47], |v46|, s53
	v_pk_mul_f32 v[94:95], v[70:71], v[72:73]
	v_mov_b32_e32 v72, 0
	v_cndmask_b32_e64 v46, v46, v47, s[46:47]
	v_cndmask_b32_e32 v47, 0, v83, vcc
	v_sub_f32_e32 v46, v46, v47
	v_mov_b32_e32 v47, 0
	v_cmp_gt_f32_e32 vcc, s50, v92
	v_add_f32_dpp v46, v46, v46 row_shr:1 row_mask:0xf bank_mask:0xf bound_ctrl:1
	v_cvt_pk_bf16_f32 v33, v94, v95
	s_nop 0
	v_add_f32_dpp v46, v46, v46 row_shr:2 row_mask:0xf bank_mask:0xf bound_ctrl:1
	s_nop 1
	v_add_f32_dpp v46, v46, v46 row_shr:4 row_mask:0xf bank_mask:0xf bound_ctrl:1
	s_nop 1
	v_add_f32_dpp v46, v46, v46 row_shr:8 row_mask:0xf bank_mask:0xf bound_ctrl:1
	s_nop 1
	v_mov_b32_dpp v47, v46 row_bcast:15 row_mask:0xa bank_mask:0xf
	v_add_f32_e32 v46, v46, v47
	v_cndmask_b32_e64 v47, 0, 32, vcc
	v_ldexp_f32 v47, v92, v47
	v_log_f32_e32 v47, v47
	v_mov_b32_dpp v72, v46 row_bcast:31 row_mask:0xc bank_mask:0xf
	v_add_f32_e32 v46, v46, v72
	v_mul_f32_e32 v72, 0x3f317217, v47
	v_fma_f32 v72, v47, s5, -v72
	v_fmac_f32_e32 v72, 0x3377d1cf, v47
	v_fmac_f32_e32 v72, 0x3f317217, v47
	v_cmp_lt_f32_e64 s[46:47], |v47|, s53
	s_nop 1
	v_cndmask_b32_e64 v47, v47, v72, s[46:47]
	v_cndmask_b32_e32 v72, 0, v83, vcc
	v_sub_f32_e32 v47, v47, v72
	v_readlane_b32 s46, v46, 31
	s_nop 0
	v_add_f32_dpp v42, v47, v47 row_shr:1 row_mask:0xf bank_mask:0xf bound_ctrl:1
	v_mov_b32_e32 v47, 0
	s_nop 0
	v_add_f32_dpp v42, v42, v42 row_shr:2 row_mask:0xf bank_mask:0xf bound_ctrl:1
	s_nop 1
	v_add_f32_dpp v42, v42, v42 row_shr:4 row_mask:0xf bank_mask:0xf bound_ctrl:1
	s_nop 1
	v_add_f32_dpp v42, v42, v42 row_shr:8 row_mask:0xf bank_mask:0xf bound_ctrl:1
	s_nop 1
	v_mov_b32_dpp v43, v42 row_bcast:15 row_mask:0xa bank_mask:0xf
	v_add_f32_e32 v43, v42, v43
	v_subrev_f32_e32 v42, s46, v46
	v_cndmask_b32_e64 v42, v42, v46, s[24:25]
	v_max_f32_e32 v42, 0xc2a00000, v42
	v_mul_f32_e32 v42, 0x3fb8aa3b, v42
	v_exp_f32_e32 v73, v42
	v_sub_f32_e32 v42, s46, v46
	v_min_f32_e32 v42, 0x42a00000, v42
	v_mul_f32_e32 v42, 0x3fb8aa3b, v42
	v_exp_f32_e32 v42, v42
	v_mov_b32_dpp v47, v43 row_bcast:31 row_mask:0xc bank_mask:0xf
	v_add_f32_e32 v46, v43, v47
	v_readlane_b32 s84, v73, 31
	v_readlane_b32 s46, v42, 63
	v_rcp_f32_e32 v90, v73
	v_mul_f32_e32 v43, s84, v73
	v_rcp_f32_e32 v72, s46
	v_readlane_b32 s46, v46, 31
	v_cndmask_b32_e64 v47, v43, v73, s[24:25]
	v_mul_f32_e32 v90, v38, v90
	v_subrev_f32_e32 v91, s46, v46
	v_sub_f32_e32 v43, s46, v46
	v_cndmask_b32_e64 v46, v91, v46, s[24:25]
	v_min_f32_e32 v43, 0x42a00000, v43
	v_max_f32_e32 v46, 0xc2a00000, v46
	v_mul_f32_e32 v43, 0x3fb8aa3b, v43
	v_mul_f32_e32 v46, 0x3fb8aa3b, v46
	v_exp_f32_e32 v43, v43
	v_exp_f32_e32 v46, v46
	v_mul_f32_e32 v47, v86, v47
	v_mul_f32_e32 v86, v86, v73
	v_readlane_b32 s47, v43, 63
	v_pk_mul_f32 v[42:43], v[38:39], v[42:43]
	v_rcp_f32_e32 v38, v46
	v_readlane_b32 s85, v46, 31
	v_cndmask_b32_e64 v92, v86, v90, s[24:25]
	v_rcp_f32_e32 v73, s47
	v_mul_f32_e32 v86, s85, v46
	v_cndmask_b32_e64 v86, v86, v46, s[24:25]
	v_mul_f32_e32 v86, v87, v86
	v_mul_f32_e32 v38, v39, v38
	v_mul_f32_e32 v39, v87, v46
	v_cndmask_b32_e64 v39, v39, v38, s[24:25]
	v_cvt_pk_bf16_f32 v38, v47, v86
	v_pk_add_f32 v[86:87], v[34:35], 1.0 op_sel_hi:[1,0] neg_lo:[1,0] neg_hi:[1,0]
	v_cvt_pk_bf16_f32 v46, v92, v39
	v_fmac_f32_e32 v88, v60, v86
	v_cmp_gt_f32_e32 vcc, s50, v88
	v_fmac_f32_e32 v89, v61, v87
	v_pk_mul_f32 v[90:91], v[72:73], v[42:43]
	v_cndmask_b32_e64 v34, 0, 32, vcc
	v_ldexp_f32 v34, v88, v34
	v_log_f32_e32 v35, v34
	v_cvt_pk_bf16_f32 v42, v42, v43
	v_mov_b32_e32 v43, 0
	v_pk_add_f32 v[60:61], v[60:61], 1.0 op_sel_hi:[1,0] neg_lo:[1,0] neg_hi:[1,0]
	v_mul_f32_e32 v39, 0x3f317217, v35
	v_fma_f32 v39, v35, s5, -v39
	v_fmac_f32_e32 v39, 0x3377d1cf, v35
	v_fmac_f32_e32 v39, 0x3f317217, v35
	v_cmp_lt_f32_e64 s[46:47], |v35|, s53
	v_pk_mul_f32 v[86:87], v[60:61], v[86:87]
	v_cvt_pk_bf16_f32 v34, v90, v91
	v_cndmask_b32_e64 v35, v35, v39, s[46:47]
	v_cndmask_b32_e32 v39, 0, v83, vcc
	v_sub_f32_e32 v35, v35, v39
	v_mov_b32_e32 v39, 0
	v_cmp_gt_f32_e32 vcc, s50, v89
	v_add_f32_dpp v35, v35, v35 row_shr:1 row_mask:0xf bank_mask:0xf bound_ctrl:1
	s_nop 1
	v_add_f32_dpp v35, v35, v35 row_shr:2 row_mask:0xf bank_mask:0xf bound_ctrl:1
	s_nop 1
	v_add_f32_dpp v35, v35, v35 row_shr:4 row_mask:0xf bank_mask:0xf bound_ctrl:1
	s_nop 1
	v_add_f32_dpp v35, v35, v35 row_shr:8 row_mask:0xf bank_mask:0xf bound_ctrl:1
	s_nop 1
	v_mov_b32_dpp v39, v35 row_bcast:15 row_mask:0xa bank_mask:0xf
	v_add_f32_e32 v35, v35, v39
	v_cndmask_b32_e64 v39, 0, 32, vcc
	v_ldexp_f32 v39, v89, v39
	v_log_f32_e32 v39, v39
	v_mov_b32_dpp v43, v35 row_bcast:31 row_mask:0xc bank_mask:0xf
	v_add_f32_e32 v35, v35, v43
	v_mul_f32_e32 v43, 0x3f317217, v39
	v_fma_f32 v43, v39, s5, -v43
	v_fmac_f32_e32 v43, 0x3377d1cf, v39
	v_fmac_f32_e32 v43, 0x3f317217, v39
	v_cmp_lt_f32_e64 s[46:47], |v39|, s53
	s_nop 1
	v_cndmask_b32_e64 v39, v39, v43, s[46:47]
	v_readlane_b32 s46, v35, 31
	v_cndmask_b32_e32 v43, 0, v83, vcc
	v_sub_f32_e32 v39, v39, v43
	v_subrev_f32_e32 v47, s46, v35
	v_cndmask_b32_e64 v47, v47, v35, s[24:25]
	v_add_f32_dpp v39, v39, v39 row_shr:1 row_mask:0xf bank_mask:0xf bound_ctrl:1
	v_max_f32_e32 v47, 0xc2a00000, v47
	v_sub_f32_e32 v35, s46, v35
	v_add_f32_dpp v39, v39, v39 row_shr:2 row_mask:0xf bank_mask:0xf bound_ctrl:1
	v_mul_f32_e32 v47, 0x3fb8aa3b, v47
	v_min_f32_e32 v35, 0x42a00000, v35
	v_add_f32_dpp v39, v39, v39 row_shr:4 row_mask:0xf bank_mask:0xf bound_ctrl:1
	v_exp_f32_e32 v47, v47
	v_mul_f32_e32 v35, 0x3fb8aa3b, v35
	v_add_f32_dpp v39, v39, v39 row_shr:8 row_mask:0xf bank_mask:0xf bound_ctrl:1
	v_mov_b32_e32 v43, 0
	v_exp_f32_e32 v88, v35
	v_readlane_b32 s86, v47, 31
	v_mov_b32_dpp v43, v39 row_bcast:15 row_mask:0xa bank_mask:0xf
	v_add_f32_e32 v39, v39, v43
	v_mov_b32_e32 v43, 0
	v_readlane_b32 s46, v88, 63
	s_nop 0
	v_mov_b32_dpp v43, v39 row_bcast:31 row_mask:0xc bank_mask:0xf
	v_add_f32_e32 v35, v39, v43
	v_mul_f32_e32 v39, s86, v47
	v_rcp_f32_e32 v60, s46
	v_cndmask_b32_e64 v39, v39, v47, s[24:25]
	v_readlane_b32 s46, v35, 31
	v_rcp_f32_e32 v43, v47
	v_mul_f32_e32 v39, v84, v39
	v_mul_f32_e32 v47, v84, v47
	v_subrev_f32_e32 v84, s46, v35
	v_sub_f32_e32 v61, s46, v35
	v_cndmask_b32_e64 v35, v84, v35, s[24:25]
	v_min_f32_e32 v61, 0x42a00000, v61
	v_max_f32_e32 v35, 0xc2a00000, v35
	v_mul_f32_e32 v61, 0x3fb8aa3b, v61
	v_mul_f32_e32 v35, 0x3fb8aa3b, v35
	v_exp_f32_e32 v89, v61
	v_exp_f32_e32 v35, v35
	v_mul_f32_e32 v43, v86, v43
	v_cndmask_b32_e64 v43, v47, v43, s[24:25]
	v_readlane_b32 s47, v89, 63
	v_rcp_f32_e32 v47, v35
	s_and_b32 s46, s55, 0xfffffe00
	v_rcp_f32_e32 v61, s47
	s_or_b32 s46, s46, s97
	v_readlane_b32 s87, v35, 31
	s_or_b32 s46, s46, s56
	s_mul_hi_i32 s47, s46, 0x10200
	v_mul_f32_e32 v84, s87, v35
	s_mul_i32 s46, s46, 0x10200
	v_readlane_b32 s55, v250, 13
	v_pk_mul_f32 v[88:89], v[86:87], v[88:89]
	v_cndmask_b32_e64 v84, v84, v35, s[24:25]
	v_mul_f32_e32 v47, v87, v47
	v_mul_f32_e32 v35, v85, v35
	s_add_u32 s46, s55, s46
	v_readlane_b32 s55, v250, 12
	v_pk_mul_f32 v[90:91], v[60:61], v[88:89]
	v_mul_f32_e32 v84, v85, v84
	v_cndmask_b32_e64 v35, v35, v47, s[24:25]
	s_addc_u32 s47, s55, s47
	v_cvt_pk_bf16_f32 v39, v39, v84
	v_cvt_pk_bf16_f32 v47, v43, v35
	v_cvt_pk_bf16_f32 v43, v88, v89
	v_cvt_pk_bf16_f32 v35, v90, v91
	ds_write_b128 v75, v[20:23]
	ds_write_b128 v75, v[28:31] offset:17408
	ds_write_b128 v75, v[24:27] offset:34816
	ds_write_b128 v75, v[16:19] offset:52224
	ds_write_b128 v75, v[36:39] offset:16
	ds_write_b128 v75, v[44:47] offset:17424
	ds_write_b128 v75, v[40:43] offset:34832
	ds_write_b128 v75, v[32:35] offset:52240
	s_and_saveexec_b64 s[76:77], s[26:27]
	s_cbranch_execz .LBB0_2112
	v_mul_f32_e32 v30, s68, v58
	v_mul_f32_e32 v29, s69, v59
	v_cndmask_b32_e64 v30, 0, v30, s[6:7]
	v_mul_f32_e32 v28, s70, v62
	v_cndmask_b32_e64 v29, v30, v29, s[8:9]
	v_mul_f32_e32 v27, s71, v63
	v_cndmask_b32_e64 v28, v29, v28, s[10:11]
	v_mul_f32_e32 v26, s73, v64
	v_cndmask_b32_e64 v27, v28, v27, s[12:13]
	v_mul_f32_e32 v25, s78, v65
	v_cndmask_b32_e64 v26, v27, v26, s[14:15]
	v_mul_f32_e32 v24, s79, v66
	v_cndmask_b32_e64 v25, v26, v25, s[16:17]
	v_mul_f32_e32 v23, s88, v67
	v_cndmask_b32_e64 v24, v25, v24, s[18:19]
	v_mul_f32_e32 v22, s94, v68
	v_cndmask_b32_e64 v23, v24, v23, s[20:21]
	v_mul_f32_e32 v21, s95, v69
	v_cndmask_b32_e64 v22, v23, v22, s[42:43]
	v_mul_f32_e32 v20, s3, v70
	v_cndmask_b32_e64 v21, v22, v21, s[40:41]
	v_mul_f32_e32 v19, s80, v71
	v_cndmask_b32_e64 v20, v21, v20, s[38:39]
	v_mul_f32_e32 v18, s84, v72
	v_cndmask_b32_e64 v19, v20, v19, s[36:37]
	v_mul_f32_e32 v17, s85, v73
	v_cndmask_b32_e64 v18, v19, v18, s[34:35]
	v_mul_f32_e32 v16, s86, v60
	v_cndmask_b32_e64 v17, v18, v17, s[30:31]
	v_cndmask_b32_e64 v16, v17, v16, s[28:29]
	v_mul_f32_e32 v17, s87, v61
	v_cndmask_b32_e64 v18, v16, v17, s[44:45]
	v_lshl_add_u64 v[16:17], v[56:57], 2, s[46:47]
	v_add_co_u32_e32 v16, vcc, 0x10000, v16
	s_nop 1
	v_addc_co_u32_e32 v17, vcc, 0, v17, vcc
	global_store_dword v[16:17], v18, off nt
	s_branch .LBB0_2112

.LBB0_2118:
	s_or_b64 exec, exec, s[28:29]
	s_waitcnt lgkmcnt(0)
	s_barrier
	ds_read_b128 v[24:27], v203
	ds_read_b128 v[28:31], v203 offset:9216
	v_lshl_add_u64 v[32:33], v[186:187], 4, s[26:27]
	s_addk_i32 s33, 0x100
	v_mov_b64_e32 v[42:43], v[22:23]
	s_waitcnt lgkmcnt(1)
	global_store_dwordx4 v[32:33], v[24:27], off nt
	v_mov_b64_e32 v[38:39], v[18:19]
	s_cmpk_lg_i32 s33, 0x800
	v_add_co_u32_e32 v24, vcc, 0x2000, v32
	v_mov_b64_e32 v[40:41], v[20:21]
	s_nop 0
	v_addc_co_u32_e32 v25, vcc, 0, v33, vcc
	s_waitcnt lgkmcnt(0)
	global_store_dwordx4 v[24:25], v[28:31], off nt
	ds_read_b128 v[24:27], v203 offset:18432
	ds_read_b128 v[28:31], v203 offset:27648
	v_add_co_u32_e32 v34, vcc, 0x4000, v32
	v_mov_b64_e32 v[36:37], v[16:17]
	s_nop 0
	v_addc_co_u32_e32 v35, vcc, 0, v33, vcc
	s_waitcnt lgkmcnt(1)
	global_store_dwordx4 v[34:35], v[24:27], off nt
	s_nop 1
	v_add_co_u32_e32 v24, vcc, 0x6000, v32
	s_nop 1
	v_addc_co_u32_e32 v25, vcc, 0, v33, vcc
	s_waitcnt lgkmcnt(0)
	global_store_dwordx4 v[24:25], v[28:31], off nt
	s_waitcnt lgkmcnt(0)
	s_barrier
	v_mov_b64_e32 v[34:35], v[14:15]
	v_mov_b64_e32 v[26:27], v[10:11]
	v_mov_b64_e32 v[32:33], v[12:13]
	v_mov_b64_e32 v[24:25], v[8:9]
	s_cbranch_scc0 .LBB0_2123

.LBB0_2121:
	s_bfe_u32 s35, s34, 0x20007
	s_lshl_b32 s36, s35, 8
	s_or_b32 s36, s36, s54
	s_waitcnt lgkmcnt(0)
	s_barrier
	v_mov_b32_e32 v28, s36
	s_waitcnt lgkmcnt(0)
	global_load_dwordx4 v[116:119], v28, s[26:27] offset:1024
	s_add_u32 s28, s28, s36
	s_addc_u32 s29, s29, 0
	s_add_u32 s36, s28, 0x4000
	s_addc_u32 s37, s29, 0
	global_load_dwordx4 v[120:123], v198, s[28:29]
	global_load_dwordx4 v[124:127], v199, s[28:29] offset:2048
	global_load_dwordx4 v[128:131], v199, s[28:29] offset:3072
	global_load_dwordx4 v[132:135], v200, s[28:29]
	global_load_dwordx4 v[136:139], v200, s[28:29] offset:1024
	global_load_dwordx4 v[140:143], v200, s[28:29] offset:2048
	global_load_dwordx4 v[144:147], v200, s[28:29] offset:3072
	global_load_dwordx4 v[148:151], v201, s[28:29]
	global_load_dwordx4 v[152:155], v201, s[28:29] offset:1024
	global_load_dwordx4 v[156:159], v201, s[28:29] offset:2048
	global_load_dwordx4 v[160:163], v201, s[28:29] offset:3072
	global_load_dwordx4 v[180:183], v197, s[36:37] offset:1024
	global_load_dwordx4 v[176:179], v197, s[36:37] offset:2048
	global_load_dwordx4 v[172:175], v197, s[36:37] offset:3072
	global_load_dwordx4 v[168:171], v199, s[28:29]
	global_load_dwordx4 v[164:167], v199, s[28:29] offset:1024
	global_load_dwordx4 v[48:51], v28, s[26:27] offset:1040
	s_add_u32 s26, s28, 0x5000
	s_addc_u32 s27, s29, 0
	ds_read_b128 v[44:47], v195
	global_load_dwordx4 v[60:63], v197, s[36:37] offset:16
	global_load_dwordx4 v[56:59], v197, s[36:37] offset:1040
	global_load_dwordx4 v[52:55], v197, s[36:37] offset:2064
	ds_read_b128 v[28:31], v195 offset:9216
	global_load_dwordx4 v[68:71], v197, s[36:37] offset:3088
	global_load_dwordx4 v[64:67], v197, s[26:27] offset:16
	s_add_u32 s26, s28, 0x5400
	s_addc_u32 s27, s29, 0
	s_add_u32 s36, s28, 0x5800
	s_addc_u32 s37, s29, 0
	global_load_dwordx4 v[72:75], v197, s[26:27] offset:16
	global_load_dwordx4 v[76:79], v197, s[36:37] offset:16
	s_add_u32 s26, s28, 0x5c00
	s_addc_u32 s27, s29, 0
	s_add_u32 s36, s28, 0x6000
	s_addc_u32 s37, s29, 0
	global_load_dwordx4 v[88:91], v197, s[26:27] offset:16
	global_load_dwordx4 v[80:83], v197, s[36:37] offset:16
	s_add_u32 s26, s28, 0x6400
	s_addc_u32 s27, s29, 0
	s_add_u32 s36, s28, 0x6800
	s_addc_u32 s37, s29, 0
	global_load_dwordx4 v[100:103], v197, s[26:27] offset:16
	global_load_dwordx4 v[84:87], v197, s[36:37] offset:16
	s_add_u32 s26, s28, 0x6c00
	s_addc_u32 s27, s29, 0
	s_add_u32 s36, s28, 0x7000
	s_addc_u32 s37, s29, 0
	global_load_dwordx4 v[104:107], v197, s[26:27] offset:16
	global_load_dwordx4 v[92:95], v197, s[36:37] offset:16
	s_add_u32 s26, s28, 0x7400
	s_addc_u32 s27, s29, 0
	s_add_u32 s36, s28, 0x7800
	s_addc_u32 s37, s29, 0
	s_add_u32 s28, s28, 0x7c00
	s_addc_u32 s29, s29, 0
	global_load_dwordx4 v[96:99], v197, s[28:29] offset:16
	s_waitcnt lgkmcnt(1)
	v_lshlrev_b32_e32 v207, 16, v44
	v_and_b32_e32 v44, 0xffff0000, v44
	v_mul_f32_e32 v44, 0x3e000000, v44
	s_waitcnt vmcnt(29)
	v_mov_b32_e32 v108, v124
	s_waitcnt vmcnt(28)
	v_mov_b32_e32 v109, v128
	v_pk_mul_f32 v[108:109], v[38:39], v[108:109]
	s_waitcnt vmcnt(27)
	v_mov_b32_e32 v110, v132
	v_fma_f32 v116, v40, v120, v116
	s_waitcnt vmcnt(19)
	v_fmac_f32_e32 v116, v41, v180
	s_waitcnt vmcnt(18)
	v_fmac_f32_e32 v116, v42, v176
	s_waitcnt vmcnt(17)
	v_fmac_f32_e32 v116, v43, v172
	s_waitcnt vmcnt(16)
	v_fmac_f32_e32 v116, v36, v168
	s_waitcnt vmcnt(15)
	v_fmac_f32_e32 v116, v37, v164
	v_mov_b32_e32 v111, v136
	v_add_f32_e32 v108, v116, v108
	v_pk_mul_f32 v[110:111], v[32:33], v[110:111]
	v_add_f32_e32 v108, v108, v109
	v_mov_b32_e32 v112, v140
	v_mov_b32_e32 v113, v144
	v_add_f32_e32 v108, v108, v110
	v_pk_mul_f32 v[112:113], v[34:35], v[112:113]
	v_add_f32_e32 v108, v108, v111
	v_mov_b32_e32 v114, v148
	v_mov_b32_e32 v115, v152
	v_add_f32_e32 v108, v108, v112
	v_pk_mul_f32 v[114:115], v[24:25], v[114:115]
	v_add_f32_e32 v108, v108, v113
	v_mov_b32_e32 v208, v156
	v_mov_b32_e32 v209, v160
	v_add_f32_e32 v108, v108, v114
	v_pk_mul_f32 v[208:209], v[26:27], v[208:209]
	v_add_f32_e32 v108, v108, v115
	v_add_f32_e32 v108, v108, v208
	v_add_f32_e32 v116, v108, v209
	v_mul_f32_e64 v108, |v116|, s2
	v_exp_f32_e32 v120, v108
	v_min_f32_e32 v116, 0, v116
	v_fma_f32 v117, v40, v121, v117
	v_fmac_f32_e32 v117, v41, v181
	v_add_f32_e32 v124, 1.0, v120
	v_add_f32_e32 v128, -1.0, v124
	v_sub_f32_e32 v132, v128, v124
	v_sub_f32_e32 v128, v120, v128
	v_add_f32_e32 v132, 1.0, v132
	v_add_f32_e32 v128, v128, v132
	v_frexp_mant_f32_e32 v132, v124
	v_cvt_f64_f32_e32 v[208:209], v124
	v_frexp_exp_i32_f64_e32 v136, v[208:209]
	v_cmp_gt_f32_e32 vcc, s4, v132
	v_fmac_f32_e32 v117, v42, v177
	v_fmac_f32_e32 v117, v43, v173
	v_subbrev_co_u32_e32 v132, vcc, 0, v136, vcc
	v_sub_u32_e32 v136, 0, v132
	v_ldexp_f32 v124, v124, v136
	v_ldexp_f32 v128, v128, v136
	v_add_f32_e32 v136, -1.0, v124
	v_add_f32_e32 v148, 1.0, v124
	v_add_f32_e32 v140, 1.0, v136
	v_add_f32_e32 v152, -1.0, v148
	v_sub_f32_e32 v140, v124, v140
	v_sub_f32_e32 v124, v124, v152
	v_add_f32_e32 v124, v128, v124
	v_add_f32_e32 v140, v128, v140
	v_add_f32_e32 v128, v148, v124
	v_rcp_f32_e32 v152, v128
	v_add_f32_e32 v144, v136, v140
	v_sub_f32_e32 v136, v144, v136
	v_sub_f32_e32 v136, v140, v136
	v_sub_f32_e32 v140, v128, v148
	v_sub_f32_e32 v124, v124, v140
	v_mul_f32_e32 v140, v144, v152
	v_mul_f32_e32 v148, v128, v140
	v_fma_f32 v156, v140, v128, -v148
	v_fmac_f32_e32 v156, v140, v124
	v_add_f32_e32 v160, v148, v156
	v_sub_f32_e32 v164, v144, v160
	v_sub_f32_e32 v144, v144, v164
	v_sub_f32_e32 v148, v160, v148
	v_sub_f32_e32 v144, v144, v160
	v_add_f32_e32 v136, v136, v144
	v_sub_f32_e32 v144, v148, v156
	v_add_f32_e32 v136, v144, v136
	v_add_f32_e32 v144, v164, v136
	v_mul_f32_e32 v148, v152, v144
	v_mul_f32_e32 v156, v128, v148
	v_fma_f32 v128, v148, v128, -v156
	v_fmac_f32_e32 v128, v148, v124
	v_sub_f32_e32 v124, v164, v144
	v_add_f32_e32 v124, v136, v124
	v_add_f32_e32 v136, v156, v128
	v_sub_f32_e32 v160, v144, v136
	v_sub_f32_e32 v144, v144, v160
	v_sub_f32_e32 v156, v136, v156
	v_sub_f32_e32 v136, v144, v136
	v_add_f32_e32 v124, v124, v136
	v_sub_f32_e32 v128, v156, v128
	v_cvt_f32_i32_e32 v132, v132
	v_add_f32_e32 v124, v128, v124
	v_add_f32_e32 v128, v140, v148
	v_add_f32_e32 v124, v160, v124
	v_sub_f32_e32 v136, v128, v140
	v_mul_f32_e32 v124, v152, v124
	v_sub_f32_e32 v136, v148, v136
	v_add_f32_e32 v124, v136, v124
	v_mul_f32_e32 v148, 0x3f317218, v132
	v_add_f32_e32 v136, v128, v124
	v_fma_f32 v152, v132, s5, -v148
	v_mul_f32_e32 v140, v136, v136
	v_fmac_f32_e32 v152, 0xb102e308, v132
	v_sub_f32_e32 v128, v136, v128
	v_fmamk_f32 v144, v140, 0x3e9b6dac, v202
	v_sub_f32_e32 v124, v124, v128
	v_add_f32_e32 v128, v148, v152
	v_fmaak_f32 v144, v140, v144, 0x3f2aaada
	v_sub_f32_e32 v132, v128, v148
	v_ldexp_f32 v148, v136, 1
	v_mul_f32_e32 v136, v136, v140
	v_mul_f32_e32 v136, v136, v144
	v_add_f32_e32 v140, v148, v136
	v_sub_f32_e32 v144, v140, v148
	v_ldexp_f32 v124, v124, 1
	v_sub_f32_e32 v136, v136, v144
	v_add_f32_e32 v124, v124, v136
	v_add_f32_e32 v136, v140, v124
	v_sub_f32_e32 v140, v136, v140
	v_sub_f32_e32 v124, v124, v140
	v_add_f32_e32 v140, v128, v136
	v_sub_f32_e32 v144, v140, v128
	v_sub_f32_e32 v148, v140, v144
	v_sub_f32_e32 v132, v152, v132
	v_sub_f32_e32 v128, v128, v148
	v_sub_f32_e32 v136, v136, v144
	v_add_f32_e32 v128, v136, v128
	v_add_f32_e32 v136, v132, v124
	v_sub_f32_e32 v144, v136, v132
	v_sub_f32_e32 v148, v136, v144
	v_sub_f32_e32 v132, v132, v148
	v_sub_f32_e32 v124, v124, v144
	v_add_f32_e32 v128, v136, v128
	v_add_f32_e32 v124, v124, v132
	v_add_f32_e32 v132, v140, v128
	v_sub_f32_e32 v136, v132, v140
	v_sub_f32_e32 v128, v128, v136
	v_add_f32_e32 v124, v124, v128
	v_add_f32_e32 v124, v132, v124
	v_cmp_neq_f32_e32 vcc, s30, v120
	v_fmac_f32_e32 v117, v36, v169
	v_mov_b32_e32 v128, v125
	v_cndmask_b32_e32 v124, v204, v124, vcc
	v_cmp_ngt_f32_e32 vcc, -1.0, v120
	v_fmac_f32_e32 v117, v37, v165
	v_mov_b32_e32 v136, v133
	v_cndmask_b32_e32 v124, v205, v124, vcc
	v_cmp_neq_f32_e32 vcc, -1.0, v120
	v_mov_b32_e32 v144, v141
	v_mov_b32_e32 v152, v149
	v_cndmask_b32_e32 v124, v206, v124, vcc
	v_cmp_lt_f32_e64 vcc, |v120|, s31
	v_mov_b32_e32 v160, v157
	v_mov_b32_e32 v132, 0
	v_cndmask_b32_e32 v120, v124, v120, vcc
	v_sub_f32_e32 v120, v116, v120
	v_mul_f32_e32 v124, 0x3d800000, v120
	v_fma_f32 v118, v40, v122, v118
	v_fmac_f32_e32 v118, v41, v182
	v_mov_b32_dpp v124, v124 row_shr:1 row_mask:0xf bank_mask:0xf bound_ctrl:1
	v_fmac_f32_e32 v124, 0x3d800000, v120
	v_fmac_f32_e32 v118, v42, v178
	v_fmac_f32_e32 v118, v43, v174
	v_add_f32_dpp v120, v124, v124 row_shr:2 row_mask:0xf bank_mask:0xf bound_ctrl:1
	v_mov_b32_e32 v124, 0
	v_fmac_f32_e32 v118, v36, v170
	v_add_f32_dpp v120, v120, v120 row_shr:4 row_mask:0xf bank_mask:0xf bound_ctrl:1
	v_fmac_f32_e32 v118, v37, v166
	v_fmac_f32_e32 v119, v40, v123
	v_add_f32_dpp v120, v120, v120 row_shr:8 row_mask:0xf bank_mask:0xf bound_ctrl:1
	v_fmac_f32_e32 v119, v41, v183
	v_fmac_f32_e32 v119, v42, v179
	v_mov_b32_dpp v124, v120 row_bcast:15 row_mask:0xa bank_mask:0xf
	v_add_f32_e32 v124, v120, v124
	v_pk_mul_f32 v[120:121], v[38:39], v[128:129]
	v_fmac_f32_e32 v119, v43, v175
	v_add_f32_e32 v117, v117, v120
	v_add_f32_e32 v117, v117, v121
	v_pk_mul_f32 v[120:121], v[32:33], v[136:137]
	v_mov_b32_dpp v132, v124 row_bcast:31 row_mask:0xc bank_mask:0xf
	v_add_f32_e32 v117, v117, v120
	v_add_f32_e32 v117, v117, v121
	v_pk_mul_f32 v[120:121], v[34:35], v[144:145]
	v_fmac_f32_e32 v119, v36, v171
	v_add_f32_e32 v117, v117, v120
	v_add_f32_e32 v117, v117, v121
	v_pk_mul_f32 v[120:121], v[24:25], v[152:153]
	v_fmac_f32_e32 v119, v37, v167
	v_add_f32_e32 v117, v117, v120
	v_add_f32_e32 v117, v117, v121
	v_pk_mul_f32 v[120:121], v[26:27], v[160:161]
	global_load_dwordx4 v[112:115], v197, s[26:27] offset:16
	global_load_dwordx4 v[108:111], v197, s[36:37] offset:16
	v_add_f32_e32 v117, v117, v120
	v_add_f32_e32 v120, v117, v121
	v_mul_f32_e64 v117, |v120|, s2
	v_exp_f32_e32 v125, v117
	v_add_f32_e32 v117, v124, v132
	v_min_f32_e32 v124, 0, v120
	s_waitcnt vmcnt(15)
	v_fma_f32 v48, v40, v60, v48
	v_add_f32_e32 v128, 1.0, v125
	v_add_f32_e32 v120, -1.0, v128
	v_sub_f32_e32 v121, v120, v128
	v_add_f32_e32 v121, 1.0, v121
	v_sub_f32_e32 v120, v125, v120
	v_add_f32_e32 v129, v120, v121
	v_frexp_mant_f32_e32 v132, v128
	v_cvt_f64_f32_e32 v[120:121], v128
	v_frexp_exp_i32_f64_e32 v120, v[120:121]
	v_cmp_gt_f32_e32 vcc, s4, v132
	s_waitcnt vmcnt(14)
	v_fmac_f32_e32 v48, v41, v56
	s_waitcnt vmcnt(13)
	v_fmac_f32_e32 v48, v42, v52
	v_subbrev_co_u32_e32 v120, vcc, 0, v120, vcc
	v_sub_u32_e32 v121, 0, v120
	v_ldexp_f32 v128, v128, v121
	v_ldexp_f32 v121, v129, v121
	v_add_f32_e32 v129, -1.0, v128
	v_add_f32_e32 v136, 1.0, v128
	v_add_f32_e32 v132, 1.0, v129
	v_add_f32_e32 v137, -1.0, v136
	v_sub_f32_e32 v132, v128, v132
	v_sub_f32_e32 v128, v128, v137
	v_add_f32_e32 v132, v121, v132
	v_add_f32_e32 v121, v121, v128
	v_add_f32_e32 v128, v136, v121
	v_rcp_f32_e32 v137, v128
	v_add_f32_e32 v133, v129, v132
	v_sub_f32_e32 v129, v133, v129
	v_sub_f32_e32 v129, v132, v129
	v_sub_f32_e32 v132, v128, v136
	v_sub_f32_e32 v121, v121, v132
	v_mul_f32_e32 v132, v133, v137
	v_mul_f32_e32 v136, v128, v132
	v_fma_f32 v140, v132, v128, -v136
	v_fmac_f32_e32 v140, v132, v121
	v_add_f32_e32 v141, v136, v140
	v_sub_f32_e32 v144, v133, v141
	v_sub_f32_e32 v133, v133, v144
	v_sub_f32_e32 v136, v141, v136
	v_sub_f32_e32 v133, v133, v141
	v_add_f32_e32 v129, v129, v133
	v_sub_f32_e32 v133, v136, v140
	v_add_f32_e32 v129, v133, v129
	v_add_f32_e32 v133, v144, v129
	v_mul_f32_e32 v136, v137, v133
	v_mul_f32_e32 v140, v128, v136
	v_fma_f32 v128, v136, v128, -v140
	v_fmac_f32_e32 v128, v136, v121
	v_sub_f32_e32 v121, v144, v133
	v_add_f32_e32 v121, v129, v121
	v_add_f32_e32 v129, v140, v128
	v_sub_f32_e32 v141, v133, v129
	v_sub_f32_e32 v133, v133, v141
	v_sub_f32_e32 v140, v129, v140
	v_sub_f32_e32 v129, v133, v129
	v_add_f32_e32 v121, v121, v129
	v_sub_f32_e32 v128, v140, v128
	v_cvt_f32_i32_e32 v120, v120
	v_add_f32_e32 v121, v128, v121
	v_add_f32_e32 v128, v132, v136
	v_add_f32_e32 v121, v141, v121
	v_sub_f32_e32 v129, v128, v132
	v_mul_f32_e32 v121, v137, v121
	v_sub_f32_e32 v129, v136, v129
	v_add_f32_e32 v121, v129, v121
	v_mul_f32_e32 v136, 0x3f317218, v120
	v_add_f32_e32 v129, v128, v121
	v_fma_f32 v137, v120, s5, -v136
	v_mul_f32_e32 v132, v129, v129
	v_fmac_f32_e32 v137, 0xb102e308, v120
	v_sub_f32_e32 v120, v129, v128
	v_fmamk_f32 v133, v132, 0x3e9b6dac, v202
	v_sub_f32_e32 v120, v121, v120
	v_add_f32_e32 v121, v136, v137
	v_fmaak_f32 v133, v132, v133, 0x3f2aaada
	v_sub_f32_e32 v128, v121, v136
	v_ldexp_f32 v136, v129, 1
	v_mul_f32_e32 v129, v129, v132
	v_mul_f32_e32 v129, v129, v133
	v_add_f32_e32 v132, v136, v129
	v_sub_f32_e32 v133, v132, v136
	v_ldexp_f32 v120, v120, 1
	v_sub_f32_e32 v129, v129, v133
	v_add_f32_e32 v120, v120, v129
	v_add_f32_e32 v129, v132, v120
	v_sub_f32_e32 v132, v129, v132
	v_sub_f32_e32 v120, v120, v132
	v_add_f32_e32 v132, v121, v129
	v_sub_f32_e32 v133, v132, v121
	v_sub_f32_e32 v136, v132, v133
	v_sub_f32_e32 v128, v137, v128
	v_sub_f32_e32 v121, v121, v136
	v_sub_f32_e32 v129, v129, v133
	v_add_f32_e32 v121, v129, v121
	v_add_f32_e32 v129, v128, v120
	v_sub_f32_e32 v133, v129, v128
	v_sub_f32_e32 v136, v129, v133
	v_sub_f32_e32 v128, v128, v136
	v_sub_f32_e32 v120, v120, v133
	v_add_f32_e32 v121, v129, v121
	v_add_f32_e32 v120, v120, v128
	v_add_f32_e32 v128, v132, v121
	v_sub_f32_e32 v129, v128, v132
	v_sub_f32_e32 v121, v121, v129
	v_add_f32_e32 v120, v120, v121
	v_add_f32_e32 v120, v128, v120
	v_cmp_neq_f32_e32 vcc, s30, v125
	s_waitcnt vmcnt(12)
	v_fmac_f32_e32 v48, v43, v68
	s_waitcnt vmcnt(11)
	v_fmac_f32_e32 v48, v36, v64
	v_cndmask_b32_e32 v120, v204, v120, vcc
	v_cmp_ngt_f32_e32 vcc, -1.0, v125
	s_waitcnt vmcnt(10)
	v_fmac_f32_e32 v48, v37, v72
	v_lshlrev_b32_e32 v60, 16, v46
	v_cndmask_b32_e32 v120, v205, v120, vcc
	v_cmp_neq_f32_e32 vcc, -1.0, v125
	v_fma_f32 v49, v40, v61, v49
	v_fmac_f32_e32 v49, v41, v57
	v_cndmask_b32_e32 v120, v206, v120, vcc
	v_cmp_lt_f32_e64 vcc, |v125|, s31
	v_fmac_f32_e32 v49, v42, v53
	v_fmac_f32_e32 v49, v43, v69
	v_cndmask_b32_e32 v120, v120, v125, vcc
	v_sub_f32_e32 v120, v124, v120
	v_mul_f32_e32 v121, 0x3d800000, v120
	v_mov_b32_e32 v125, 0
	v_fmac_f32_e32 v49, v36, v65
	v_mov_b32_dpp v121, v121 row_shr:1 row_mask:0xf bank_mask:0xf bound_ctrl:1
	v_fmac_f32_e32 v121, 0x3d800000, v120
	v_fmac_f32_e32 v49, v37, v73
	v_fma_f32 v50, v40, v62, v50
	v_add_f32_dpp v120, v121, v121 row_shr:2 row_mask:0xf bank_mask:0xf bound_ctrl:1
	v_mov_b32_e32 v121, 0
	v_fmac_f32_e32 v50, v41, v58
	v_add_f32_dpp v120, v120, v120 row_shr:4 row_mask:0xf bank_mask:0xf bound_ctrl:1
	v_fmac_f32_e32 v50, v42, v54
	v_fmac_f32_e32 v50, v43, v70
	v_add_f32_dpp v120, v120, v120 row_shr:8 row_mask:0xf bank_mask:0xf bound_ctrl:1
	v_fmac_f32_e32 v50, v36, v66
	v_fmac_f32_e32 v50, v37, v74
	v_mov_b32_dpp v121, v120 row_bcast:15 row_mask:0xa bank_mask:0xf
	v_add_f32_e32 v124, v120, v121
	v_mov_b32_e32 v120, v126
	v_mov_b32_e32 v121, v130
	v_pk_mul_f32 v[120:121], v[38:39], v[120:121]
	v_mov_b32_dpp v125, v124 row_bcast:31 row_mask:0xc bank_mask:0xf
	v_add_f32_e32 v118, v118, v120
	v_add_f32_e32 v118, v118, v121
	v_mov_b32_e32 v120, v134
	v_mov_b32_e32 v121, v138
	v_pk_mul_f32 v[120:121], v[32:33], v[120:121]
	v_mov_b32_e32 v138, v135
	v_add_f32_e32 v118, v118, v120
	v_add_f32_e32 v118, v118, v121
	v_mov_b32_e32 v120, v142
	v_mov_b32_e32 v121, v146
	v_pk_mul_f32 v[120:121], v[34:35], v[120:121]
	v_mov_b32_e32 v146, v143
	v_add_f32_e32 v118, v118, v120
	v_add_f32_e32 v118, v118, v121
	v_mov_b32_e32 v120, v150
	v_mov_b32_e32 v121, v154
	v_pk_mul_f32 v[120:121], v[24:25], v[120:121]
	v_mov_b32_e32 v154, v151
	v_add_f32_e32 v118, v118, v120
	v_add_f32_e32 v118, v118, v121
	v_mov_b32_e32 v120, v158
	v_mov_b32_e32 v121, v162
	v_pk_mul_f32 v[120:121], v[26:27], v[120:121]
	v_mov_b32_e32 v162, v159
	v_add_f32_e32 v118, v118, v120
	v_add_f32_e32 v120, v118, v121
	v_mul_f32_e64 v118, |v120|, s2
	v_exp_f32_e32 v122, v118
	v_add_f32_e32 v118, v124, v125
	v_min_f32_e32 v125, 0, v120
	v_lshlrev_b32_e32 v124, 16, v45
	v_add_f32_e32 v126, 1.0, v122
	v_add_f32_e32 v120, -1.0, v126
	v_sub_f32_e32 v121, v120, v126
	v_add_f32_e32 v121, 1.0, v121
	v_sub_f32_e32 v120, v122, v120
	v_add_f32_e32 v128, v120, v121
	v_frexp_mant_f32_e32 v129, v126
	v_cvt_f64_f32_e32 v[120:121], v126
	v_frexp_exp_i32_f64_e32 v120, v[120:121]
	v_cmp_gt_f32_e32 vcc, s4, v129
	v_fmac_f32_e32 v51, v40, v63
	v_fmac_f32_e32 v51, v41, v59
	v_subbrev_co_u32_e32 v120, vcc, 0, v120, vcc
	v_sub_u32_e32 v121, 0, v120
	v_ldexp_f32 v126, v126, v121
	v_ldexp_f32 v121, v128, v121
	v_add_f32_e32 v128, -1.0, v126
	v_add_f32_e32 v132, 1.0, v126
	v_add_f32_e32 v129, 1.0, v128
	v_add_f32_e32 v133, -1.0, v132
	v_sub_f32_e32 v129, v126, v129
	v_sub_f32_e32 v126, v126, v133
	v_add_f32_e32 v129, v121, v129
	v_add_f32_e32 v121, v121, v126
	v_add_f32_e32 v126, v132, v121
	v_rcp_f32_e32 v133, v126
	v_add_f32_e32 v130, v128, v129
	v_sub_f32_e32 v128, v130, v128
	v_sub_f32_e32 v128, v129, v128
	v_sub_f32_e32 v129, v126, v132
	v_sub_f32_e32 v121, v121, v129
	v_mul_f32_e32 v129, v130, v133
	v_mul_f32_e32 v132, v126, v129
	v_fma_f32 v134, v129, v126, -v132
	v_fmac_f32_e32 v134, v129, v121
	v_add_f32_e32 v136, v132, v134
	v_sub_f32_e32 v137, v130, v136
	v_sub_f32_e32 v130, v130, v137
	v_sub_f32_e32 v132, v136, v132
	v_sub_f32_e32 v130, v130, v136
	v_add_f32_e32 v128, v128, v130
	v_sub_f32_e32 v130, v132, v134
	v_add_f32_e32 v128, v130, v128
	v_add_f32_e32 v130, v137, v128
	v_mul_f32_e32 v132, v133, v130
	v_mul_f32_e32 v134, v126, v132
	v_fma_f32 v126, v132, v126, -v134
	v_fmac_f32_e32 v126, v132, v121
	v_sub_f32_e32 v121, v137, v130
	v_add_f32_e32 v121, v128, v121
	v_add_f32_e32 v128, v134, v126
	v_sub_f32_e32 v136, v130, v128
	v_sub_f32_e32 v130, v130, v136
	v_sub_f32_e32 v134, v128, v134
	v_sub_f32_e32 v128, v130, v128
	v_add_f32_e32 v121, v121, v128
	v_sub_f32_e32 v126, v134, v126
	v_cvt_f32_i32_e32 v120, v120
	v_add_f32_e32 v121, v126, v121
	v_add_f32_e32 v126, v129, v132
	v_add_f32_e32 v121, v136, v121
	v_sub_f32_e32 v128, v126, v129
	v_mul_f32_e32 v121, v133, v121
	v_sub_f32_e32 v128, v132, v128
	v_add_f32_e32 v121, v128, v121
	v_mul_f32_e32 v132, 0x3f317218, v120
	v_add_f32_e32 v128, v126, v121
	v_fma_f32 v133, v120, s5, -v132
	v_mul_f32_e32 v129, v128, v128
	v_fmac_f32_e32 v133, 0xb102e308, v120
	v_sub_f32_e32 v120, v128, v126
	v_fmamk_f32 v130, v129, 0x3e9b6dac, v202
	v_sub_f32_e32 v120, v121, v120
	v_add_f32_e32 v121, v132, v133
	v_fmaak_f32 v130, v129, v130, 0x3f2aaada
	v_sub_f32_e32 v126, v121, v132
	v_ldexp_f32 v132, v128, 1
	v_mul_f32_e32 v128, v128, v129
	v_mul_f32_e32 v128, v128, v130
	v_add_f32_e32 v129, v132, v128
	v_sub_f32_e32 v130, v129, v132
	v_ldexp_f32 v120, v120, 1
	v_sub_f32_e32 v128, v128, v130
	v_add_f32_e32 v120, v120, v128
	v_add_f32_e32 v128, v129, v120
	v_sub_f32_e32 v129, v128, v129
	v_sub_f32_e32 v120, v120, v129
	v_add_f32_e32 v129, v121, v128
	v_sub_f32_e32 v130, v129, v121
	v_sub_f32_e32 v132, v129, v130
	v_sub_f32_e32 v126, v133, v126
	v_sub_f32_e32 v121, v121, v132
	v_sub_f32_e32 v128, v128, v130
	v_add_f32_e32 v121, v128, v121
	v_add_f32_e32 v128, v126, v120
	v_sub_f32_e32 v130, v128, v126
	v_sub_f32_e32 v132, v128, v130
	v_sub_f32_e32 v126, v126, v132
	v_sub_f32_e32 v120, v120, v130
	v_add_f32_e32 v121, v128, v121
	v_add_f32_e32 v120, v120, v126
	v_add_f32_e32 v126, v129, v121
	v_sub_f32_e32 v128, v126, v129
	v_sub_f32_e32 v121, v121, v128
	v_add_f32_e32 v120, v120, v121
	v_add_f32_e32 v120, v126, v120
	v_cmp_neq_f32_e32 vcc, s30, v122
	v_mov_b32_e32 v130, v127
	v_fmac_f32_e32 v51, v42, v55
	v_cndmask_b32_e32 v120, v204, v120, vcc
	v_cmp_ngt_f32_e32 vcc, -1.0, v122
	v_fmac_f32_e32 v51, v43, v71
	v_fmac_f32_e32 v51, v36, v67
	v_cndmask_b32_e32 v120, v205, v120, vcc
	v_cmp_neq_f32_e32 vcc, -1.0, v122
	v_fmac_f32_e32 v51, v37, v75
	v_readlane_b32 s26, v117, 31
	v_cndmask_b32_e32 v120, v206, v120, vcc
	v_cmp_lt_f32_e64 vcc, |v122|, s31
	v_mul_f32_e32 v116, 0x3e000000, v207
	v_and_b32_e32 v45, 0xffff0000, v45
	v_cndmask_b32_e32 v120, v120, v122, vcc
	v_sub_f32_e32 v121, v125, v120
	v_mul_f32_e32 v122, 0x3d800000, v121
	v_mul_f32_e32 v120, 0x3e000000, v124
	v_mov_b32_e32 v124, 0
	v_mov_b32_dpp v122, v122 row_shr:1 row_mask:0xf bank_mask:0xf bound_ctrl:1
	v_fmac_f32_e32 v122, 0x3d800000, v121
	v_mul_f32_e32 v45, 0x3e000000, v45
	v_and_b32_e32 v46, 0xffff0000, v46
	v_add_f32_dpp v121, v122, v122 row_shr:2 row_mask:0xf bank_mask:0xf bound_ctrl:1
	v_mov_b32_e32 v122, 0
	v_mul_f32_e32 v46, 0x3e000000, v46
	v_add_f32_dpp v121, v121, v121 row_shr:4 row_mask:0xf bank_mask:0xf bound_ctrl:1
	v_lshlrev_b32_e32 v58, 16, v47
	s_lshl_b32 s27, s35, 7
	v_add_f32_dpp v121, v121, v121 row_shr:8 row_mask:0xf bank_mask:0xf bound_ctrl:1
	s_nop 1
	v_mov_b32_dpp v122, v121 row_bcast:15 row_mask:0xa bank_mask:0xf
	v_add_f32_e32 v121, v121, v122
	v_pk_mul_f32 v[122:123], v[38:39], v[130:131]
	s_nop 0
	v_add_f32_e32 v119, v119, v122
	v_add_f32_e32 v119, v119, v123
	v_pk_mul_f32 v[122:123], v[32:33], v[138:139]
	v_mov_b32_dpp v124, v121 row_bcast:31 row_mask:0xc bank_mask:0xf
	v_add_f32_e32 v119, v119, v122
	v_add_f32_e32 v119, v119, v123
	v_pk_mul_f32 v[122:123], v[34:35], v[146:147]
	s_nop 0
	v_add_f32_e32 v119, v119, v122
	v_add_f32_e32 v119, v119, v123
	v_pk_mul_f32 v[122:123], v[24:25], v[154:155]
	s_nop 0
	v_add_f32_e32 v119, v119, v122
	v_add_f32_e32 v119, v119, v123
	v_pk_mul_f32 v[122:123], v[26:27], v[162:163]
	s_nop 0
	v_add_f32_e32 v119, v119, v122
	v_add_f32_e32 v122, v119, v123
	v_mul_f32_e64 v119, |v122|, s2
	v_exp_f32_e32 v125, v119
	v_add_f32_e32 v119, v121, v124
	v_min_f32_e32 v121, 0, v122
	v_add_f32_e32 v124, 1.0, v125
	v_add_f32_e32 v122, -1.0, v124
	v_sub_f32_e32 v123, v122, v124
	v_add_f32_e32 v123, 1.0, v123
	v_sub_f32_e32 v122, v125, v122
	v_add_f32_e32 v126, v122, v123
	v_frexp_mant_f32_e32 v127, v124
	v_cvt_f64_f32_e32 v[122:123], v124
	v_frexp_exp_i32_f64_e32 v122, v[122:123]
	v_cmp_gt_f32_e32 vcc, s4, v127
	s_nop 1
	v_subbrev_co_u32_e32 v122, vcc, 0, v122, vcc
	v_sub_u32_e32 v123, 0, v122
	v_ldexp_f32 v124, v124, v123
	v_ldexp_f32 v123, v126, v123
	v_add_f32_e32 v126, -1.0, v124
	v_add_f32_e32 v129, 1.0, v124
	v_add_f32_e32 v127, 1.0, v126
	v_add_f32_e32 v130, -1.0, v129
	v_sub_f32_e32 v127, v124, v127
	v_sub_f32_e32 v124, v124, v130
	v_add_f32_e32 v127, v123, v127
	v_add_f32_e32 v123, v123, v124
	v_add_f32_e32 v124, v129, v123
	v_rcp_f32_e32 v130, v124
	v_add_f32_e32 v128, v126, v127
	v_sub_f32_e32 v126, v128, v126
	v_sub_f32_e32 v126, v127, v126
	v_sub_f32_e32 v127, v124, v129
	v_sub_f32_e32 v123, v123, v127
	v_mul_f32_e32 v127, v128, v130
	v_mul_f32_e32 v129, v124, v127
	v_fma_f32 v131, v127, v124, -v129
	v_fmac_f32_e32 v131, v127, v123
	v_add_f32_e32 v132, v129, v131
	v_sub_f32_e32 v133, v128, v132
	v_sub_f32_e32 v128, v128, v133
	v_sub_f32_e32 v129, v132, v129
	v_sub_f32_e32 v128, v128, v132
	v_add_f32_e32 v126, v126, v128
	v_sub_f32_e32 v128, v129, v131
	v_add_f32_e32 v126, v128, v126
	v_add_f32_e32 v128, v133, v126
	v_mul_f32_e32 v129, v130, v128
	v_mul_f32_e32 v131, v124, v129
	v_fma_f32 v124, v129, v124, -v131
	v_fmac_f32_e32 v124, v129, v123
	v_sub_f32_e32 v123, v133, v128
	v_add_f32_e32 v123, v126, v123
	v_add_f32_e32 v126, v131, v124
	v_sub_f32_e32 v132, v128, v126
	v_sub_f32_e32 v128, v128, v132
	v_sub_f32_e32 v131, v126, v131
	v_sub_f32_e32 v126, v128, v126
	v_add_f32_e32 v123, v123, v126
	v_sub_f32_e32 v124, v131, v124
	v_cvt_f32_i32_e32 v122, v122
	v_add_f32_e32 v123, v124, v123
	v_add_f32_e32 v124, v127, v129
	v_add_f32_e32 v123, v132, v123
	v_sub_f32_e32 v126, v124, v127
	v_mul_f32_e32 v123, v130, v123
	v_sub_f32_e32 v126, v129, v126
	v_add_f32_e32 v123, v126, v123
	v_mul_f32_e32 v129, 0x3f317218, v122
	v_add_f32_e32 v126, v124, v123
	v_fma_f32 v130, v122, s5, -v129
	v_mul_f32_e32 v127, v126, v126
	v_fmac_f32_e32 v130, 0xb102e308, v122
	v_sub_f32_e32 v122, v126, v124
	v_fmamk_f32 v128, v127, 0x3e9b6dac, v202
	v_sub_f32_e32 v122, v123, v122
	v_add_f32_e32 v123, v129, v130
	v_fmaak_f32 v128, v127, v128, 0x3f2aaada
	v_sub_f32_e32 v124, v123, v129
	v_ldexp_f32 v129, v126, 1
	v_mul_f32_e32 v126, v126, v127
	v_mul_f32_e32 v126, v126, v128
	v_add_f32_e32 v127, v129, v126
	v_sub_f32_e32 v128, v127, v129
	v_ldexp_f32 v122, v122, 1
	v_sub_f32_e32 v126, v126, v128
	v_add_f32_e32 v122, v122, v126
	v_add_f32_e32 v126, v127, v122
	v_sub_f32_e32 v127, v126, v127
	v_sub_f32_e32 v122, v122, v127
	v_add_f32_e32 v127, v123, v126
	v_sub_f32_e32 v128, v127, v123
	v_sub_f32_e32 v129, v127, v128
	v_sub_f32_e32 v124, v130, v124
	v_sub_f32_e32 v123, v123, v129
	v_sub_f32_e32 v126, v126, v128
	v_add_f32_e32 v123, v126, v123
	v_add_f32_e32 v126, v124, v122
	v_sub_f32_e32 v128, v126, v124
	v_sub_f32_e32 v129, v126, v128
	v_sub_f32_e32 v124, v124, v129
	v_sub_f32_e32 v122, v122, v128
	v_add_f32_e32 v123, v126, v123
	v_add_f32_e32 v122, v122, v124
	v_add_f32_e32 v124, v127, v123
	v_sub_f32_e32 v126, v124, v127
	v_sub_f32_e32 v123, v123, v126
	v_add_f32_e32 v122, v122, v123
	v_add_f32_e32 v122, v124, v122
	v_cmp_neq_f32_e32 vcc, s30, v125
	s_waitcnt vmcnt(8)
	v_mov_b32_e32 v123, v88
	v_mov_b32_e32 v124, 0
	v_cndmask_b32_e32 v122, v204, v122, vcc
	v_cmp_ngt_f32_e32 vcc, -1.0, v125
	s_nop 1
	v_cndmask_b32_e32 v122, v205, v122, vcc
	v_cmp_neq_f32_e32 vcc, -1.0, v125
	s_nop 1
	v_cndmask_b32_e32 v122, v206, v122, vcc
	v_cmp_lt_f32_e64 vcc, |v125|, s31
	s_nop 1
	v_cndmask_b32_e32 v122, v122, v125, vcc
	v_sub_f32_e32 v121, v121, v122
	v_mul_f32_e32 v122, 0x3d800000, v121
	s_nop 1
	v_mov_b32_dpp v122, v122 row_shr:1 row_mask:0xf bank_mask:0xf bound_ctrl:1
	v_fmac_f32_e32 v122, 0x3d800000, v121
	s_nop 1
	v_add_f32_dpp v121, v122, v122 row_shr:2 row_mask:0xf bank_mask:0xf bound_ctrl:1
	v_mov_b32_e32 v122, 0
	s_nop 0
	v_add_f32_dpp v121, v121, v121 row_shr:4 row_mask:0xf bank_mask:0xf bound_ctrl:1
	s_nop 1
	v_add_f32_dpp v121, v121, v121 row_shr:8 row_mask:0xf bank_mask:0xf bound_ctrl:1
	s_nop 1
	v_mov_b32_dpp v122, v121 row_bcast:15 row_mask:0xa bank_mask:0xf
	v_add_f32_e32 v121, v121, v122
	v_mov_b32_e32 v122, v76
	v_pk_mul_f32 v[122:123], v[38:39], v[122:123]
	v_mov_b32_dpp v124, v121 row_bcast:31 row_mask:0xc bank_mask:0xf
	v_add_f32_e32 v48, v48, v122
	v_add_f32_e32 v48, v48, v123
	s_waitcnt vmcnt(7)
	v_mov_b32_e32 v122, v80
	s_waitcnt vmcnt(6)
	v_mov_b32_e32 v123, v100
	v_pk_mul_f32 v[122:123], v[32:33], v[122:123]
	s_nop 0
	v_add_f32_e32 v48, v48, v122
	v_add_f32_e32 v48, v48, v123
	s_waitcnt vmcnt(5)
	v_mov_b32_e32 v122, v84
	s_waitcnt vmcnt(4)
	v_mov_b32_e32 v123, v104
	v_pk_mul_f32 v[122:123], v[34:35], v[122:123]
	s_nop 0
	v_add_f32_e32 v48, v48, v122
	v_add_f32_e32 v48, v48, v123
	s_waitcnt vmcnt(3)
	v_mov_b32_e32 v122, v92
	s_waitcnt vmcnt(1)
	v_mov_b32_e32 v123, v112
	v_pk_mul_f32 v[122:123], v[24:25], v[122:123]
	v_mov_b32_e32 v112, v93
	v_add_f32_e32 v48, v48, v122
	v_add_f32_e32 v48, v48, v123
	s_waitcnt vmcnt(0)
	v_mov_b32_e32 v122, v108
	v_mov_b32_e32 v123, v96
	v_pk_mul_f32 v[122:123], v[26:27], v[122:123]
	s_nop 0
	v_add_f32_e32 v48, v48, v122
	v_add_f32_e32 v52, v48, v123
	v_mul_f32_e64 v48, |v52|, s2
	v_exp_f32_e32 v56, v48
	v_min_f32_e32 v52, 0, v52
	v_add_f32_e32 v48, v121, v124
	v_add_f32_e32 v64, 1.0, v56
	v_add_f32_e32 v68, -1.0, v64
	v_sub_f32_e32 v72, v68, v64
	v_add_f32_e32 v72, 1.0, v72
	v_sub_f32_e32 v68, v56, v68
	v_add_f32_e32 v68, v68, v72
	v_frexp_mant_f32_e32 v72, v64
	v_cvt_f64_f32_e32 v[122:123], v64
	v_frexp_exp_i32_f64_e32 v76, v[122:123]
	v_cmp_gt_f32_e32 vcc, s4, v72
	s_nop 1
	v_subbrev_co_u32_e32 v72, vcc, 0, v76, vcc
	v_sub_u32_e32 v76, 0, v72
	v_ldexp_f32 v64, v64, v76
	v_ldexp_f32 v68, v68, v76
	v_add_f32_e32 v76, -1.0, v64
	v_add_f32_e32 v88, 1.0, v64
	v_add_f32_e32 v80, 1.0, v76
	v_add_f32_e32 v92, -1.0, v88
	v_sub_f32_e32 v80, v64, v80
	v_sub_f32_e32 v64, v64, v92
	v_add_f32_e32 v64, v68, v64
	v_add_f32_e32 v80, v68, v80
	v_add_f32_e32 v68, v88, v64
	v_rcp_f32_e32 v92, v68
	v_add_f32_e32 v84, v76, v80
	v_sub_f32_e32 v76, v84, v76
	v_sub_f32_e32 v76, v80, v76
	v_sub_f32_e32 v80, v68, v88
	v_sub_f32_e32 v64, v64, v80
	v_mul_f32_e32 v80, v84, v92
	v_mul_f32_e32 v88, v68, v80
	v_fma_f32 v96, v80, v68, -v88
	v_fmac_f32_e32 v96, v80, v64
	v_add_f32_e32 v100, v88, v96
	v_sub_f32_e32 v104, v84, v100
	v_sub_f32_e32 v84, v84, v104
	v_sub_f32_e32 v88, v100, v88
	v_sub_f32_e32 v84, v84, v100
	v_add_f32_e32 v76, v76, v84
	v_sub_f32_e32 v84, v88, v96
	v_add_f32_e32 v76, v84, v76
	v_add_f32_e32 v84, v104, v76
	v_mul_f32_e32 v88, v92, v84
	v_mul_f32_e32 v96, v68, v88
	v_fma_f32 v68, v88, v68, -v96
	v_fmac_f32_e32 v68, v88, v64
	v_sub_f32_e32 v64, v104, v84
	v_add_f32_e32 v64, v76, v64
	v_add_f32_e32 v76, v96, v68
	v_sub_f32_e32 v100, v84, v76
	v_sub_f32_e32 v84, v84, v100
	v_sub_f32_e32 v96, v76, v96
	v_sub_f32_e32 v76, v84, v76
	v_add_f32_e32 v64, v64, v76
	v_sub_f32_e32 v68, v96, v68
	v_cvt_f32_i32_e32 v72, v72
	v_add_f32_e32 v64, v68, v64
	v_add_f32_e32 v68, v80, v88
	v_add_f32_e32 v64, v100, v64
	v_sub_f32_e32 v76, v68, v80
	v_mul_f32_e32 v64, v92, v64
	v_sub_f32_e32 v76, v88, v76
	v_add_f32_e32 v64, v76, v64
	v_mul_f32_e32 v88, 0x3f317218, v72
	v_add_f32_e32 v76, v68, v64
	v_fma_f32 v92, v72, s5, -v88
	v_mul_f32_e32 v80, v76, v76
	v_fmac_f32_e32 v92, 0xb102e308, v72
	v_sub_f32_e32 v68, v76, v68
	v_fmamk_f32 v84, v80, 0x3e9b6dac, v202
	v_sub_f32_e32 v64, v64, v68
	v_add_f32_e32 v68, v88, v92
	v_fmaak_f32 v84, v80, v84, 0x3f2aaada
	v_sub_f32_e32 v72, v68, v88
	v_ldexp_f32 v88, v76, 1
	v_mul_f32_e32 v76, v76, v80
	v_mul_f32_e32 v76, v76, v84
	v_add_f32_e32 v80, v88, v76
	v_sub_f32_e32 v84, v80, v88
	v_ldexp_f32 v64, v64, 1
	v_sub_f32_e32 v76, v76, v84
	v_add_f32_e32 v64, v64, v76
	v_add_f32_e32 v76, v80, v64
	v_sub_f32_e32 v80, v76, v80
	v_sub_f32_e32 v64, v64, v80
	v_add_f32_e32 v80, v68, v76
	v_sub_f32_e32 v84, v80, v68
	v_sub_f32_e32 v88, v80, v84
	v_sub_f32_e32 v72, v92, v72
	v_sub_f32_e32 v68, v68, v88
	v_sub_f32_e32 v76, v76, v84
	v_add_f32_e32 v68, v76, v68
	v_add_f32_e32 v76, v72, v64
	v_sub_f32_e32 v84, v76, v72
	v_sub_f32_e32 v88, v76, v84
	v_sub_f32_e32 v72, v72, v88
	v_sub_f32_e32 v64, v64, v84
	v_add_f32_e32 v68, v76, v68
	v_add_f32_e32 v64, v64, v72
	v_add_f32_e32 v72, v80, v68
	v_sub_f32_e32 v76, v72, v80
	v_sub_f32_e32 v68, v68, v76
	v_add_f32_e32 v64, v64, v68
	v_add_f32_e32 v64, v72, v64
	v_cmp_neq_f32_e32 vcc, s30, v56
	v_mov_b32_e32 v88, v77
	v_mov_b32_e32 v100, v81
	v_cndmask_b32_e32 v64, v204, v64, vcc
	v_cmp_ngt_f32_e32 vcc, -1.0, v56
	v_mov_b32_e32 v104, v85
	v_mov_b32_e32 v96, v109
	v_cndmask_b32_e32 v64, v205, v64, vcc
	v_cmp_neq_f32_e32 vcc, -1.0, v56
	s_nop 1
	v_cndmask_b32_e32 v64, v206, v64, vcc
	v_cmp_lt_f32_e64 vcc, |v56|, s31
	s_nop 1
	v_cndmask_b32_e32 v56, v64, v56, vcc
	v_sub_f32_e32 v56, v52, v56
	v_mul_f32_e32 v64, 0x3d800000, v56
	v_mul_f32_e32 v52, 0x3e000000, v60
	s_nop 0
	v_mov_b32_dpp v60, v64 row_shr:1 row_mask:0xf bank_mask:0xf bound_ctrl:1
	v_fmac_f32_e32 v60, 0x3d800000, v56
	v_mov_b32_e32 v64, 0
	s_nop 0
	v_add_f32_dpp v56, v60, v60 row_shr:2 row_mask:0xf bank_mask:0xf bound_ctrl:1
	v_mov_b32_e32 v60, 0
	s_nop 0
	v_add_f32_dpp v56, v56, v56 row_shr:4 row_mask:0xf bank_mask:0xf bound_ctrl:1
	s_nop 1
	v_add_f32_dpp v56, v56, v56 row_shr:8 row_mask:0xf bank_mask:0xf bound_ctrl:1
	s_nop 1
	v_mov_b32_dpp v60, v56 row_bcast:15 row_mask:0xa bank_mask:0xf
	v_add_f32_e32 v60, v56, v60
	v_pk_mul_f32 v[56:57], v[38:39], v[88:89]
	s_nop 0
	v_add_f32_e32 v49, v49, v56
	v_add_f32_e32 v49, v49, v57
	v_pk_mul_f32 v[56:57], v[32:33], v[100:101]
	v_mov_b32_dpp v64, v60 row_bcast:31 row_mask:0xc bank_mask:0xf
	v_add_f32_e32 v49, v49, v56
	v_add_f32_e32 v49, v49, v57
	v_pk_mul_f32 v[56:57], v[34:35], v[104:105]
	s_nop 0
	v_add_f32_e32 v49, v49, v56
	v_add_f32_e32 v49, v49, v57
	v_pk_mul_f32 v[56:57], v[24:25], v[112:113]
	s_nop 0
	v_add_f32_e32 v49, v49, v56
	v_add_f32_e32 v49, v49, v57
	v_pk_mul_f32 v[56:57], v[26:27], v[96:97]
	s_nop 0
	v_add_f32_e32 v49, v49, v56
	v_add_f32_e32 v53, v49, v57
	v_mul_f32_e64 v49, |v53|, s2
	v_exp_f32_e32 v61, v49
	v_add_f32_e32 v49, v60, v64
	v_min_f32_e32 v53, 0, v53
	v_add_f32_e32 v60, 1.0, v61
	v_add_f32_e32 v56, -1.0, v60
	v_sub_f32_e32 v57, v56, v60
	v_add_f32_e32 v57, 1.0, v57
	v_sub_f32_e32 v56, v61, v56
	v_add_f32_e32 v64, v56, v57
	v_frexp_mant_f32_e32 v65, v60
	v_cvt_f64_f32_e32 v[56:57], v60
	v_frexp_exp_i32_f64_e32 v56, v[56:57]
	v_cmp_gt_f32_e32 vcc, s4, v65
	s_nop 1
	v_subbrev_co_u32_e32 v56, vcc, 0, v56, vcc
	v_sub_u32_e32 v57, 0, v56
	v_ldexp_f32 v60, v60, v57
	v_ldexp_f32 v57, v64, v57
	v_add_f32_e32 v64, -1.0, v60
	v_add_f32_e32 v69, 1.0, v60
	v_add_f32_e32 v65, 1.0, v64
	v_add_f32_e32 v72, -1.0, v69
	v_sub_f32_e32 v65, v60, v65
	v_sub_f32_e32 v60, v60, v72
	v_add_f32_e32 v65, v57, v65
	v_add_f32_e32 v57, v57, v60
	v_add_f32_e32 v60, v69, v57
	v_rcp_f32_e32 v72, v60
	v_add_f32_e32 v68, v64, v65
	v_sub_f32_e32 v64, v68, v64
	v_sub_f32_e32 v64, v65, v64
	v_sub_f32_e32 v65, v60, v69
	v_sub_f32_e32 v57, v57, v65
	v_mul_f32_e32 v65, v68, v72
	v_mul_f32_e32 v69, v60, v65
	v_fma_f32 v73, v65, v60, -v69
	v_fmac_f32_e32 v73, v65, v57
	v_add_f32_e32 v76, v69, v73
	v_sub_f32_e32 v77, v68, v76
	v_sub_f32_e32 v68, v68, v77
	v_sub_f32_e32 v69, v76, v69
	v_sub_f32_e32 v68, v68, v76
	v_add_f32_e32 v64, v64, v68
	v_sub_f32_e32 v68, v69, v73
	v_add_f32_e32 v64, v68, v64
	v_add_f32_e32 v68, v77, v64
	v_mul_f32_e32 v69, v72, v68
	v_mul_f32_e32 v73, v60, v69
	v_fma_f32 v60, v69, v60, -v73
	v_fmac_f32_e32 v60, v69, v57
	v_sub_f32_e32 v57, v77, v68
	v_add_f32_e32 v57, v64, v57
	v_add_f32_e32 v64, v73, v60
	v_sub_f32_e32 v76, v68, v64
	v_sub_f32_e32 v68, v68, v76
	v_sub_f32_e32 v73, v64, v73
	v_sub_f32_e32 v64, v68, v64
	v_add_f32_e32 v57, v57, v64
	v_sub_f32_e32 v60, v73, v60
	v_cvt_f32_i32_e32 v56, v56
	v_add_f32_e32 v57, v60, v57
	v_add_f32_e32 v60, v65, v69
	v_add_f32_e32 v57, v76, v57
	v_sub_f32_e32 v64, v60, v65
	v_mul_f32_e32 v57, v72, v57
	v_sub_f32_e32 v64, v69, v64
	v_add_f32_e32 v57, v64, v57
	v_mul_f32_e32 v69, 0x3f317218, v56
	v_add_f32_e32 v64, v60, v57
	v_fma_f32 v72, v56, s5, -v69
	v_mul_f32_e32 v65, v64, v64
	v_fmac_f32_e32 v72, 0xb102e308, v56
	v_sub_f32_e32 v56, v64, v60
	v_fmamk_f32 v68, v65, 0x3e9b6dac, v202
	v_sub_f32_e32 v56, v57, v56
	v_add_f32_e32 v57, v69, v72
	v_fmaak_f32 v68, v65, v68, 0x3f2aaada
	v_sub_f32_e32 v60, v57, v69
	v_ldexp_f32 v69, v64, 1
	v_mul_f32_e32 v64, v64, v65
	v_mul_f32_e32 v64, v64, v68
	v_add_f32_e32 v65, v69, v64
	v_sub_f32_e32 v68, v65, v69
	v_ldexp_f32 v56, v56, 1
	v_sub_f32_e32 v64, v64, v68
	v_add_f32_e32 v56, v56, v64
	v_add_f32_e32 v64, v65, v56
	v_sub_f32_e32 v65, v64, v65
	v_sub_f32_e32 v56, v56, v65
	v_add_f32_e32 v65, v57, v64
	v_sub_f32_e32 v68, v65, v57
	v_sub_f32_e32 v69, v65, v68
	v_sub_f32_e32 v60, v72, v60
	v_sub_f32_e32 v57, v57, v69
	v_sub_f32_e32 v64, v64, v68
	v_add_f32_e32 v57, v64, v57
	v_add_f32_e32 v64, v60, v56
	v_sub_f32_e32 v68, v64, v60
	v_sub_f32_e32 v69, v64, v68
	v_sub_f32_e32 v60, v60, v69
	v_sub_f32_e32 v56, v56, v68
	v_add_f32_e32 v57, v64, v57
	v_add_f32_e32 v56, v56, v60
	v_add_f32_e32 v60, v65, v57
	v_sub_f32_e32 v64, v60, v65
	v_sub_f32_e32 v57, v57, v64
	v_add_f32_e32 v56, v56, v57
	v_add_f32_e32 v56, v60, v56
	v_cmp_neq_f32_e32 vcc, s30, v61
	v_mov_b32_e32 v57, v90
	v_mov_b32_e32 v60, 0
	v_cndmask_b32_e32 v56, v204, v56, vcc
	v_cmp_ngt_f32_e32 vcc, -1.0, v61
	v_mov_b32_e32 v90, v79
	v_pk_mul_f32 v[36:37], v[38:39], v[90:91]
	v_cndmask_b32_e32 v56, v205, v56, vcc
	v_cmp_neq_f32_e32 vcc, -1.0, v61
	v_add_f32_e32 v36, v51, v36
	v_add_f32_e32 v36, v36, v37
	v_cndmask_b32_e32 v56, v206, v56, vcc
	v_cmp_lt_f32_e64 vcc, |v61|, s31
	s_nop 1
	v_cndmask_b32_e32 v56, v56, v61, vcc
	v_sub_f32_e32 v53, v53, v56
	v_mul_f32_e32 v56, 0x3d800000, v53
	s_nop 1
	v_mov_b32_dpp v56, v56 row_shr:1 row_mask:0xf bank_mask:0xf bound_ctrl:1
	v_fmac_f32_e32 v56, 0x3d800000, v53
	s_nop 1
	v_add_f32_dpp v53, v56, v56 row_shr:2 row_mask:0xf bank_mask:0xf bound_ctrl:1
	v_mov_b32_e32 v56, 0
	s_nop 0
	v_add_f32_dpp v53, v53, v53 row_shr:4 row_mask:0xf bank_mask:0xf bound_ctrl:1
	s_nop 1
	v_add_f32_dpp v53, v53, v53 row_shr:8 row_mask:0xf bank_mask:0xf bound_ctrl:1
	s_nop 1
	v_mov_b32_dpp v56, v53 row_bcast:15 row_mask:0xa bank_mask:0xf
	v_add_f32_e32 v53, v53, v56
	v_mov_b32_e32 v56, v78
	v_pk_mul_f32 v[56:57], v[38:39], v[56:57]
	v_mov_b32_dpp v60, v53 row_bcast:31 row_mask:0xc bank_mask:0xf
	v_add_f32_e32 v50, v50, v56
	v_add_f32_e32 v50, v50, v57
	v_mov_b32_e32 v56, v82
	v_mov_b32_e32 v57, v102
	v_pk_mul_f32 v[56:57], v[32:33], v[56:57]
	v_add_f32_e32 v53, v53, v60
	v_add_f32_e32 v50, v50, v56
	v_add_f32_e32 v50, v50, v57
	v_mov_b32_e32 v56, v86
	v_mov_b32_e32 v57, v106
	v_pk_mul_f32 v[56:57], v[34:35], v[56:57]
	v_mov_b32_e32 v102, v83
	v_add_f32_e32 v50, v50, v56
	v_add_f32_e32 v50, v50, v57
	v_mov_b32_e32 v56, v94
	v_mov_b32_e32 v57, v114
	v_pk_mul_f32 v[56:57], v[24:25], v[56:57]
	v_pk_mul_f32 v[32:33], v[32:33], v[102:103]
	v_add_f32_e32 v50, v50, v56
	v_add_f32_e32 v50, v50, v57
	v_mov_b32_e32 v56, v110
	v_mov_b32_e32 v57, v98
	v_pk_mul_f32 v[56:57], v[26:27], v[56:57]
	v_add_f32_e32 v32, v36, v32
	v_add_f32_e32 v50, v50, v56
	v_add_f32_e32 v50, v50, v57
	v_mul_f32_e64 v54, |v50|, s2
	v_exp_f32_e32 v54, v54
	v_mov_b32_e32 v106, v87
	v_add_f32_e32 v36, v32, v33
	v_pk_mul_f32 v[32:33], v[34:35], v[106:107]
	v_add_f32_e32 v60, 1.0, v54
	v_add_f32_e32 v56, -1.0, v60
	v_sub_f32_e32 v57, v56, v60
	v_add_f32_e32 v57, 1.0, v57
	v_sub_f32_e32 v56, v54, v56
	v_add_f32_e32 v61, v56, v57
	v_frexp_mant_f32_e32 v62, v60
	v_cvt_f64_f32_e32 v[56:57], v60
	v_frexp_exp_i32_f64_e32 v56, v[56:57]
	v_cmp_gt_f32_e32 vcc, s4, v62
	v_add_f32_e32 v32, v36, v32
	v_mov_b32_e32 v114, v95
	v_subbrev_co_u32_e32 v56, vcc, 0, v56, vcc
	v_sub_u32_e32 v57, 0, v56
	v_ldexp_f32 v60, v60, v57
	v_ldexp_f32 v57, v61, v57
	v_add_f32_e32 v61, -1.0, v60
	v_add_f32_e32 v65, 1.0, v60
	v_add_f32_e32 v62, 1.0, v61
	v_add_f32_e32 v66, -1.0, v65
	v_sub_f32_e32 v62, v60, v62
	v_sub_f32_e32 v60, v60, v66
	v_add_f32_e32 v62, v57, v62
	v_add_f32_e32 v57, v57, v60
	v_add_f32_e32 v60, v65, v57
	v_rcp_f32_e32 v66, v60
	v_add_f32_e32 v64, v61, v62
	v_sub_f32_e32 v61, v64, v61
	v_sub_f32_e32 v61, v62, v61
	v_sub_f32_e32 v62, v60, v65
	v_sub_f32_e32 v57, v57, v62
	v_mul_f32_e32 v62, v64, v66
	v_mul_f32_e32 v65, v60, v62
	v_fma_f32 v68, v62, v60, -v65
	v_fmac_f32_e32 v68, v62, v57
	v_add_f32_e32 v69, v65, v68
	v_sub_f32_e32 v70, v64, v69
	v_sub_f32_e32 v64, v64, v70
	v_sub_f32_e32 v65, v69, v65
	v_sub_f32_e32 v64, v64, v69
	v_add_f32_e32 v61, v61, v64
	v_sub_f32_e32 v64, v65, v68
	v_add_f32_e32 v61, v64, v61
	v_add_f32_e32 v64, v70, v61
	v_mul_f32_e32 v65, v66, v64
	v_mul_f32_e32 v68, v60, v65
	v_fma_f32 v60, v65, v60, -v68
	v_fmac_f32_e32 v60, v65, v57
	v_sub_f32_e32 v57, v70, v64
	v_add_f32_e32 v57, v61, v57
	v_add_f32_e32 v61, v68, v60
	v_sub_f32_e32 v69, v64, v61
	v_sub_f32_e32 v64, v64, v69
	v_sub_f32_e32 v68, v61, v68
	v_sub_f32_e32 v61, v64, v61
	v_add_f32_e32 v57, v57, v61
	v_sub_f32_e32 v60, v68, v60
	v_cvt_f32_i32_e32 v56, v56
	v_add_f32_e32 v57, v60, v57
	v_add_f32_e32 v60, v62, v65
	v_add_f32_e32 v57, v69, v57
	v_sub_f32_e32 v61, v60, v62
	v_mul_f32_e32 v57, v66, v57
	v_sub_f32_e32 v61, v65, v61
	v_add_f32_e32 v57, v61, v57
	v_mul_f32_e32 v65, 0x3f317218, v56
	v_add_f32_e32 v61, v60, v57
	v_fma_f32 v66, v56, s5, -v65
	v_mul_f32_e32 v62, v61, v61
	v_fmac_f32_e32 v66, 0xb102e308, v56
	v_sub_f32_e32 v56, v61, v60
	v_fmamk_f32 v64, v62, 0x3e9b6dac, v202
	v_sub_f32_e32 v56, v57, v56
	v_add_f32_e32 v57, v65, v66
	v_fmaak_f32 v64, v62, v64, 0x3f2aaada
	v_sub_f32_e32 v60, v57, v65
	v_ldexp_f32 v65, v61, 1
	v_mul_f32_e32 v61, v61, v62
	v_mul_f32_e32 v61, v61, v64
	v_add_f32_e32 v62, v65, v61
	v_sub_f32_e32 v64, v62, v65
	v_ldexp_f32 v56, v56, 1
	v_sub_f32_e32 v61, v61, v64
	v_add_f32_e32 v56, v56, v61
	v_add_f32_e32 v61, v62, v56
	v_sub_f32_e32 v62, v61, v62
	v_sub_f32_e32 v56, v56, v62
	v_add_f32_e32 v62, v57, v61
	v_sub_f32_e32 v64, v62, v57
	v_add_f32_e32 v32, v32, v33
	v_pk_mul_f32 v[24:25], v[24:25], v[114:115]
	v_sub_f32_e32 v65, v62, v64
	v_add_f32_e32 v24, v32, v24
	v_mov_b32_e32 v98, v111
	v_sub_f32_e32 v60, v66, v60
	v_sub_f32_e32 v57, v57, v65
	v_sub_f32_e32 v61, v61, v64
	v_add_f32_e32 v32, v24, v25
	v_pk_mul_f32 v[24:25], v[26:27], v[98:99]
	v_add_f32_e32 v57, v61, v57
	v_add_f32_e32 v61, v60, v56
	v_add_f32_e32 v24, v32, v24
	v_sub_f32_e32 v64, v61, v60
	v_add_f32_e32 v24, v24, v25
	v_sub_f32_e32 v65, v61, v64
	v_mul_f32_e64 v25, |v24|, s2
	v_sub_f32_e32 v60, v60, v65
	v_sub_f32_e32 v56, v56, v64
	v_add_f32_e32 v57, v61, v57
	v_exp_f32_e32 v26, v25
	v_add_f32_e32 v56, v56, v60
	v_add_f32_e32 v60, v62, v57
	v_sub_f32_e32 v61, v60, v62
	v_sub_f32_e32 v57, v57, v61
	v_add_f32_e32 v56, v56, v57
	v_add_f32_e32 v33, 1.0, v26
	v_add_f32_e32 v56, v60, v56
	v_cmp_neq_f32_e32 vcc, s30, v54
	v_min_f32_e32 v32, 0, v24
	v_add_f32_e32 v24, -1.0, v33
	v_cndmask_b32_e32 v56, v204, v56, vcc
	v_cmp_ngt_f32_e32 vcc, -1.0, v54
	v_sub_f32_e32 v25, v24, v33
	v_add_f32_e32 v25, 1.0, v25
	v_cndmask_b32_e32 v56, v205, v56, vcc
	v_cmp_neq_f32_e32 vcc, -1.0, v54
	v_sub_f32_e32 v24, v26, v24
	v_add_f32_e32 v34, v24, v25
	v_cndmask_b32_e32 v56, v206, v56, vcc
	v_cmp_lt_f32_e64 vcc, |v54|, s31
	v_frexp_mant_f32_e32 v35, v33
	v_cvt_f64_f32_e32 v[24:25], v33
	v_cndmask_b32_e32 v54, v56, v54, vcc
	v_frexp_exp_i32_f64_e32 v24, v[24:25]
	v_cmp_gt_f32_e32 vcc, s4, v35
	v_and_b32_e32 v27, 0xffff0000, v47
	v_mul_f32_e32 v55, 0x3e000000, v27
	v_subbrev_co_u32_e32 v24, vcc, 0, v24, vcc
	v_sub_u32_e32 v25, 0, v24
	v_ldexp_f32 v33, v33, v25
	v_ldexp_f32 v25, v34, v25
	v_add_f32_e32 v34, -1.0, v33
	v_add_f32_e32 v37, 1.0, v33
	v_add_f32_e32 v35, 1.0, v34
	v_add_f32_e32 v38, -1.0, v37
	v_sub_f32_e32 v35, v33, v35
	v_sub_f32_e32 v33, v33, v38
	v_add_f32_e32 v35, v25, v35
	v_add_f32_e32 v25, v25, v33
	v_add_f32_e32 v33, v37, v25
	v_rcp_f32_e32 v38, v33
	v_add_f32_e32 v36, v34, v35
	v_sub_f32_e32 v34, v36, v34
	v_sub_f32_e32 v34, v35, v34
	v_sub_f32_e32 v35, v33, v37
	v_sub_f32_e32 v25, v25, v35
	v_mul_f32_e32 v35, v36, v38
	v_mul_f32_e32 v37, v33, v35
	v_fma_f32 v39, v35, v33, -v37
	v_fmac_f32_e32 v39, v35, v25
	v_add_f32_e32 v40, v37, v39
	v_sub_f32_e32 v41, v36, v40
	v_sub_f32_e32 v36, v36, v41
	v_sub_f32_e32 v37, v40, v37
	v_sub_f32_e32 v36, v36, v40
	v_add_f32_e32 v34, v34, v36
	v_sub_f32_e32 v36, v37, v39
	v_add_f32_e32 v34, v36, v34
	v_add_f32_e32 v36, v41, v34
	v_mul_f32_e32 v37, v38, v36
	v_mul_f32_e32 v39, v33, v37
	v_fma_f32 v33, v37, v33, -v39
	v_fmac_f32_e32 v33, v37, v25
	v_sub_f32_e32 v25, v41, v36
	v_add_f32_e32 v25, v34, v25
	v_add_f32_e32 v34, v39, v33
	v_sub_f32_e32 v40, v36, v34
	v_sub_f32_e32 v36, v36, v40
	v_sub_f32_e32 v39, v34, v39
	v_sub_f32_e32 v34, v36, v34
	v_add_f32_e32 v25, v25, v34
	v_sub_f32_e32 v33, v39, v33
	v_cvt_f32_i32_e32 v24, v24
	v_add_f32_e32 v25, v33, v25
	v_add_f32_e32 v33, v35, v37
	v_add_f32_e32 v25, v40, v25
	v_sub_f32_e32 v34, v33, v35
	v_mul_f32_e32 v25, v38, v25
	v_sub_f32_e32 v34, v37, v34
	v_add_f32_e32 v25, v34, v25
	v_mul_f32_e32 v37, 0x3f317218, v24
	v_add_f32_e32 v34, v33, v25
	v_fma_f32 v38, v24, s5, -v37
	v_mul_f32_e32 v35, v34, v34
	v_fmac_f32_e32 v38, 0xb102e308, v24
	v_sub_f32_e32 v24, v34, v33
	v_fmamk_f32 v36, v35, 0x3e9b6dac, v202
	v_sub_f32_e32 v24, v25, v24
	v_add_f32_e32 v25, v37, v38
	v_fmaak_f32 v36, v35, v36, 0x3f2aaada
	v_sub_f32_e32 v33, v25, v37
	v_ldexp_f32 v37, v34, 1
	v_mul_f32_e32 v34, v34, v35
	v_mul_f32_e32 v34, v34, v36
	v_add_f32_e32 v35, v37, v34
	v_sub_f32_e32 v36, v35, v37
	v_ldexp_f32 v24, v24, 1
	v_sub_f32_e32 v34, v34, v36
	v_add_f32_e32 v24, v24, v34
	v_add_f32_e32 v34, v35, v24
	v_sub_f32_e32 v35, v34, v35
	v_sub_f32_e32 v24, v24, v35
	v_add_f32_e32 v35, v25, v34
	v_sub_f32_e32 v36, v35, v25
	v_sub_f32_e32 v37, v35, v36
	v_sub_f32_e32 v33, v38, v33
	v_sub_f32_e32 v25, v25, v37
	v_sub_f32_e32 v34, v34, v36
	v_add_f32_e32 v25, v34, v25
	v_add_f32_e32 v34, v33, v24
	v_sub_f32_e32 v36, v34, v33
	v_sub_f32_e32 v37, v34, v36
	v_sub_f32_e32 v33, v33, v37
	v_sub_f32_e32 v24, v24, v36
	v_add_f32_e32 v25, v34, v25
	v_add_f32_e32 v24, v24, v33
	v_add_f32_e32 v33, v35, v25
	v_sub_f32_e32 v34, v33, v35
	v_sub_f32_e32 v25, v25, v34
	v_add_f32_e32 v24, v24, v25
	v_add_f32_e32 v24, v33, v24
	v_cmp_neq_f32_e32 vcc, s30, v26
	v_min_f32_e32 v50, 0, v50
	v_sub_f32_e32 v50, v50, v54
	v_cndmask_b32_e32 v24, v204, v24, vcc
	v_cmp_ngt_f32_e32 vcc, -1.0, v26
	v_mul_f32_e32 v54, 0x3d800000, v50
	v_mul_f32_e32 v56, 0x3e000000, v58
	v_cndmask_b32_e32 v24, v205, v24, vcc
	v_cmp_neq_f32_e32 vcc, -1.0, v26
	v_mov_b32_dpp v54, v54 row_shr:1 row_mask:0xf bank_mask:0xf bound_ctrl:1
	v_fmac_f32_e32 v54, 0x3d800000, v50
	v_cndmask_b32_e32 v24, v206, v24, vcc
	v_cmp_lt_f32_e64 vcc, |v26|, s31
	v_add_f32_dpp v50, v54, v54 row_shr:2 row_mask:0xf bank_mask:0xf bound_ctrl:1
	v_mov_b32_e32 v54, 0
	v_cndmask_b32_e32 v24, v24, v26, vcc
	v_subrev_f32_e32 v26, s26, v117
	v_sub_f32_e32 v24, v32, v24
	v_cndmask_b32_e64 v26, v26, v117, s[24:25]
	v_mul_f32_e32 v25, 0x3d800000, v24
	v_max_f32_e32 v26, 0xc2a00000, v26
	v_mul_f32_e32 v26, 0x3fb8aa3b, v26
	v_mov_b32_dpp v25, v25 row_shr:1 row_mask:0xf bank_mask:0xf bound_ctrl:1
	v_fmac_f32_e32 v25, 0x3d800000, v24
	v_exp_f32_e32 v32, v26
	v_sub_f32_e32 v26, s26, v117
	v_add_f32_dpp v24, v25, v25 row_shr:2 row_mask:0xf bank_mask:0xf bound_ctrl:1
	v_min_f32_e32 v26, 0x42a00000, v26
	v_mul_f32_e32 v26, 0x3fb8aa3b, v26
	v_add_f32_dpp v24, v24, v24 row_shr:4 row_mask:0xf bank_mask:0xf bound_ctrl:1
	v_mov_b32_e32 v25, 0
	v_exp_f32_e32 v26, v26
	v_add_f32_dpp v24, v24, v24 row_shr:8 row_mask:0xf bank_mask:0xf bound_ctrl:1
	v_readlane_b32 s36, v32, 31
	v_rcp_f32_e32 v35, v32
	v_mov_b32_dpp v25, v24 row_bcast:15 row_mask:0xa bank_mask:0xf
	v_add_f32_e32 v24, v24, v25
	v_mov_b32_e32 v25, 0
	v_readlane_b32 s26, v26, 63
	v_mul_f32_e32 v36, v116, v32
	v_mov_b32_dpp v25, v24 row_bcast:31 row_mask:0xc bank_mask:0xf
	v_add_f32_e32 v57, v24, v25
	v_mul_f32_e32 v25, s36, v32
	v_rcp_f32_e32 v24, s26
	v_cndmask_b32_e64 v25, v25, v32, s[24:25]
	v_readlane_b32 s26, v118, 31
	v_mul_f32_e32 v34, v116, v25
	v_add_f32_dpp v50, v50, v50 row_shr:4 row_mask:0xf bank_mask:0xf bound_ctrl:1
	v_subrev_f32_e32 v25, s26, v118
	v_cndmask_b32_e64 v25, v25, v118, s[24:25]
	v_max_f32_e32 v25, 0xc2a00000, v25
	v_mul_f32_e32 v25, 0x3fb8aa3b, v25
	v_exp_f32_e32 v33, v25
	v_sub_f32_e32 v25, s26, v118
	v_min_f32_e32 v25, 0x42a00000, v25
	v_mul_f32_e32 v25, 0x3fb8aa3b, v25
	v_exp_f32_e32 v27, v25
	v_readlane_b32 s37, v33, 31
	v_rcp_f32_e32 v39, v33
	v_mul_f32_e32 v40, v44, v33
	v_mul_f32_e32 v32, s37, v33
	v_cndmask_b32_e64 v32, v32, v33, s[24:25]
	v_mul_f32_e32 v38, v44, v32
	s_waitcnt lgkmcnt(0)
	v_lshlrev_b32_e32 v32, 16, v28
	v_and_b32_e32 v33, 0xffff0000, v28
	v_readlane_b32 s26, v27, 63
	v_mul_f32_e32 v28, v35, v32
	v_pk_mul_f32 v[26:27], v[26:27], v[32:33]
	v_mul_f32_e32 v32, v39, v33
	v_rcp_f32_e32 v25, s26
	v_cndmask_b32_e64 v28, v36, v28, s[24:25]
	v_cndmask_b32_e64 v32, v40, v32, s[24:25]
	v_readlane_b32 s26, v119, 31
	v_cvt_pk_bf16_f32 v34, v34, v38
	v_cvt_pk_bf16_f32 v38, v28, v32
	v_subrev_f32_e32 v28, s26, v119
	v_cndmask_b32_e64 v28, v28, v119, s[24:25]
	v_max_f32_e32 v28, 0xc2a00000, v28
	v_sub_f32_e32 v32, s26, v119
	v_mul_f32_e32 v28, 0x3fb8aa3b, v28
	v_min_f32_e32 v32, 0x42a00000, v32
	v_exp_f32_e32 v28, v28
	v_mul_f32_e32 v32, 0x3fb8aa3b, v32
	v_exp_f32_e32 v32, v32
	v_pk_mul_f32 v[36:37], v[24:25], v[26:27]
	v_readlane_b32 s38, v28, 31
	v_cvt_pk_bf16_f32 v42, v26, v27
	v_readlane_b32 s26, v32, 63
	v_mul_f32_e32 v27, s38, v28
	v_cndmask_b32_e64 v27, v27, v28, s[24:25]
	v_rcp_f32_e32 v26, s26
	v_readlane_b32 s26, v48, 31
	v_add_f32_dpp v50, v50, v50 row_shr:8 row_mask:0xf bank_mask:0xf bound_ctrl:1
	v_mul_f32_e32 v35, v120, v27
	v_subrev_f32_e32 v27, s26, v48
	v_mov_b32_dpp v54, v50 row_bcast:15 row_mask:0xa bank_mask:0xf
	v_cndmask_b32_e64 v27, v27, v48, s[24:25]
	v_add_f32_e32 v50, v50, v54
	v_mov_b32_e32 v54, 0
	v_max_f32_e32 v27, 0xc2a00000, v27
	v_mul_f32_e32 v27, 0x3fb8aa3b, v27
	v_mov_b32_dpp v54, v50 row_bcast:31 row_mask:0xc bank_mask:0xf
	v_add_f32_e32 v54, v50, v54
	v_cvt_pk_bf16_f32 v50, v36, v37
	v_exp_f32_e32 v36, v27
	v_sub_f32_e32 v27, s26, v48
	v_min_f32_e32 v27, 0x42a00000, v27
	v_mul_f32_e32 v27, 0x3fb8aa3b, v27
	v_exp_f32_e32 v33, v27
	v_rcp_f32_e32 v37, v28
	v_readlane_b32 s39, v36, 31
	v_rcp_f32_e32 v41, v36
	v_mul_f32_e32 v39, v120, v28
	v_mul_f32_e32 v28, s39, v36
	v_cndmask_b32_e64 v28, v28, v36, s[24:25]
	v_mul_f32_e32 v40, v45, v28
	v_lshlrev_b32_e32 v28, 16, v29
	v_and_b32_e32 v29, 0xffff0000, v29
	v_readlane_b32 s26, v33, 63
	v_mul_f32_e32 v43, v45, v36
	v_mul_f32_e32 v36, v37, v28
	v_pk_mul_f32 v[32:33], v[32:33], v[28:29]
	v_mul_f32_e32 v28, v41, v29
	v_rcp_f32_e32 v27, s26
	v_cndmask_b32_e64 v39, v39, v36, s[24:25]
	v_cndmask_b32_e64 v28, v43, v28, s[24:25]
	v_readlane_b32 s26, v49, 31
	v_cvt_pk_bf16_f32 v39, v39, v28
	v_cvt_pk_bf16_f32 v35, v35, v40
	v_subrev_f32_e32 v28, s26, v49
	v_cndmask_b32_e64 v28, v28, v49, s[24:25]
	v_max_f32_e32 v28, 0xc2a00000, v28
	v_mul_f32_e32 v28, 0x3fb8aa3b, v28
	v_exp_f32_e32 v29, v28
	v_sub_f32_e32 v28, s26, v49
	v_min_f32_e32 v28, 0x42a00000, v28
	v_mul_f32_e32 v28, 0x3fb8aa3b, v28
	v_exp_f32_e32 v40, v28
	v_readlane_b32 s40, v29, 31
	v_pk_mul_f32 v[36:37], v[26:27], v[32:33]
	v_cvt_pk_bf16_f32 v43, v32, v33
	v_readlane_b32 s26, v40, 63
	v_mul_f32_e32 v32, s40, v29
	v_cndmask_b32_e64 v32, v32, v29, s[24:25]
	v_rcp_f32_e32 v28, s26
	v_readlane_b32 s26, v53, 31
	v_cvt_pk_bf16_f32 v51, v36, v37
	v_mul_f32_e32 v36, v52, v32
	v_subrev_f32_e32 v32, s26, v53
	v_cndmask_b32_e64 v32, v32, v53, s[24:25]
	v_max_f32_e32 v32, 0xc2a00000, v32
	v_mul_f32_e32 v32, 0x3fb8aa3b, v32
	v_exp_f32_e32 v32, v32
	v_sub_f32_e32 v33, s26, v53
	v_min_f32_e32 v33, 0x42a00000, v33
	v_mul_f32_e32 v33, 0x3fb8aa3b, v33
	v_rcp_f32_e32 v37, v29
	v_exp_f32_e32 v41, v33
	v_readlane_b32 s41, v32, 31
	v_rcp_f32_e32 v49, v32
	v_mul_f32_e32 v44, v52, v29
	v_mul_f32_e32 v33, s41, v32
	v_cndmask_b32_e64 v33, v33, v32, s[24:25]
	v_mul_f32_e32 v52, v46, v32
	v_lshlrev_b32_e32 v32, 16, v30
	v_mul_f32_e32 v48, v46, v33
	v_and_b32_e32 v33, 0xffff0000, v30
	v_mul_f32_e32 v30, v37, v32
	v_readlane_b32 s26, v41, 63
	v_cndmask_b32_e64 v30, v44, v30, s[24:25]
	v_pk_mul_f32 v[44:45], v[40:41], v[32:33]
	v_mul_f32_e32 v32, v49, v33
	v_rcp_f32_e32 v29, s26
	v_cndmask_b32_e64 v32, v52, v32, s[24:25]
	v_readlane_b32 s26, v54, 31
	v_cvt_pk_bf16_f32 v40, v30, v32
	v_cvt_pk_bf16_f32 v36, v36, v48
	v_subrev_f32_e32 v30, s26, v54
	v_cndmask_b32_e64 v30, v30, v54, s[24:25]
	v_max_f32_e32 v30, 0xc2a00000, v30
	v_sub_f32_e32 v32, s26, v54
	v_mul_f32_e32 v30, 0x3fb8aa3b, v30
	v_min_f32_e32 v32, 0x42a00000, v32
	v_exp_f32_e32 v30, v30
	v_mul_f32_e32 v32, 0x3fb8aa3b, v32
	v_exp_f32_e32 v48, v32
	v_pk_mul_f32 v[46:47], v[28:29], v[44:45]
	v_readlane_b32 s42, v30, 31
	v_cvt_pk_bf16_f32 v44, v44, v45
	v_readlane_b32 s26, v48, 63
	v_mul_f32_e32 v33, s42, v30
	v_cndmask_b32_e64 v33, v33, v30, s[24:25]
	v_rcp_f32_e32 v32, s26
	v_readlane_b32 s26, v57, 31
	v_mul_f32_e32 v37, v56, v33
	v_rcp_f32_e32 v45, v30
	v_subrev_f32_e32 v33, s26, v57
	v_cndmask_b32_e64 v33, v33, v57, s[24:25]
	v_max_f32_e32 v33, 0xc2a00000, v33
	v_mul_f32_e32 v33, 0x3fb8aa3b, v33
	v_exp_f32_e32 v41, v33
	v_sub_f32_e32 v33, s26, v57
	v_min_f32_e32 v33, 0x42a00000, v33
	v_mul_f32_e32 v33, 0x3fb8aa3b, v33
	v_exp_f32_e32 v49, v33
	v_readlane_b32 s43, v41, 31
	v_cvt_pk_bf16_f32 v52, v46, v47
	v_mul_f32_e32 v46, v56, v30
	v_readlane_b32 s26, v49, 63
	v_mul_f32_e32 v30, s43, v41
	v_rcp_f32_e32 v54, v41
	v_rcp_f32_e32 v33, s26
	s_and_b32 s26, s34, 0xfffffe00
	v_cndmask_b32_e64 v30, v30, v41, s[24:25]
	s_or_b32 s26, s27, s26
	v_mul_f32_e32 v53, v55, v30
	v_lshlrev_b32_e32 v30, 16, v31
	s_or_b32 s26, s26, s97
	v_and_b32_e32 v31, 0xffff0000, v31
	v_mul_f32_e32 v45, v45, v30
	s_mul_hi_i32 s27, s26, 0x8100
	s_mul_i32 s26, s26, 0x8100
	v_mul_f32_e32 v41, v55, v41
	v_cndmask_b32_e64 v45, v46, v45, s[24:25]
	v_pk_mul_f32 v[46:47], v[48:49], v[30:31]
	v_mul_f32_e32 v30, v54, v31
	s_add_u32 s26, s52, s26
	v_pk_mul_f32 v[48:49], v[32:33], v[46:47]
	v_cndmask_b32_e64 v30, v41, v30, s[24:25]
	v_cvt_pk_bf16_f32 v37, v37, v53
	s_addc_u32 s27, s53, s27
	v_cvt_pk_bf16_f32 v41, v45, v30
	v_cvt_pk_bf16_f32 v45, v46, v47
	v_cvt_pk_bf16_f32 v53, v48, v49
	ds_write_b128 v194, v[34:37]
	ds_write_b128 v194, v[38:41] offset:9216
	ds_write_b128 v194, v[42:45] offset:18432
	ds_write_b128 v194, v[50:53] offset:27648
	s_and_saveexec_b64 s[28:29], s[22:23]
	s_cbranch_execz .LBB0_2118
	v_mul_f32_e32 v24, s36, v24
	v_mul_f32_e32 v25, s37, v25
	v_cndmask_b32_e64 v24, 0, v24, s[6:7]
	v_mul_f32_e32 v26, s38, v26
	v_cndmask_b32_e64 v24, v24, v25, s[8:9]
	v_mul_f32_e32 v27, s39, v27
	v_cndmask_b32_e64 v24, v24, v26, s[10:11]
	v_mul_f32_e32 v28, s40, v28
	v_cndmask_b32_e64 v24, v24, v27, s[12:13]
	v_mul_f32_e32 v29, s41, v29
	v_cndmask_b32_e64 v24, v24, v28, s[14:15]
	v_mul_f32_e32 v30, s42, v32
	v_cndmask_b32_e64 v24, v24, v29, s[16:17]
	v_cndmask_b32_e64 v24, v24, v30, s[18:19]
	v_mul_f32_e32 v25, s43, v33
	v_cndmask_b32_e64 v26, v24, v25, s[20:21]
	v_lshl_add_u64 v[24:25], v[188:189], 2, s[26:27]
	v_add_co_u32_e32 v24, vcc, 0x8000, v24
	s_nop 1
	v_addc_co_u32_e32 v25, vcc, 0, v25, vcc
	global_store_dword v[24:25], v26, off nt
	s_branch .LBB0_2118
